# v10: v9 + value-row loads of sample attention issued inside the score section (V prefetch), softmax temps renamed
# baseline (speedup 1.0000x reference)
; #define LAS __attribute__((address_space(3)))
; DI void lbar() { asm volatile("s_waitcnt lgkmcnt(0)" ::: "memory"); __builtin_amdgcn_s_barrier(); asm volatile("" ::: "memory"); }
; DI void attn_sample_item(const Params& p, int item, ldsp lds, int tid_) {
;     ...
;   for (int j = 0; j < 16; ++j) vvB[j] = __builtin_nontemporal_load((const f32x4*)(cv + (size_t)(wid * 32 + 16 + j) * 1024 + lane * 4));
;   lbar();
;   {
;     f32x4 acc[4];
; #pragma unroll
;     for (int t = 0; t < 4; ++t) acc[t] = (f32x4){0.f, 0.f, 0.f, 0.f};
; #pragma unroll
;     for (int t = 0; t < 4; ++t)
; #pragma unroll
;       for (int j4 = 0; j4 < 4; ++j4) { const f32x4 pp = *(const LAS f32x4*)(SC + t * 256 + wid * 32 + j4 * 4);
; #pragma unroll
;         for (int e = 0; e < 4; ++e) acc[t] += pp[e] * vvA[j4 * 4 + e]; }
.LBB0_1603:
	s_or_b64 exec, exec, s[4:5]
	s_waitcnt lgkmcnt(0)
	s_barrier
	ds_read_b128 v[128:131], v136
	ds_read_b128 v[132:135], v136 offset:16
	ds_read_b128 v[138:141], v136 offset:32
	ds_read_b128 v[146:149], v136 offset:48
	s_add_i32 s4, s28, 0x4000
	s_waitcnt vmcnt(31) lgkmcnt(3)
	v_pk_fma_f32 v[142:143], v[100:101], v[128:129], 0 op_sel_hi:[1,0,0]
	v_pk_fma_f32 v[150:151], v[102:103], v[128:129], 0 op_sel_hi:[1,0,0]
	s_lshl_b32 s26, s26, 1
	s_waitcnt vmcnt(30)
	v_pk_fma_f32 v[150:151], v[94:95], v[128:129], v[150:151] op_sel:[0,1,0]
	v_pk_fma_f32 v[128:129], v[92:93], v[128:129], v[142:143] op_sel:[0,1,0]
	s_waitcnt vmcnt(29)
	v_pk_fma_f32 v[142:143], v[114:115], v[130:131], v[150:151] op_sel_hi:[1,0,1]
	v_pk_fma_f32 v[128:129], v[112:113], v[130:131], v[128:129] op_sel_hi:[1,0,1]
	v_mov_b32_e32 v130, v131
	s_waitcnt vmcnt(28)
	v_pk_fma_f32 v[128:129], v[108:109], v[130:131], v[128:129] op_sel_hi:[1,0,1]
	v_pk_fma_f32 v[130:131], v[110:111], v[130:131], v[142:143] op_sel_hi:[1,0,1]
	s_waitcnt vmcnt(27) lgkmcnt(2)
	v_pk_fma_f32 v[128:129], v[120:121], v[132:133], v[128:129] op_sel_hi:[1,0,1]
	v_pk_fma_f32 v[130:131], v[122:123], v[132:133], v[130:131] op_sel_hi:[1,0,1]
	s_waitcnt vmcnt(26)
	v_pk_fma_f32 v[128:129], v[116:117], v[132:133], v[128:129] op_sel:[0,1,0]
	v_pk_fma_f32 v[130:131], v[118:119], v[132:133], v[130:131] op_sel:[0,1,0]
	s_waitcnt vmcnt(25)
	v_pk_fma_f32 v[128:129], v[124:125], v[134:135], v[128:129] op_sel_hi:[1,0,1]
	v_pk_fma_f32 v[130:131], v[126:127], v[134:135], v[130:131] op_sel_hi:[1,0,1]
	v_mov_b32_e32 v132, v135
	s_waitcnt vmcnt(24)
	v_pk_fma_f32 v[128:129], v[104:105], v[132:133], v[128:129] op_sel_hi:[1,0,1]
	v_pk_fma_f32 v[130:131], v[106:107], v[132:133], v[130:131] op_sel_hi:[1,0,1]
	s_waitcnt vmcnt(23) lgkmcnt(1)
	v_pk_fma_f32 v[128:129], v[68:69], v[138:139], v[128:129] op_sel_hi:[1,0,1]
	v_pk_fma_f32 v[130:131], v[70:71], v[138:139], v[130:131] op_sel_hi:[1,0,1]
	s_waitcnt vmcnt(22)
	v_pk_fma_f32 v[128:129], v[64:65], v[138:139], v[128:129] op_sel:[0,1,0]
	v_pk_fma_f32 v[130:131], v[66:67], v[138:139], v[130:131] op_sel:[0,1,0]
	s_waitcnt vmcnt(21)
	v_pk_fma_f32 v[128:129], v[80:81], v[140:141], v[128:129] op_sel_hi:[1,0,1]
	v_pk_fma_f32 v[130:131], v[82:83], v[140:141], v[130:131] op_sel_hi:[1,0,1]
	v_mov_b32_e32 v132, v141
	s_waitcnt vmcnt(20)
	v_pk_fma_f32 v[128:129], v[76:77], v[132:133], v[128:129] op_sel_hi:[1,0,1]
	v_pk_fma_f32 v[130:131], v[78:79], v[132:133], v[130:131] op_sel_hi:[1,0,1]
	s_waitcnt vmcnt(19) lgkmcnt(0)
	v_pk_fma_f32 v[128:129], v[88:89], v[146:147], v[128:129] op_sel_hi:[1,0,1]
	v_pk_fma_f32 v[130:131], v[90:91], v[146:147], v[130:131] op_sel_hi:[1,0,1]
	s_waitcnt vmcnt(18)
	v_pk_fma_f32 v[128:129], v[84:85], v[146:147], v[128:129] op_sel:[0,1,0]
	v_pk_fma_f32 v[130:131], v[86:87], v[146:147], v[130:131] op_sel:[0,1,0]
	s_waitcnt vmcnt(17)
	v_pk_fma_f32 v[134:135], v[96:97], v[148:149], v[128:129] op_sel_hi:[1,0,1]
	v_pk_fma_f32 v[132:133], v[98:99], v[148:149], v[130:131] op_sel_hi:[1,0,1]
	ds_read_b128 v[128:131], v136 offset:1024
	v_mov_b32_e32 v138, v149
	s_waitcnt vmcnt(16)
	v_pk_fma_f32 v[142:143], v[72:73], v[138:139], v[134:135] op_sel_hi:[1,0,1]
	v_pk_fma_f32 v[150:151], v[74:75], v[138:139], v[132:133] op_sel_hi:[1,0,1]
	ds_read_b128 v[132:135], v136 offset:1040
	s_waitcnt lgkmcnt(1)
	v_pk_fma_f32 v[138:139], v[100:101], v[128:129], 0 op_sel_hi:[1,0,0]
	v_pk_fma_f32 v[140:141], v[102:103], v[128:129], 0 op_sel_hi:[1,0,0]
	ds_read_b128 v[146:149], v136 offset:2064
	v_pk_fma_f32 v[140:141], v[94:95], v[128:129], v[140:141] op_sel:[0,1,0]
	v_pk_fma_f32 v[128:129], v[92:93], v[128:129], v[138:139] op_sel:[0,1,0]
	v_pk_fma_f32 v[138:139], v[114:115], v[130:131], v[140:141] op_sel_hi:[1,0,1]
	v_pk_fma_f32 v[128:129], v[112:113], v[130:131], v[128:129] op_sel_hi:[1,0,1]
	v_mov_b32_e32 v130, v131
	v_pk_fma_f32 v[128:129], v[108:109], v[130:131], v[128:129] op_sel_hi:[1,0,1]
	v_pk_fma_f32 v[130:131], v[110:111], v[130:131], v[138:139] op_sel_hi:[1,0,1]
	s_waitcnt lgkmcnt(1)
	v_pk_fma_f32 v[128:129], v[120:121], v[132:133], v[128:129] op_sel_hi:[1,0,1]
	v_pk_fma_f32 v[130:131], v[122:123], v[132:133], v[130:131] op_sel_hi:[1,0,1]
	v_pk_fma_f32 v[128:129], v[116:117], v[132:133], v[128:129] op_sel:[0,1,0]
	v_pk_fma_f32 v[130:131], v[118:119], v[132:133], v[130:131] op_sel:[0,1,0]
	v_pk_fma_f32 v[138:139], v[124:125], v[134:135], v[128:129] op_sel_hi:[1,0,1]
	v_pk_fma_f32 v[132:133], v[126:127], v[134:135], v[130:131] op_sel_hi:[1,0,1]
	ds_read_b128 v[128:131], v136 offset:1056
	v_mov_b32_e32 v134, v135
	v_pk_fma_f32 v[138:139], v[104:105], v[134:135], v[138:139] op_sel_hi:[1,0,1]
	v_pk_fma_f32 v[140:141], v[106:107], v[134:135], v[132:133] op_sel_hi:[1,0,1]
	ds_read_b128 v[132:135], v136 offset:1072
	s_waitcnt lgkmcnt(1)
	v_pk_fma_f32 v[140:141], v[70:71], v[128:129], v[140:141] op_sel_hi:[1,0,1]
	v_pk_fma_f32 v[138:139], v[68:69], v[128:129], v[138:139] op_sel_hi:[1,0,1]
	s_add_i32 s40, s40, s94
	v_pk_fma_f32 v[138:139], v[64:65], v[128:129], v[138:139] op_sel:[0,1,0]
	v_pk_fma_f32 v[128:129], v[66:67], v[128:129], v[140:141] op_sel:[0,1,0]
	v_pk_fma_f32 v[138:139], v[80:81], v[130:131], v[138:139] op_sel_hi:[1,0,1]
	v_pk_fma_f32 v[128:129], v[82:83], v[130:131], v[128:129] op_sel_hi:[1,0,1]
	v_mov_b32_e32 v130, v131
	v_pk_fma_f32 v[138:139], v[76:77], v[130:131], v[138:139] op_sel_hi:[1,0,1]
	v_pk_fma_f32 v[128:129], v[78:79], v[130:131], v[128:129] op_sel_hi:[1,0,1]
	s_waitcnt lgkmcnt(0)
; #define LAS __attribute__((address_space(3)))
; DI void attn_sample_item(const Params& p, int item, ldsp lds, int tid_) {
;     ...
;     for (int t = 0; t < 4; ++t)
; #pragma unroll
;       for (int j4 = 0; j4 < 4; ++j4) { const f32x4 pp = *(const LAS f32x4*)(SC + t * 256 + wid * 32 + j4 * 4);
; #pragma unroll
;         for (int e = 0; e < 4; ++e) acc[t] += pp[e] * vvA[j4 * 4 + e]; }
	v_pk_fma_f32 v[130:131], v[88:89], v[132:133], v[138:139] op_sel_hi:[1,0,1]
	ds_read_b128 v[138:141], v136 offset:2048
	v_pk_fma_f32 v[128:129], v[90:91], v[132:133], v[128:129] op_sel_hi:[1,0,1]
	v_pk_fma_f32 v[130:131], v[84:85], v[132:133], v[130:131] op_sel:[0,1,0]
	v_pk_fma_f32 v[128:129], v[86:87], v[132:133], v[128:129] op_sel:[0,1,0]
	s_add_i32 s0, s0, s1
	v_pk_fma_f32 v[132:133], v[98:99], v[134:135], v[128:129] op_sel_hi:[1,0,1]
	v_pk_fma_f32 v[128:129], v[96:97], v[134:135], v[130:131] op_sel_hi:[1,0,1]
	v_mov_b32_e32 v130, v135
	v_pk_fma_f32 v[128:129], v[72:73], v[130:131], v[128:129] op_sel_hi:[1,0,1]
	v_pk_fma_f32 v[132:133], v[74:75], v[130:131], v[132:133] op_sel_hi:[1,0,1]
	s_waitcnt lgkmcnt(0)
	v_pk_fma_f32 v[130:131], v[100:101], v[138:139], 0 op_sel_hi:[1,0,0]
	v_pk_fma_f32 v[134:135], v[102:103], v[138:139], 0 op_sel_hi:[1,0,0]
	v_pk_fma_f32 v[130:131], v[92:93], v[138:139], v[130:131] op_sel:[0,1,0]
	v_pk_fma_f32 v[134:135], v[94:95], v[138:139], v[134:135] op_sel:[0,1,0]
	v_pk_fma_f32 v[130:131], v[112:113], v[140:141], v[130:131] op_sel_hi:[1,0,1]
	v_pk_fma_f32 v[134:135], v[114:115], v[140:141], v[134:135] op_sel_hi:[1,0,1]
	v_mov_b32_e32 v138, v141
	v_pk_fma_f32 v[130:131], v[108:109], v[138:139], v[130:131] op_sel_hi:[1,0,1]
	v_pk_fma_f32 v[134:135], v[110:111], v[138:139], v[134:135] op_sel_hi:[1,0,1]
	ds_read_b128 v[138:141], v136 offset:2080
	v_pk_fma_f32 v[134:135], v[122:123], v[146:147], v[134:135] op_sel_hi:[1,0,1]
	v_pk_fma_f32 v[130:131], v[120:121], v[146:147], v[130:131] op_sel_hi:[1,0,1]
	v_pk_fma_f32 v[134:135], v[118:119], v[146:147], v[134:135] op_sel:[0,1,0]
	v_pk_fma_f32 v[130:131], v[116:117], v[146:147], v[130:131] op_sel:[0,1,0]
	v_pk_fma_f32 v[134:135], v[126:127], v[148:149], v[134:135] op_sel_hi:[1,0,1]
	v_pk_fma_f32 v[130:131], v[124:125], v[148:149], v[130:131] op_sel_hi:[1,0,1]
	v_mov_b32_e32 v146, v149
	v_pk_fma_f32 v[130:131], v[104:105], v[146:147], v[130:131] op_sel_hi:[1,0,1]
	v_pk_fma_f32 v[134:135], v[106:107], v[146:147], v[134:135] op_sel_hi:[1,0,1]
	ds_read_b128 v[146:149], v136 offset:2096
	s_waitcnt lgkmcnt(1)
	v_pk_fma_f32 v[134:135], v[70:71], v[138:139], v[134:135] op_sel_hi:[1,0,1]
	v_pk_fma_f32 v[130:131], v[68:69], v[138:139], v[130:131] op_sel_hi:[1,0,1]
	v_pk_fma_f32 v[134:135], v[66:67], v[138:139], v[134:135] op_sel:[0,1,0]
	v_pk_fma_f32 v[130:131], v[64:65], v[138:139], v[130:131] op_sel:[0,1,0]
	v_pk_fma_f32 v[134:135], v[82:83], v[140:141], v[134:135] op_sel_hi:[1,0,1]
	v_pk_fma_f32 v[130:131], v[80:81], v[140:141], v[130:131] op_sel_hi:[1,0,1]
	v_mov_b32_e32 v138, v141
	v_pk_fma_f32 v[130:131], v[76:77], v[138:139], v[130:131] op_sel_hi:[1,0,1]
	v_pk_fma_f32 v[134:135], v[78:79], v[138:139], v[134:135] op_sel_hi:[1,0,1]
	ds_read_b128 v[138:141], v136 offset:3072
	s_waitcnt lgkmcnt(1)
	v_pk_fma_f32 v[134:135], v[90:91], v[146:147], v[134:135] op_sel_hi:[1,0,1]
	v_pk_fma_f32 v[130:131], v[88:89], v[146:147], v[130:131] op_sel_hi:[1,0,1]
	v_pk_fma_f32 v[134:135], v[86:87], v[146:147], v[134:135] op_sel:[0,1,0]
	v_pk_fma_f32 v[130:131], v[84:85], v[146:147], v[130:131] op_sel:[0,1,0]
	v_pk_fma_f32 v[134:135], v[98:99], v[148:149], v[134:135] op_sel_hi:[1,0,1]
	v_pk_fma_f32 v[130:131], v[96:97], v[148:149], v[130:131] op_sel_hi:[1,0,1]
	v_mov_b32_e32 v146, v149
	v_pk_fma_f32 v[130:131], v[72:73], v[146:147], v[130:131] op_sel_hi:[1,0,1]
	v_pk_fma_f32 v[134:135], v[74:75], v[146:147], v[134:135] op_sel_hi:[1,0,1]
	ds_read_b128 v[146:149], v136 offset:3088
	s_waitcnt lgkmcnt(1)
	v_pk_fma_f32 v[100:101], v[100:101], v[138:139], 0 op_sel_hi:[1,0,0]
	v_pk_fma_f32 v[102:103], v[102:103], v[138:139], 0 op_sel_hi:[1,0,0]
	v_pk_fma_f32 v[92:93], v[92:93], v[138:139], v[100:101] op_sel:[0,1,0]
	v_pk_fma_f32 v[94:95], v[94:95], v[138:139], v[102:103] op_sel:[0,1,0]
	v_pk_fma_f32 v[92:93], v[112:113], v[140:141], v[92:93] op_sel_hi:[1,0,1]
	v_pk_fma_f32 v[94:95], v[114:115], v[140:141], v[94:95] op_sel_hi:[1,0,1]
	v_mov_b32_e32 v100, v141
	v_pk_fma_f32 v[92:93], v[108:109], v[100:101], v[92:93] op_sel_hi:[1,0,1]
	v_pk_fma_f32 v[94:95], v[110:111], v[100:101], v[94:95] op_sel_hi:[1,0,1]
	s_waitcnt lgkmcnt(0)
	v_pk_fma_f32 v[92:93], v[120:121], v[146:147], v[92:93] op_sel_hi:[1,0,1]
	v_pk_fma_f32 v[94:95], v[122:123], v[146:147], v[94:95] op_sel_hi:[1,0,1]
	v_pk_fma_f32 v[92:93], v[116:117], v[146:147], v[92:93] op_sel:[0,1,0]
	v_pk_fma_f32 v[94:95], v[118:119], v[146:147], v[94:95] op_sel:[0,1,0]
	v_pk_fma_f32 v[102:103], v[124:125], v[148:149], v[92:93] op_sel_hi:[1,0,1]
	v_pk_fma_f32 v[100:101], v[126:127], v[148:149], v[94:95] op_sel_hi:[1,0,1]
	ds_read_b128 v[92:95], v136 offset:3104
	v_mov_b32_e32 v108, v149
	v_pk_fma_f32 v[104:105], v[104:105], v[108:109], v[102:103] op_sel_hi:[1,0,1]
	v_pk_fma_f32 v[106:107], v[106:107], v[108:109], v[100:101] op_sel_hi:[1,0,1]
	ds_read_b128 v[100:103], v136 offset:3120
	s_waitcnt lgkmcnt(1)
	v_pk_fma_f32 v[70:71], v[70:71], v[92:93], v[106:107] op_sel_hi:[1,0,1]
	v_pk_fma_f32 v[68:69], v[68:69], v[92:93], v[104:105] op_sel_hi:[1,0,1]
	v_pk_fma_f32 v[66:67], v[66:67], v[92:93], v[70:71] op_sel:[0,1,0]
	v_pk_fma_f32 v[64:65], v[64:65], v[92:93], v[68:69] op_sel:[0,1,0]
	v_pk_fma_f32 v[66:67], v[82:83], v[94:95], v[66:67] op_sel_hi:[1,0,1]
	v_pk_fma_f32 v[64:65], v[80:81], v[94:95], v[64:65] op_sel_hi:[1,0,1]
	v_mov_b32_e32 v68, v95
	v_pk_fma_f32 v[64:65], v[76:77], v[68:69], v[64:65] op_sel_hi:[1,0,1]
	v_pk_fma_f32 v[66:67], v[78:79], v[68:69], v[66:67] op_sel_hi:[1,0,1]
	ds_read_b128 v[68:71], v136 offset:64
	s_waitcnt lgkmcnt(1)
; #define LAS __attribute__((address_space(3)))
; DI void attn_sample_item(const Params& p, int item, ldsp lds, int tid_) {
;     ...
;     for (int t = 0; t < 4; ++t)
; #pragma unroll
;       for (int j4 = 0; j4 < 4; ++j4) { const f32x4 pp = *(const LAS f32x4*)(SC + t * 256 + wid * 32 + 16 + j4 * 4);
; #pragma unroll
;         for (int e = 0; e < 4; ++e) acc[t] += pp[e] * vvB[j4 * 4 + e]; }
	v_pk_fma_f32 v[66:67], v[90:91], v[100:101], v[66:67] op_sel_hi:[1,0,1]
	v_pk_fma_f32 v[64:65], v[88:89], v[100:101], v[64:65] op_sel_hi:[1,0,1]
	v_pk_fma_f32 v[66:67], v[86:87], v[100:101], v[66:67] op_sel:[0,1,0]
	v_pk_fma_f32 v[64:65], v[84:85], v[100:101], v[64:65] op_sel:[0,1,0]
	v_pk_fma_f32 v[66:67], v[98:99], v[102:103], v[66:67] op_sel_hi:[1,0,1]
	v_pk_fma_f32 v[64:65], v[96:97], v[102:103], v[64:65] op_sel_hi:[1,0,1]
	v_mov_b32_e32 v76, v103
	v_pk_fma_f32 v[64:65], v[72:73], v[76:77], v[64:65] op_sel_hi:[1,0,1]
	v_pk_fma_f32 v[66:67], v[74:75], v[76:77], v[66:67] op_sel_hi:[1,0,1]
	ds_read_b128 v[72:75], v136 offset:80
	s_waitcnt vmcnt(15) lgkmcnt(1)
	v_pk_fma_f32 v[76:77], v[42:43], v[68:69], v[150:151] op_sel_hi:[1,0,1]
	v_pk_fma_f32 v[78:79], v[40:41], v[68:69], v[142:143] op_sel_hi:[1,0,1]
	s_waitcnt vmcnt(14)
	v_pk_fma_f32 v[76:77], v[38:39], v[68:69], v[76:77] op_sel:[0,1,0]
	v_pk_fma_f32 v[68:69], v[36:37], v[68:69], v[78:79] op_sel:[0,1,0]
	s_waitcnt vmcnt(13)
	v_pk_fma_f32 v[76:77], v[50:51], v[70:71], v[76:77] op_sel_hi:[1,0,1]
	v_pk_fma_f32 v[68:69], v[48:49], v[70:71], v[68:69] op_sel_hi:[1,0,1]
	v_mov_b32_e32 v70, v71
	s_waitcnt vmcnt(12)
	v_pk_fma_f32 v[76:77], v[46:47], v[70:71], v[76:77] op_sel_hi:[1,0,1]
	v_pk_fma_f32 v[68:69], v[44:45], v[70:71], v[68:69] op_sel_hi:[1,0,1]
	s_waitcnt vmcnt(11) lgkmcnt(0)
	v_pk_fma_f32 v[70:71], v[58:59], v[72:73], v[76:77] op_sel_hi:[1,0,1]
	v_pk_fma_f32 v[68:69], v[56:57], v[72:73], v[68:69] op_sel_hi:[1,0,1]
	s_waitcnt vmcnt(10)
	v_pk_fma_f32 v[70:71], v[54:55], v[72:73], v[70:71] op_sel:[0,1,0]
	v_pk_fma_f32 v[68:69], v[52:53], v[72:73], v[68:69] op_sel:[0,1,0]
	s_waitcnt vmcnt(9)
	v_pk_fma_f32 v[72:73], v[62:63], v[74:75], v[70:71] op_sel_hi:[1,0,1]
	v_pk_fma_f32 v[76:77], v[60:61], v[74:75], v[68:69] op_sel_hi:[1,0,1]
	ds_read_b128 v[68:71], v136 offset:96
	v_mov_b32_e32 v74, v75
	s_waitcnt vmcnt(8)
	v_pk_fma_f32 v[78:79], v[34:35], v[74:75], v[72:73] op_sel_hi:[1,0,1]
	v_pk_fma_f32 v[76:77], v[32:33], v[74:75], v[76:77] op_sel_hi:[1,0,1]
	ds_read_b128 v[72:75], v136 offset:112
	s_waitcnt vmcnt(7) lgkmcnt(1)
	v_pk_fma_f32 v[78:79], v[14:15], v[68:69], v[78:79] op_sel_hi:[1,0,1]
	v_pk_fma_f32 v[76:77], v[12:13], v[68:69], v[76:77] op_sel_hi:[1,0,1]
	s_waitcnt vmcnt(6)
	v_pk_fma_f32 v[78:79], v[6:7], v[68:69], v[78:79] op_sel:[0,1,0]
	v_pk_fma_f32 v[68:69], v[4:5], v[68:69], v[76:77] op_sel:[0,1,0]
	s_waitcnt vmcnt(5)
	v_pk_fma_f32 v[76:77], v[22:23], v[70:71], v[78:79] op_sel_hi:[1,0,1]
	v_pk_fma_f32 v[68:69], v[20:21], v[70:71], v[68:69] op_sel_hi:[1,0,1]
	v_mov_b32_e32 v70, v71
	s_waitcnt vmcnt(4)
	v_pk_fma_f32 v[76:77], v[10:11], v[70:71], v[76:77] op_sel_hi:[1,0,1]
	v_pk_fma_f32 v[68:69], v[8:9], v[70:71], v[68:69] op_sel_hi:[1,0,1]
	s_waitcnt vmcnt(3) lgkmcnt(0)
	v_pk_fma_f32 v[70:71], v[26:27], v[72:73], v[76:77] op_sel_hi:[1,0,1]
	v_pk_fma_f32 v[68:69], v[24:25], v[72:73], v[68:69] op_sel_hi:[1,0,1]
	s_waitcnt vmcnt(2)
	v_pk_fma_f32 v[70:71], v[18:19], v[72:73], v[70:71] op_sel:[0,1,0]
	v_pk_fma_f32 v[68:69], v[16:17], v[72:73], v[68:69] op_sel:[0,1,0]
	s_waitcnt vmcnt(1)
	v_pk_fma_f32 v[72:73], v[30:31], v[74:75], v[70:71] op_sel_hi:[1,0,1]
	v_pk_fma_f32 v[76:77], v[28:29], v[74:75], v[68:69] op_sel_hi:[1,0,1]
	ds_read_b128 v[68:71], v136 offset:1088
	v_mov_b32_e32 v78, v75
	s_waitcnt vmcnt(0)
	v_pk_fma_f32 v[74:75], v[2:3], v[78:79], v[72:73] op_sel_hi:[1,0,1]
	v_pk_fma_f32 v[72:73], v[0:1], v[78:79], v[76:77] op_sel_hi:[1,0,1]
	ds_read_b128 v[76:79], v136 offset:1104
	s_waitcnt lgkmcnt(1)
	v_pk_fma_f32 v[80:81], v[42:43], v[68:69], v[132:133] op_sel_hi:[1,0,1]
	v_pk_fma_f32 v[82:83], v[40:41], v[68:69], v[128:129] op_sel_hi:[1,0,1]
	v_pk_fma_f32 v[80:81], v[38:39], v[68:69], v[80:81] op_sel:[0,1,0]
	v_pk_fma_f32 v[68:69], v[36:37], v[68:69], v[82:83] op_sel:[0,1,0]
	v_pk_fma_f32 v[80:81], v[50:51], v[70:71], v[80:81] op_sel_hi:[1,0,1]
	v_pk_fma_f32 v[68:69], v[48:49], v[70:71], v[68:69] op_sel_hi:[1,0,1]
	v_mov_b32_e32 v70, v71
	v_pk_fma_f32 v[80:81], v[46:47], v[70:71], v[80:81] op_sel_hi:[1,0,1]
	v_pk_fma_f32 v[68:69], v[44:45], v[70:71], v[68:69] op_sel_hi:[1,0,1]
	s_waitcnt lgkmcnt(0)
	v_pk_fma_f32 v[70:71], v[58:59], v[76:77], v[80:81] op_sel_hi:[1,0,1]
	v_pk_fma_f32 v[68:69], v[56:57], v[76:77], v[68:69] op_sel_hi:[1,0,1]
	v_pk_fma_f32 v[70:71], v[54:55], v[76:77], v[70:71] op_sel:[0,1,0]
	v_pk_fma_f32 v[68:69], v[52:53], v[76:77], v[68:69] op_sel:[0,1,0]
	v_pk_fma_f32 v[76:77], v[62:63], v[78:79], v[70:71] op_sel_hi:[1,0,1]
	v_pk_fma_f32 v[80:81], v[60:61], v[78:79], v[68:69] op_sel_hi:[1,0,1]
	ds_read_b128 v[68:71], v136 offset:1120
	v_mov_b32_e32 v78, v79
	v_pk_fma_f32 v[82:83], v[34:35], v[78:79], v[76:77] op_sel_hi:[1,0,1]
	v_pk_fma_f32 v[80:81], v[32:33], v[78:79], v[80:81] op_sel_hi:[1,0,1]
	ds_read_b128 v[76:79], v136 offset:1136
	s_waitcnt lgkmcnt(1)
	v_pk_fma_f32 v[82:83], v[14:15], v[68:69], v[82:83] op_sel_hi:[1,0,1]
	v_pk_fma_f32 v[80:81], v[12:13], v[68:69], v[80:81] op_sel_hi:[1,0,1]
	v_pk_fma_f32 v[82:83], v[6:7], v[68:69], v[82:83] op_sel:[0,1,0]
	v_pk_fma_f32 v[68:69], v[4:5], v[68:69], v[80:81] op_sel:[0,1,0]
	v_pk_fma_f32 v[80:81], v[22:23], v[70:71], v[82:83] op_sel_hi:[1,0,1]
	v_pk_fma_f32 v[68:69], v[20:21], v[70:71], v[68:69] op_sel_hi:[1,0,1]
	v_mov_b32_e32 v70, v71
	v_pk_fma_f32 v[80:81], v[10:11], v[70:71], v[80:81] op_sel_hi:[1,0,1]
	v_pk_fma_f32 v[68:69], v[8:9], v[70:71], v[68:69] op_sel_hi:[1,0,1]
	s_waitcnt lgkmcnt(0)
; #define LAS __attribute__((address_space(3)))
; DI void lbar() { asm volatile("s_waitcnt lgkmcnt(0)" ::: "memory"); __builtin_amdgcn_s_barrier(); asm volatile("" ::: "memory"); }
; DI void attn_sample_item(const Params& p, int item, ldsp lds, int tid_) {
;     ...
;     for (int t = 0; t < 4; ++t)
; #pragma unroll
;       for (int j4 = 0; j4 < 4; ++j4) { const f32x4 pp = *(const LAS f32x4*)(SC + t * 256 + wid * 32 + 16 + j4 * 4);
; #pragma unroll
;         for (int e = 0; e < 4; ++e) acc[t] += pp[e] * vvB[j4 * 4 + e]; }
; #pragma unroll
;     for (int t = 0; t < 4; ++t) *(LAS f32x4*)(PART + (wid * 4 + t) * 256 + lane * 4) = acc[t];
;   }
;   lbar();
;   {
;     const int e0 = tid * 2, t = e0 >> 8, d = e0 & 255;
	v_pk_fma_f32 v[70:71], v[26:27], v[76:77], v[80:81] op_sel_hi:[1,0,1]
	v_pk_fma_f32 v[68:69], v[24:25], v[76:77], v[68:69] op_sel_hi:[1,0,1]
	v_pk_fma_f32 v[70:71], v[18:19], v[76:77], v[70:71] op_sel:[0,1,0]
	v_pk_fma_f32 v[68:69], v[16:17], v[76:77], v[68:69] op_sel:[0,1,0]
	v_pk_fma_f32 v[76:77], v[30:31], v[78:79], v[70:71] op_sel_hi:[1,0,1]
	v_pk_fma_f32 v[80:81], v[28:29], v[78:79], v[68:69] op_sel_hi:[1,0,1]
	ds_read_b128 v[68:71], v136 offset:2112
	v_mov_b32_e32 v82, v79
	v_pk_fma_f32 v[78:79], v[2:3], v[82:83], v[76:77] op_sel_hi:[1,0,1]
	v_pk_fma_f32 v[76:77], v[0:1], v[82:83], v[80:81] op_sel_hi:[1,0,1]
	ds_read_b128 v[80:83], v136 offset:2128
	s_waitcnt lgkmcnt(1)
	v_pk_fma_f32 v[84:85], v[42:43], v[68:69], v[134:135] op_sel_hi:[1,0,1]
	v_pk_fma_f32 v[86:87], v[40:41], v[68:69], v[130:131] op_sel_hi:[1,0,1]
	v_pk_fma_f32 v[84:85], v[38:39], v[68:69], v[84:85] op_sel:[0,1,0]
	v_pk_fma_f32 v[68:69], v[36:37], v[68:69], v[86:87] op_sel:[0,1,0]
	v_pk_fma_f32 v[84:85], v[50:51], v[70:71], v[84:85] op_sel_hi:[1,0,1]
	v_pk_fma_f32 v[68:69], v[48:49], v[70:71], v[68:69] op_sel_hi:[1,0,1]
	v_mov_b32_e32 v70, v71
	v_pk_fma_f32 v[84:85], v[46:47], v[70:71], v[84:85] op_sel_hi:[1,0,1]
	v_pk_fma_f32 v[68:69], v[44:45], v[70:71], v[68:69] op_sel_hi:[1,0,1]
	s_waitcnt lgkmcnt(0)
	v_pk_fma_f32 v[70:71], v[58:59], v[80:81], v[84:85] op_sel_hi:[1,0,1]
	v_pk_fma_f32 v[68:69], v[56:57], v[80:81], v[68:69] op_sel_hi:[1,0,1]
	v_pk_fma_f32 v[70:71], v[54:55], v[80:81], v[70:71] op_sel:[0,1,0]
	v_pk_fma_f32 v[68:69], v[52:53], v[80:81], v[68:69] op_sel:[0,1,0]
	v_pk_fma_f32 v[80:81], v[62:63], v[82:83], v[70:71] op_sel_hi:[1,0,1]
	v_pk_fma_f32 v[84:85], v[60:61], v[82:83], v[68:69] op_sel_hi:[1,0,1]
	ds_read_b128 v[68:71], v136 offset:2144
	v_mov_b32_e32 v82, v83
	v_pk_fma_f32 v[86:87], v[34:35], v[82:83], v[80:81] op_sel_hi:[1,0,1]
	v_pk_fma_f32 v[84:85], v[32:33], v[82:83], v[84:85] op_sel_hi:[1,0,1]
	ds_read_b128 v[80:83], v136 offset:2160
	s_waitcnt lgkmcnt(1)
	v_pk_fma_f32 v[86:87], v[14:15], v[68:69], v[86:87] op_sel_hi:[1,0,1]
	v_pk_fma_f32 v[84:85], v[12:13], v[68:69], v[84:85] op_sel_hi:[1,0,1]
	v_pk_fma_f32 v[86:87], v[6:7], v[68:69], v[86:87] op_sel:[0,1,0]
	v_pk_fma_f32 v[68:69], v[4:5], v[68:69], v[84:85] op_sel:[0,1,0]
	v_pk_fma_f32 v[84:85], v[22:23], v[70:71], v[86:87] op_sel_hi:[1,0,1]
	v_pk_fma_f32 v[68:69], v[20:21], v[70:71], v[68:69] op_sel_hi:[1,0,1]
	v_mov_b32_e32 v70, v71
	v_pk_fma_f32 v[84:85], v[10:11], v[70:71], v[84:85] op_sel_hi:[1,0,1]
	v_pk_fma_f32 v[68:69], v[8:9], v[70:71], v[68:69] op_sel_hi:[1,0,1]
	s_waitcnt lgkmcnt(0)
	v_pk_fma_f32 v[70:71], v[26:27], v[80:81], v[84:85] op_sel_hi:[1,0,1]
	v_pk_fma_f32 v[68:69], v[24:25], v[80:81], v[68:69] op_sel_hi:[1,0,1]
	v_pk_fma_f32 v[70:71], v[18:19], v[80:81], v[70:71] op_sel:[0,1,0]
	v_pk_fma_f32 v[68:69], v[16:17], v[80:81], v[68:69] op_sel:[0,1,0]
	v_pk_fma_f32 v[80:81], v[30:31], v[82:83], v[70:71] op_sel_hi:[1,0,1]
	v_pk_fma_f32 v[84:85], v[28:29], v[82:83], v[68:69] op_sel_hi:[1,0,1]
	ds_read_b128 v[68:71], v136 offset:3136
	v_mov_b32_e32 v86, v83
	v_pk_fma_f32 v[82:83], v[2:3], v[86:87], v[80:81] op_sel_hi:[1,0,1]
	v_pk_fma_f32 v[80:81], v[0:1], v[86:87], v[84:85] op_sel_hi:[1,0,1]
	ds_read_b128 v[84:87], v136 offset:3152
	s_waitcnt lgkmcnt(1)
	v_pk_fma_f32 v[42:43], v[42:43], v[68:69], v[66:67] op_sel_hi:[1,0,1]
	v_pk_fma_f32 v[40:41], v[40:41], v[68:69], v[64:65] op_sel_hi:[1,0,1]
	v_pk_fma_f32 v[38:39], v[38:39], v[68:69], v[42:43] op_sel:[0,1,0]
	v_pk_fma_f32 v[36:37], v[36:37], v[68:69], v[40:41] op_sel:[0,1,0]
	v_pk_fma_f32 v[38:39], v[50:51], v[70:71], v[38:39] op_sel_hi:[1,0,1]
	v_pk_fma_f32 v[36:37], v[48:49], v[70:71], v[36:37] op_sel_hi:[1,0,1]
	v_mov_b32_e32 v40, v71
	v_pk_fma_f32 v[38:39], v[46:47], v[40:41], v[38:39] op_sel_hi:[1,0,1]
	v_pk_fma_f32 v[36:37], v[44:45], v[40:41], v[36:37] op_sel_hi:[1,0,1]
	s_waitcnt lgkmcnt(0)
	v_pk_fma_f32 v[38:39], v[58:59], v[84:85], v[38:39] op_sel_hi:[1,0,1]
	v_pk_fma_f32 v[36:37], v[56:57], v[84:85], v[36:37] op_sel_hi:[1,0,1]
	v_pk_fma_f32 v[38:39], v[54:55], v[84:85], v[38:39] op_sel:[0,1,0]
	v_pk_fma_f32 v[36:37], v[52:53], v[84:85], v[36:37] op_sel:[0,1,0]
	v_pk_fma_f32 v[40:41], v[62:63], v[86:87], v[38:39] op_sel_hi:[1,0,1]
	v_pk_fma_f32 v[42:43], v[60:61], v[86:87], v[36:37] op_sel_hi:[1,0,1]
	ds_read_b128 v[36:39], v136 offset:3168
	v_mov_b32_e32 v44, v87
	v_pk_fma_f32 v[40:41], v[34:35], v[44:45], v[40:41] op_sel_hi:[1,0,1]
	v_pk_fma_f32 v[42:43], v[32:33], v[44:45], v[42:43] op_sel_hi:[1,0,1]
	ds_read_b128 v[32:35], v136 offset:3184
	s_waitcnt lgkmcnt(1)
	v_pk_fma_f32 v[12:13], v[12:13], v[36:37], v[42:43] op_sel_hi:[1,0,1]
	v_pk_fma_f32 v[14:15], v[14:15], v[36:37], v[40:41] op_sel_hi:[1,0,1]
	v_pk_fma_f32 v[4:5], v[4:5], v[36:37], v[12:13] op_sel:[0,1,0]
	v_mov_b32_e32 v12, v39
	v_pk_fma_f32 v[4:5], v[20:21], v[38:39], v[4:5] op_sel_hi:[1,0,1]
	v_pk_fma_f32 v[6:7], v[6:7], v[36:37], v[14:15] op_sel:[0,1,0]
	v_pk_fma_f32 v[4:5], v[8:9], v[12:13], v[4:5] op_sel_hi:[1,0,1]
	v_pk_fma_f32 v[6:7], v[22:23], v[38:39], v[6:7] op_sel_hi:[1,0,1]
	s_waitcnt lgkmcnt(0)
	v_pk_fma_f32 v[4:5], v[24:25], v[32:33], v[4:5] op_sel_hi:[1,0,1]
	v_pk_fma_f32 v[6:7], v[10:11], v[12:13], v[6:7] op_sel_hi:[1,0,1]
	v_pk_fma_f32 v[4:5], v[16:17], v[32:33], v[4:5] op_sel:[0,1,0]
	v_pk_fma_f32 v[6:7], v[26:27], v[32:33], v[6:7] op_sel_hi:[1,0,1]
	v_pk_fma_f32 v[4:5], v[28:29], v[34:35], v[4:5] op_sel_hi:[1,0,1]
	v_mov_b32_e32 v8, v35
	v_pk_fma_f32 v[6:7], v[18:19], v[32:33], v[6:7] op_sel:[0,1,0]
	v_pk_fma_f32 v[0:1], v[0:1], v[8:9], v[4:5] op_sel_hi:[1,0,1]
	v_lshlrev_b32_e32 v4, 12, v210
	v_pk_fma_f32 v[6:7], v[30:31], v[34:35], v[6:7] op_sel_hi:[1,0,1]
	v_add3_u32 v4, 16, v4, v144
	v_pk_fma_f32 v[2:3], v[2:3], v[8:9], v[6:7] op_sel_hi:[1,0,1]
	ds_write_b128 v4, v[72:75] offset:4096
	ds_write_b128 v4, v[76:79] offset:5120
	ds_write_b128 v4, v[80:83] offset:6144
	ds_write_b128 v4, v[0:3] offset:7168
	v_lshlrev_b32_e32 v0, 1, v222
	v_ashrrev_i32_e32 v16, 7, v222
	v_and_b32_e32 v17, 0xfe, v0
	v_lshlrev_b32_e32 v0, 10, v16
	v_lshlrev_b32_e32 v1, 2, v17
	s_waitcnt lgkmcnt(0)
	s_barrier
; #define LAS __attribute__((address_space(3)))
; DI unsigned pk2(float lo, float hi) { f32x2 v = {lo, hi}; return __builtin_bit_cast(unsigned, __builtin_convertvector(v, bf16x2v)); }
; DI void lbar() { asm volatile("s_waitcnt lgkmcnt(0)" ::: "memory"); __builtin_amdgcn_s_barrier(); asm volatile("" ::: "memory"); }
; DI void attn_sample_item(const Params& p, int item, ldsp lds, int tid_) {
;     ...
;   const int b = item >> 2, h = item & 3;
;   bf16_t* qx = (bf16_t*)(p.ws + B_QX);
;   const float* ck = p.in[6] + ((size_t)b * 256 * 4 + h) * 256;
;   const float* cv = p.in[7] + ((size_t)b * 256 * 4 + h) * 256;
;   LAS float* SC = (LAS float*)lds;
;   LAS float* PART = (LAS float*)(lds + 4096);
;   float q[4][4];
; #pragma unroll
;   for (int t = 0; t < 4; ++t) { f32x4 a = {0.f, 0.f, 0.f, 0.f}; const float* pp = (const float*)(p.ws + B_PART) + (size_t)(b * 4 + t) * 1024 + h * 256 + lane * 4;
; #pragma unroll
;     for (int kp = 0; kp < 4; ++kp) a += *(const f32x4*)(pp + (size_t)kp * 512 * 1024);
;     q[t][0] = a[0] * 0.0625f; q[t][1] = a[1] * 0.0625f; q[t][2] = a[2] * 0.0625f; q[t][3] = a[3] * 0.0625f; }
;     ...
;     const int e0 = tid * 2, t = e0 >> 8, d = e0 & 255;
;     float s0 = 0.f, s1 = 0.f;
; #pragma unroll
;     for (int w = 0; w < 8; ++w) { const f32x2 v = *(const LAS f32x2*)(PART + (w * 4 + t) * 256 + d); s0 += v[0]; s1 += v[1]; }
;     *(unsigned*)((bf16_t*)(p.ws + B_XA) + (size_t)(TP + b * 4 + t) * D + h * 256 + d) = pk2(s0, s1);
;   }
;   lbar();
	v_add3_u32 v12, 16, v0, v1
	ds_read2st64_b64 v[0:3], v12 offset0:8 offset1:16
	ds_read2st64_b64 v[4:7], v12 offset0:24 offset1:32
	ds_read2st64_b64 v[8:11], v12 offset0:40 offset1:48
	ds_read2st64_b64 v[12:15], v12 offset0:56 offset1:64
	v_lshlrev_b32_e32 v144, 1, v17
	s_waitcnt lgkmcnt(3)
	v_pk_add_f32 v[0:1], v[0:1], 0 op_sel_hi:[1,0]
	s_cmpk_lt_i32 s40, 0x200
	v_pk_add_f32 v[0:1], v[0:1], v[2:3]
	s_waitcnt lgkmcnt(2)
	v_pk_add_f32 v[0:1], v[0:1], v[4:5]
	s_nop 0
	v_pk_add_f32 v[0:1], v[0:1], v[6:7]
	s_waitcnt lgkmcnt(1)
	v_pk_add_f32 v[0:1], v[0:1], v[8:9]
	s_nop 0
	v_pk_add_f32 v[0:1], v[0:1], v[10:11]
	s_waitcnt lgkmcnt(0)
	v_pk_add_f32 v[0:1], v[0:1], v[12:13]
	s_nop 0
	v_pk_add_f32 v[0:1], v[0:1], v[14:15]
	s_nop 0
	v_cvt_pk_bf16_f32 v2, v0, v1
	v_add_u32_e32 v0, s4, v16
	v_ashrrev_i32_e32 v1, 31, v0
	v_lshlrev_b64 v[0:1], 11, v[0:1]
	v_lshl_add_u64 v[0:1], s[22:23], 0, v[0:1]
	v_lshl_add_u64 v[0:1], v[0:1], 0, s[26:27]
	v_lshl_add_u64 v[0:1], v[0:1], 0, v[144:145]
	global_store_dword v[0:1], v2, off
	s_waitcnt lgkmcnt(0)
	s_barrier
	s_cbranch_scc0 .LBB0_1670
.LBB0_1604:
	s_ashr_i32 s4, s40, 2
	s_ashr_i32 s5, s4, 31
	s_lshl_b64 s[4:5], s[4:5], 18
	s_and_b32 s26, s0, 0x300
	v_mov_b32_e32 v222, v212
	s_or_b32 s4, s4, s26
	s_and_b32 s28, s40, -4
	s_lshl_b32 s6, s26, 2
	s_add_u32 s6, s36, s6
	v_and_b32_e32 v223, 63, v222
	s_addc_u32 s7, s37, 0
	v_lshlrev_b32_e32 v144, 4, v223
	s_ashr_i32 s29, s28, 31
	v_lshl_add_u64 v[48:49], s[6:7], 0, v[144:145]
	s_lshl_b64 s[6:7], s[28:29], 12
	v_lshl_add_u64 v[8:9], v[48:49], 0, s[6:7]
	v_add_co_u32_e32 v4, vcc, s3, v8
	s_or_b32 s6, s28, 1
	s_nop 0
	v_addc_co_u32_e32 v5, vcc, 0, v9, vcc
	v_add_co_u32_e32 v10, vcc, s33, v8
	s_ashr_i32 s7, s6, 31
	s_nop 0
	v_addc_co_u32_e32 v11, vcc, 0, v9, vcc
	v_add_co_u32_e32 v12, vcc, s38, v8
	s_lshl_b64 s[6:7], s[6:7], 12
	s_nop 0
	v_addc_co_u32_e32 v13, vcc, 0, v9, vcc
	v_lshl_add_u64 v[24:25], v[48:49], 0, s[6:7]
	v_add_co_u32_e32 v20, vcc, s3, v24
	s_or_b32 s6, s28, 2
	s_nop 0
	v_addc_co_u32_e32 v21, vcc, 0, v25, vcc
	v_add_co_u32_e32 v26, vcc, s33, v24
	s_ashr_i32 s7, s6, 31
	s_nop 0
	v_addc_co_u32_e32 v27, vcc, 0, v25, vcc
	v_add_co_u32_e32 v28, vcc, s38, v24
	s_lshl_b64 s[6:7], s[6:7], 12
	global_load_dwordx4 v[0:3], v[8:9], off
	s_nop 0
	global_load_dwordx4 v[4:7], v[4:5], off
	v_addc_co_u32_e32 v29, vcc, 0, v25, vcc
	v_lshl_add_u64 v[44:45], v[48:49], 0, s[6:7]
	global_load_dwordx4 v[8:11], v[10:11], off
	s_nop 0
	global_load_dwordx4 v[12:15], v[12:13], off
	s_nop 0
	global_load_dwordx4 v[16:19], v[24:25], off
	s_nop 0
	global_load_dwordx4 v[20:23], v[20:21], off
	v_add_co_u32_e32 v36, vcc, s3, v44
	global_load_dwordx4 v[24:27], v[26:27], off
	s_nop 0
	global_load_dwordx4 v[28:31], v[28:29], off
	v_addc_co_u32_e32 v37, vcc, 0, v45, vcc
	v_add_co_u32_e32 v40, vcc, s33, v44
	global_load_dwordx4 v[32:35], v[44:45], off
	s_nop 0
	global_load_dwordx4 v[36:39], v[36:37], off
	v_addc_co_u32_e32 v41, vcc, 0, v45, vcc
	v_add_co_u32_e32 v44, vcc, s38, v44
	global_load_dwordx4 v[40:43], v[40:41], off
	s_nop 0
	v_addc_co_u32_e32 v45, vcc, 0, v45, vcc
	global_load_dwordx4 v[44:47], v[44:45], off
	s_or_b32 s6, s40, 3
	s_ashr_i32 s7, s6, 31
	s_lshl_b64 s[6:7], s[6:7], 12
	s_lshl_b64 s[30:31], s[4:5], 2
	s_add_u32 s4, s12, s30
	s_addc_u32 s5, s13, s31
	s_waitcnt vmcnt(11)
	v_pk_add_f32 v[2:3], v[2:3], 0 op_sel_hi:[1,0]
	v_pk_add_f32 v[0:1], v[0:1], 0 op_sel_hi:[1,0]
	s_waitcnt vmcnt(10)
	v_pk_add_f32 v[2:3], v[2:3], v[6:7]
	v_pk_add_f32 v[0:1], v[0:1], v[4:5]
	s_waitcnt vmcnt(9)
	v_pk_add_f32 v[2:3], v[2:3], v[10:11]
	s_waitcnt vmcnt(7)
	v_pk_add_f32 v[4:5], v[18:19], 0 op_sel_hi:[1,0]
	v_pk_add_f32 v[6:7], v[16:17], 0 op_sel_hi:[1,0]
	v_pk_add_f32 v[0:1], v[0:1], v[8:9]
	s_waitcnt vmcnt(6)
	v_pk_add_f32 v[4:5], v[4:5], v[22:23]
	v_pk_add_f32 v[6:7], v[6:7], v[20:21]
	v_pk_add_f32 v[2:3], v[2:3], v[14:15]
	v_pk_add_f32 v[0:1], v[0:1], v[12:13]
	s_waitcnt vmcnt(5)
	v_pk_add_f32 v[4:5], v[4:5], v[26:27]
	v_pk_add_f32 v[6:7], v[6:7], v[24:25]
	v_mul_f32_e32 v228, 0x3d800000, v0
	v_mul_f32_e32 v231, 0x3d800000, v1
	v_mul_f32_e32 v229, 0x3d800000, v2
	v_mul_f32_e32 v225, 0x3d800000, v3
	s_waitcnt vmcnt(4)
	v_pk_add_f32 v[0:1], v[4:5], v[30:31]
	v_pk_add_f32 v[2:3], v[6:7], v[28:29]
	v_mul_f32_e32 v227, 0x3d800000, v0
	v_mul_f32_e32 v226, 0x3d800000, v2
	v_mul_f32_e32 v230, 0x3d800000, v3
	v_mul_f32_e32 v224, 0x3d800000, v1
	s_waitcnt vmcnt(3)
	v_pk_add_f32 v[0:1], v[34:35], 0 op_sel_hi:[1,0]
	v_pk_add_f32 v[2:3], v[32:33], 0 op_sel_hi:[1,0]
	s_waitcnt vmcnt(2)
	v_pk_add_f32 v[0:1], v[0:1], v[38:39]
	v_pk_add_f32 v[2:3], v[2:3], v[36:37]
	s_waitcnt vmcnt(1)
	v_pk_add_f32 v[0:1], v[0:1], v[42:43]
	v_pk_add_f32 v[2:3], v[2:3], v[40:41]
	s_waitcnt vmcnt(0)
; DI void attn_sample_item(const Params& p, int item, ldsp lds, int tid_) {
;     ...
;   for (int t = 0; t < 4; ++t) { f32x4 a = {0.f, 0.f, 0.f, 0.f}; const float* pp = (const float*)(p.ws + B_PART) + (size_t)(b * 4 + t) * 1024 + h * 256 + lane * 4;
; #pragma unroll
;     for (int kp = 0; kp < 4; ++kp) a += *(const f32x4*)(pp + (size_t)kp * 512 * 1024);
;     q[t][0] = a[0] * 0.0625f; q[t][1] = a[1] * 0.0625f; q[t][2] = a[2] * 0.0625f; q[t][3] = a[3] * 0.0625f; }
;   const bool b0 = lane & 1, b1 = lane & 2;
;   f32x4 kvA[16], kvB[16];
; #pragma unroll
;   for (int j = 0; j < 16; ++j) kvA[j] = __builtin_nontemporal_load((const f32x4*)(ck + (size_t)(wid * 32 + j) * 1024 + lane * 4));
; #pragma unroll
;   for (int j = 0; j < 16; ++j) kvB[j] = __builtin_nontemporal_load((const f32x4*)(ck + (size_t)(wid * 32 + 16 + j) * 1024 + lane * 4));
	v_pk_add_f32 v[210:211], v[0:1], v[46:47]
	v_pk_add_f32 v[0:1], v[2:3], v[44:45]
	v_mul_f32_e32 v233, 0x3d800000, v210
	v_mul_f32_e32 v232, 0x3d800000, v0
	v_mul_f32_e32 v234, 0x3d800000, v1
	v_lshl_add_u64 v[0:1], v[48:49], 0, s[6:7]
	v_add_co_u32_e32 v2, vcc, s3, v0
	v_ashrrev_i32_e32 v210, 6, v222
	s_nop 0
	v_addc_co_u32_e32 v3, vcc, 0, v1, vcc
	global_load_dwordx4 v[128:131], v[0:1], off
	global_load_dwordx4 v[132:135], v[2:3], off
	v_add_co_u32_e32 v2, vcc, s33, v0
	v_mul_f32_e32 v211, 0x3d800000, v211
	s_nop 0
	v_addc_co_u32_e32 v3, vcc, 0, v1, vcc
	v_add_co_u32_e32 v0, vcc, s38, v0
	v_cmp_lt_i32_e64 s[6:7], v218, v216
	s_nop 0
	v_addc_co_u32_e32 v1, vcc, 0, v1, vcc
	global_load_dwordx4 v[136:139], v[2:3], off
	global_load_dwordx4 v[140:143], v[0:1], off
	v_lshlrev_b32_e32 v0, 5, v210
	v_ashrrev_i32_e32 v1, 31, v0
	v_or_b32_e32 v6, 1, v0
	v_lshl_add_u64 v[2:3], s[4:5], 0, v[144:145]
	v_lshlrev_b64 v[162:163], 12, v[0:1]
	v_ashrrev_i32_e32 v7, 31, v6
	v_lshl_add_u64 v[4:5], v[2:3], 0, v[162:163]
	v_lshlrev_b64 v[166:167], 12, v[6:7]
	v_lshl_add_u64 v[6:7], v[2:3], 0, v[166:167]
	global_load_dwordx4 v[124:127], v[4:5], off nt
	global_load_dwordx4 v[120:123], v[6:7], off nt
	v_or_b32_e32 v4, 2, v0
	v_ashrrev_i32_e32 v5, 31, v4
	v_or_b32_e32 v6, 3, v0
	v_lshlrev_b64 v[168:169], 12, v[4:5]
	v_ashrrev_i32_e32 v7, 31, v6
	v_lshl_add_u64 v[4:5], v[2:3], 0, v[168:169]
	v_lshlrev_b64 v[172:173], 12, v[6:7]
	v_lshl_add_u64 v[6:7], v[2:3], 0, v[172:173]
	global_load_dwordx4 v[116:119], v[4:5], off nt
	global_load_dwordx4 v[112:115], v[6:7], off nt
	v_or_b32_e32 v4, 4, v0
	v_ashrrev_i32_e32 v5, 31, v4
	v_or_b32_e32 v6, 5, v0
	v_lshlrev_b64 v[176:177], 12, v[4:5]
	v_ashrrev_i32_e32 v7, 31, v6
	v_lshl_add_u64 v[4:5], v[2:3], 0, v[176:177]
	v_lshlrev_b64 v[180:181], 12, v[6:7]
	v_lshl_add_u64 v[6:7], v[2:3], 0, v[180:181]
	global_load_dwordx4 v[108:111], v[4:5], off nt
	global_load_dwordx4 v[104:107], v[6:7], off nt
	v_or_b32_e32 v4, 6, v0
	v_ashrrev_i32_e32 v5, 31, v4
	v_or_b32_e32 v6, 7, v0
	v_lshlrev_b64 v[182:183], 12, v[4:5]
	v_ashrrev_i32_e32 v7, 31, v6
	v_lshl_add_u64 v[4:5], v[2:3], 0, v[182:183]
	v_lshlrev_b64 v[186:187], 12, v[6:7]
	v_lshl_add_u64 v[6:7], v[2:3], 0, v[186:187]
	global_load_dwordx4 v[100:103], v[4:5], off nt
	global_load_dwordx4 v[96:99], v[6:7], off nt
	v_or_b32_e32 v4, 8, v0
	v_ashrrev_i32_e32 v5, 31, v4
	v_or_b32_e32 v6, 9, v0
	v_lshlrev_b64 v[190:191], 12, v[4:5]
	v_ashrrev_i32_e32 v7, 31, v6
	v_lshl_add_u64 v[4:5], v[2:3], 0, v[190:191]
	v_lshlrev_b64 v[194:195], 12, v[6:7]
	v_lshl_add_u64 v[6:7], v[2:3], 0, v[194:195]
	global_load_dwordx4 v[92:95], v[4:5], off nt
	global_load_dwordx4 v[88:91], v[6:7], off nt
	v_or_b32_e32 v4, 10, v0
	v_ashrrev_i32_e32 v5, 31, v4
	v_or_b32_e32 v6, 11, v0
	v_lshlrev_b64 v[198:199], 12, v[4:5]
	v_ashrrev_i32_e32 v7, 31, v6
	v_lshl_add_u64 v[4:5], v[2:3], 0, v[198:199]
	v_lshlrev_b64 v[200:201], 12, v[6:7]
	v_lshl_add_u64 v[6:7], v[2:3], 0, v[200:201]
	global_load_dwordx4 v[84:87], v[4:5], off nt
	global_load_dwordx4 v[80:83], v[6:7], off nt
	v_or_b32_e32 v4, 12, v0
	v_ashrrev_i32_e32 v5, 31, v4
	v_or_b32_e32 v6, 13, v0
	v_lshlrev_b64 v[202:203], 12, v[4:5]
	v_ashrrev_i32_e32 v7, 31, v6
	v_lshl_add_u64 v[4:5], v[2:3], 0, v[202:203]
	v_lshlrev_b64 v[204:205], 12, v[6:7]
	v_lshl_add_u64 v[6:7], v[2:3], 0, v[204:205]
	global_load_dwordx4 v[76:79], v[4:5], off nt
	global_load_dwordx4 v[72:75], v[6:7], off nt
	v_or_b32_e32 v4, 14, v0
	v_ashrrev_i32_e32 v5, 31, v4
	v_or_b32_e32 v6, 15, v0
	v_lshlrev_b64 v[206:207], 12, v[4:5]
	v_ashrrev_i32_e32 v7, 31, v6
	v_lshl_add_u64 v[4:5], v[2:3], 0, v[206:207]
	v_lshlrev_b64 v[208:209], 12, v[6:7]
	v_lshl_add_u64 v[6:7], v[2:3], 0, v[208:209]
	global_load_dwordx4 v[68:71], v[4:5], off nt
	global_load_dwordx4 v[64:67], v[6:7], off nt
	v_or_b32_e32 v4, 16, v0
	v_ashrrev_i32_e32 v5, 31, v4
	v_or_b32_e32 v6, 17, v0
	v_lshlrev_b64 v[146:147], 12, v[4:5]
	v_ashrrev_i32_e32 v7, 31, v6
	v_lshl_add_u64 v[4:5], v[2:3], 0, v[146:147]
	v_lshlrev_b64 v[148:149], 12, v[6:7]
	v_lshl_add_u64 v[6:7], v[2:3], 0, v[148:149]
	global_load_dwordx4 v[60:63], v[4:5], off nt
	global_load_dwordx4 v[56:59], v[6:7], off nt
	v_or_b32_e32 v4, 18, v0
	v_ashrrev_i32_e32 v5, 31, v4
	v_or_b32_e32 v6, 19, v0
	v_lshlrev_b64 v[150:151], 12, v[4:5]
	v_ashrrev_i32_e32 v7, 31, v6
	v_lshl_add_u64 v[4:5], v[2:3], 0, v[150:151]
	v_lshlrev_b64 v[152:153], 12, v[6:7]
	v_lshl_add_u64 v[6:7], v[2:3], 0, v[152:153]
	global_load_dwordx4 v[52:55], v[4:5], off nt
	global_load_dwordx4 v[48:51], v[6:7], off nt
	v_or_b32_e32 v4, 20, v0
	v_ashrrev_i32_e32 v5, 31, v4
	v_or_b32_e32 v6, 21, v0
	v_lshlrev_b64 v[154:155], 12, v[4:5]
	v_ashrrev_i32_e32 v7, 31, v6
	v_lshl_add_u64 v[4:5], v[2:3], 0, v[154:155]
	v_lshlrev_b64 v[156:157], 12, v[6:7]
	v_lshl_add_u64 v[6:7], v[2:3], 0, v[156:157]
	global_load_dwordx4 v[44:47], v[4:5], off nt
	global_load_dwordx4 v[40:43], v[6:7], off nt
	v_or_b32_e32 v4, 22, v0
	v_ashrrev_i32_e32 v5, 31, v4
	v_or_b32_e32 v6, 23, v0
	v_lshlrev_b64 v[158:159], 12, v[4:5]
	v_ashrrev_i32_e32 v7, 31, v6
	v_lshl_add_u64 v[4:5], v[2:3], 0, v[158:159]
	v_lshlrev_b64 v[160:161], 12, v[6:7]
	v_lshl_add_u64 v[6:7], v[2:3], 0, v[160:161]
	global_load_dwordx4 v[36:39], v[4:5], off nt
	global_load_dwordx4 v[32:35], v[6:7], off nt
	v_or_b32_e32 v4, 24, v0
	v_ashrrev_i32_e32 v5, 31, v4
	v_or_b32_e32 v6, 25, v0
	v_lshlrev_b64 v[164:165], 12, v[4:5]
	v_ashrrev_i32_e32 v7, 31, v6
	v_lshl_add_u64 v[4:5], v[2:3], 0, v[164:165]
	v_lshlrev_b64 v[170:171], 12, v[6:7]
	v_lshl_add_u64 v[6:7], v[2:3], 0, v[170:171]
	global_load_dwordx4 v[28:31], v[4:5], off nt
	global_load_dwordx4 v[24:27], v[6:7], off nt
	v_or_b32_e32 v4, 26, v0
	v_ashrrev_i32_e32 v5, 31, v4
	v_or_b32_e32 v6, 27, v0
	v_lshlrev_b64 v[174:175], 12, v[4:5]
	v_ashrrev_i32_e32 v7, 31, v6
	v_lshl_add_u64 v[4:5], v[2:3], 0, v[174:175]
	v_lshlrev_b64 v[178:179], 12, v[6:7]
	v_lshl_add_u64 v[6:7], v[2:3], 0, v[178:179]
	global_load_dwordx4 v[20:23], v[4:5], off nt
	global_load_dwordx4 v[16:19], v[6:7], off nt
	v_or_b32_e32 v4, 28, v0
	v_ashrrev_i32_e32 v5, 31, v4
	v_or_b32_e32 v6, 29, v0
	v_lshlrev_b64 v[184:185], 12, v[4:5]
	v_ashrrev_i32_e32 v7, 31, v6
	v_lshl_add_u64 v[4:5], v[2:3], 0, v[184:185]
	v_lshlrev_b64 v[188:189], 12, v[6:7]
	v_lshl_add_u64 v[6:7], v[2:3], 0, v[188:189]
	global_load_dwordx4 v[12:15], v[4:5], off nt
	global_load_dwordx4 v[8:11], v[6:7], off nt
	v_or_b32_e32 v4, 30, v0
	v_or_b32_e32 v0, 31, v0
	v_ashrrev_i32_e32 v5, 31, v4
	v_ashrrev_i32_e32 v1, 31, v0
	v_lshlrev_b64 v[192:193], 12, v[4:5]
	v_lshlrev_b64 v[196:197], 12, v[0:1]
	v_lshl_add_u64 v[4:5], v[2:3], 0, v[192:193]
	v_lshl_add_u64 v[0:1], v[2:3], 0, v[196:197]
	global_load_dwordx4 v[4:7], v[4:5], off nt
	s_nop 0
	global_load_dwordx4 v[0:3], v[0:1], off nt
	s_waitcnt vmcnt(35)
; #define LAS __attribute__((address_space(3)))
; DI void attn_sample_item(const Params& p, int item, ldsp lds, int tid_) {
;     ...
;   const float* cv = p.in[7] + ((size_t)b * 256 * 4 + h) * 256;
;   LAS float* SC = (LAS float*)lds;
;   LAS float* PART = (LAS float*)(lds + 4096);
;   float q[4][4];
; #pragma unroll
;   for (int t = 0; t < 4; ++t) { f32x4 a = {0.f, 0.f, 0.f, 0.f}; const float* pp = (const float*)(p.ws + B_PART) + (size_t)(b * 4 + t) * 1024 + h * 256 + lane * 4;
; #pragma unroll
;     for (int kp = 0; kp < 4; ++kp) a += *(const f32x4*)(pp + (size_t)kp * 512 * 1024);
;     q[t][0] = a[0] * 0.0625f; q[t][1] = a[1] * 0.0625f; q[t][2] = a[2] * 0.0625f; q[t][3] = a[3] * 0.0625f; }
;   const bool b0 = lane & 1, b1 = lane & 2;
;   f32x4 kvA[16], kvB[16];
; #pragma unroll
;   for (int j = 0; j < 16; ++j) kvA[j] = __builtin_nontemporal_load((const f32x4*)(ck + (size_t)(wid * 32 + j) * 1024 + lane * 4));
; #pragma unroll
;   for (int j = 0; j < 16; ++j) kvB[j] = __builtin_nontemporal_load((const f32x4*)(ck + (size_t)(wid * 32 + 16 + j) * 1024 + lane * 4));
;     ...
;   SC_SCORE(kvA, 0)
	v_pk_add_f32 v[128:129], v[128:129], 0 op_sel_hi:[1,0]
	v_pk_add_f32 v[130:131], v[130:131], 0 op_sel_hi:[1,0]
	s_waitcnt vmcnt(34)
	v_pk_add_f32 v[128:129], v[128:129], v[132:133]
	v_pk_add_f32 v[130:131], v[130:131], v[134:135]
	s_waitcnt vmcnt(33)
	v_pk_add_f32 v[128:129], v[128:129], v[136:137]
	v_pk_add_f32 v[130:131], v[130:131], v[138:139]
	s_waitcnt vmcnt(32)
	v_pk_add_f32 v[128:129], v[128:129], v[140:141]
	v_pk_add_f32 v[130:131], v[130:131], v[142:143]
	v_mul_f32_e32 v138, 0x3d800000, v129
	v_mul_f32_e32 v135, 0x3d800000, v128
	v_mul_f32_e32 v134, 0x3d800000, v131
	s_add_u32 s66, s14, s30
	s_addc_u32 s67, s15, s31
	v_mul_f32_e32 v137, 0x3d800000, v130
	v_lshlrev_b32_e32 v128, 2, v215
	v_lshlrev_b32_e32 v129, 2, v217
	v_lshlrev_b32_e32 v130, 2, v218
	v_lshlrev_b32_e32 v131, 2, v219
	v_lshlrev_b32_e32 v132, 2, v220
	v_lshlrev_b32_e32 v133, 2, v221
	v_lshl_add_u32 v136, v210, 7, 16
	v_and_b32_e32 v139, 3, v223
	v_bfrev_b32_e32 v139, v139
	v_lshrrev_b32_e32 v139, 20, v139
	v_and_b32_e32 v235, -4, v223
	v_add3_u32 v235, v136, v139, v235
	v_mov_b32_e32 v236, v228
	v_mov_b32_e32 v237, v226
	v_mov_b32_e32 v238, v231
	v_mov_b32_e32 v239, v230
	v_mov_b32_e32 v240, v229
	v_mov_b32_e32 v241, v227
	v_mov_b32_e32 v242, v225
	v_mov_b32_e32 v243, v224
	v_mov_b32_e32 v244, v232
	v_mov_b32_e32 v245, v135
	v_mov_b32_e32 v246, v234
	v_mov_b32_e32 v247, v138
	v_mov_b32_e32 v248, v233
	v_mov_b32_e32 v249, v137
	v_mov_b32_e32 v250, v211
	v_mov_b32_e32 v251, v134
	s_mov_b32 vcc_lo, 0x55555555
	s_mov_b32 vcc_hi, 0x55555555
	s_mov_b32 s4, 0x33333333
	s_mov_b32 s5, 0x33333333
	s_mov_b32 s6, 0x0f0f0f0f
	s_mov_b32 s7, 0x0f0f0f0f
	s_mov_b32 s64, 0x00ff00ff
	s_mov_b32 s65, 0x00ff00ff
	s_waitcnt vmcnt(31)
	v_pk_mul_f32 v[252:253], v[236:237], v[124:125] op_sel_hi:[1,0]
	v_pk_mul_f32 v[254:255], v[244:245], v[124:125] op_sel_hi:[1,0]
	v_pk_fma_f32 v[252:253], v[238:239], v[124:125], v[252:253] op_sel:[0,1,0]
	v_pk_fma_f32 v[254:255], v[246:247], v[124:125], v[254:255] op_sel:[0,1,0]
	v_pk_fma_f32 v[252:253], v[240:241], v[126:127], v[252:253] op_sel_hi:[1,0,1]
	v_pk_fma_f32 v[254:255], v[248:249], v[126:127], v[254:255] op_sel_hi:[1,0,1]
	v_pk_fma_f32 v[252:253], v[242:243], v[126:127], v[252:253] op_sel:[0,1,0]
	v_pk_fma_f32 v[254:255], v[250:251], v[126:127], v[254:255] op_sel:[0,1,0]
	s_waitcnt vmcnt(30)
	v_pk_mul_f32 v[140:141], v[236:237], v[120:121] op_sel_hi:[1,0]
	v_pk_mul_f32 v[142:143], v[244:245], v[120:121] op_sel_hi:[1,0]
	v_pk_fma_f32 v[140:141], v[238:239], v[120:121], v[140:141] op_sel:[0,1,0]
	v_pk_fma_f32 v[142:143], v[246:247], v[120:121], v[142:143] op_sel:[0,1,0]
	v_pk_fma_f32 v[140:141], v[240:241], v[122:123], v[140:141] op_sel_hi:[1,0,1]
	v_pk_fma_f32 v[142:143], v[248:249], v[122:123], v[142:143] op_sel_hi:[1,0,1]
	v_pk_fma_f32 v[140:141], v[242:243], v[122:123], v[140:141] op_sel:[0,1,0]
	v_pk_fma_f32 v[142:143], v[250:251], v[122:123], v[142:143] op_sel:[0,1,0]
	v_add_f32_dpp v124, v252, v252 quad_perm:[1,0,3,2] row_mask:0xf bank_mask:0xf
	v_add_f32_dpp v125, v253, v253 quad_perm:[1,0,3,2] row_mask:0xf bank_mask:0xf
	v_add_f32_dpp v126, v254, v254 quad_perm:[1,0,3,2] row_mask:0xf bank_mask:0xf
	v_add_f32_dpp v127, v255, v255 quad_perm:[1,0,3,2] row_mask:0xf bank_mask:0xf
	v_cndmask_b32_e32 v124, v126, v124, vcc
	v_cndmask_b32_e32 v125, v127, v125, vcc
	s_waitcnt vmcnt(29)
	v_pk_mul_f32 v[252:253], v[236:237], v[116:117] op_sel_hi:[1,0]
	v_pk_mul_f32 v[254:255], v[244:245], v[116:117] op_sel_hi:[1,0]
	v_pk_fma_f32 v[252:253], v[238:239], v[116:117], v[252:253] op_sel:[0,1,0]
	v_pk_fma_f32 v[254:255], v[246:247], v[116:117], v[254:255] op_sel:[0,1,0]
	v_pk_fma_f32 v[252:253], v[240:241], v[118:119], v[252:253] op_sel_hi:[1,0,1]
	v_pk_fma_f32 v[254:255], v[248:249], v[118:119], v[254:255] op_sel_hi:[1,0,1]
	v_pk_fma_f32 v[252:253], v[242:243], v[118:119], v[252:253] op_sel:[0,1,0]
	v_pk_fma_f32 v[254:255], v[250:251], v[118:119], v[254:255] op_sel:[0,1,0]
	v_add_f32_dpp v120, v140, v140 quad_perm:[1,0,3,2] row_mask:0xf bank_mask:0xf
	v_add_f32_dpp v121, v141, v141 quad_perm:[1,0,3,2] row_mask:0xf bank_mask:0xf
	v_add_f32_dpp v122, v142, v142 quad_perm:[1,0,3,2] row_mask:0xf bank_mask:0xf
	v_add_f32_dpp v123, v143, v143 quad_perm:[1,0,3,2] row_mask:0xf bank_mask:0xf
	v_cndmask_b32_e32 v120, v122, v120, vcc
	v_cndmask_b32_e32 v121, v123, v121, vcc
	v_add_f32_dpp v126, v124, v124 quad_perm:[2,3,0,1] row_mask:0xf bank_mask:0xf
	v_add_f32_dpp v127, v125, v125 quad_perm:[2,3,0,1] row_mask:0xf bank_mask:0xf
	v_cndmask_b32_e64 v124, v127, v126, s[4:5]
	s_waitcnt vmcnt(28)
	v_pk_mul_f32 v[140:141], v[236:237], v[112:113] op_sel_hi:[1,0]
	v_pk_mul_f32 v[142:143], v[244:245], v[112:113] op_sel_hi:[1,0]
	v_pk_fma_f32 v[140:141], v[238:239], v[112:113], v[140:141] op_sel:[0,1,0]
	v_pk_fma_f32 v[142:143], v[246:247], v[112:113], v[142:143] op_sel:[0,1,0]
	v_pk_fma_f32 v[140:141], v[240:241], v[114:115], v[140:141] op_sel_hi:[1,0,1]
	v_pk_fma_f32 v[142:143], v[248:249], v[114:115], v[142:143] op_sel_hi:[1,0,1]
	v_pk_fma_f32 v[140:141], v[242:243], v[114:115], v[140:141] op_sel:[0,1,0]
	v_pk_fma_f32 v[142:143], v[250:251], v[114:115], v[142:143] op_sel:[0,1,0]
	v_add_f32_dpp v116, v252, v252 quad_perm:[1,0,3,2] row_mask:0xf bank_mask:0xf
	v_add_f32_dpp v117, v253, v253 quad_perm:[1,0,3,2] row_mask:0xf bank_mask:0xf
	v_add_f32_dpp v118, v254, v254 quad_perm:[1,0,3,2] row_mask:0xf bank_mask:0xf
	v_add_f32_dpp v119, v255, v255 quad_perm:[1,0,3,2] row_mask:0xf bank_mask:0xf
	v_cndmask_b32_e32 v116, v118, v116, vcc
	v_cndmask_b32_e32 v117, v119, v117, vcc
	v_add_f32_dpp v122, v120, v120 quad_perm:[2,3,0,1] row_mask:0xf bank_mask:0xf
	v_add_f32_dpp v123, v121, v121 quad_perm:[2,3,0,1] row_mask:0xf bank_mask:0xf
	v_cndmask_b32_e64 v120, v123, v122, s[4:5]
	v_cndmask_b32_e64 v125, v120, v124, s[6:7]
	v_cndmask_b32_e64 v126, v124, v120, s[6:7]
	s_waitcnt vmcnt(27)
; DI void attn_sample_item(const Params& p, int item, ldsp lds, int tid_) {
;     ...
;   SC_SCORE(kvA, 0)
;   SC_SCORE(kvB, 1)
	v_pk_mul_f32 v[252:253], v[236:237], v[108:109] op_sel_hi:[1,0]
	v_pk_mul_f32 v[254:255], v[244:245], v[108:109] op_sel_hi:[1,0]
	v_pk_fma_f32 v[252:253], v[238:239], v[108:109], v[252:253] op_sel:[0,1,0]
	v_pk_fma_f32 v[254:255], v[246:247], v[108:109], v[254:255] op_sel:[0,1,0]
	v_pk_fma_f32 v[252:253], v[240:241], v[110:111], v[252:253] op_sel_hi:[1,0,1]
	v_pk_fma_f32 v[254:255], v[248:249], v[110:111], v[254:255] op_sel_hi:[1,0,1]
	v_pk_fma_f32 v[252:253], v[242:243], v[110:111], v[252:253] op_sel:[0,1,0]
	v_pk_fma_f32 v[254:255], v[250:251], v[110:111], v[254:255] op_sel:[0,1,0]
	v_add_f32_dpp v124, v126, v125 row_ror:4 row_mask:0xf bank_mask:0xf
	v_add_f32_dpp v112, v140, v140 quad_perm:[1,0,3,2] row_mask:0xf bank_mask:0xf
	v_add_f32_dpp v113, v141, v141 quad_perm:[1,0,3,2] row_mask:0xf bank_mask:0xf
	v_add_f32_dpp v114, v142, v142 quad_perm:[1,0,3,2] row_mask:0xf bank_mask:0xf
	v_add_f32_dpp v115, v143, v143 quad_perm:[1,0,3,2] row_mask:0xf bank_mask:0xf
	v_cndmask_b32_e32 v112, v114, v112, vcc
	v_cndmask_b32_e32 v113, v115, v113, vcc
	v_add_f32_dpp v118, v116, v116 quad_perm:[2,3,0,1] row_mask:0xf bank_mask:0xf
	v_add_f32_dpp v119, v117, v117 quad_perm:[2,3,0,1] row_mask:0xf bank_mask:0xf
	v_cndmask_b32_e64 v116, v119, v118, s[4:5]
	s_waitcnt vmcnt(26)
	v_pk_mul_f32 v[140:141], v[236:237], v[104:105] op_sel_hi:[1,0]
	v_pk_mul_f32 v[142:143], v[244:245], v[104:105] op_sel_hi:[1,0]
	v_pk_fma_f32 v[140:141], v[238:239], v[104:105], v[140:141] op_sel:[0,1,0]
	v_pk_fma_f32 v[142:143], v[246:247], v[104:105], v[142:143] op_sel:[0,1,0]
	v_pk_fma_f32 v[140:141], v[240:241], v[106:107], v[140:141] op_sel_hi:[1,0,1]
	v_pk_fma_f32 v[142:143], v[248:249], v[106:107], v[142:143] op_sel_hi:[1,0,1]
	v_pk_fma_f32 v[140:141], v[242:243], v[106:107], v[140:141] op_sel:[0,1,0]
	v_pk_fma_f32 v[142:143], v[250:251], v[106:107], v[142:143] op_sel:[0,1,0]
	v_add_f32_dpp v108, v252, v252 quad_perm:[1,0,3,2] row_mask:0xf bank_mask:0xf
	v_add_f32_dpp v109, v253, v253 quad_perm:[1,0,3,2] row_mask:0xf bank_mask:0xf
	v_add_f32_dpp v110, v254, v254 quad_perm:[1,0,3,2] row_mask:0xf bank_mask:0xf
	v_add_f32_dpp v111, v255, v255 quad_perm:[1,0,3,2] row_mask:0xf bank_mask:0xf
	v_cndmask_b32_e32 v108, v110, v108, vcc
	v_cndmask_b32_e32 v109, v111, v109, vcc
	v_add_f32_dpp v114, v112, v112 quad_perm:[2,3,0,1] row_mask:0xf bank_mask:0xf
	v_add_f32_dpp v115, v113, v113 quad_perm:[2,3,0,1] row_mask:0xf bank_mask:0xf
	v_cndmask_b32_e64 v112, v115, v114, s[4:5]
	v_cndmask_b32_e64 v117, v112, v116, s[6:7]
	v_cndmask_b32_e64 v118, v116, v112, s[6:7]
	s_waitcnt vmcnt(25)
	v_pk_mul_f32 v[252:253], v[236:237], v[100:101] op_sel_hi:[1,0]
	v_pk_mul_f32 v[254:255], v[244:245], v[100:101] op_sel_hi:[1,0]
	v_pk_fma_f32 v[252:253], v[238:239], v[100:101], v[252:253] op_sel:[0,1,0]
	v_pk_fma_f32 v[254:255], v[246:247], v[100:101], v[254:255] op_sel:[0,1,0]
	v_pk_fma_f32 v[252:253], v[240:241], v[102:103], v[252:253] op_sel_hi:[1,0,1]
	v_pk_fma_f32 v[254:255], v[248:249], v[102:103], v[254:255] op_sel_hi:[1,0,1]
	v_pk_fma_f32 v[252:253], v[242:243], v[102:103], v[252:253] op_sel:[0,1,0]
	v_pk_fma_f32 v[254:255], v[250:251], v[102:103], v[254:255] op_sel:[0,1,0]
	v_add_f32_dpp v116, v118, v117 row_ror:4 row_mask:0xf bank_mask:0xf
	v_cndmask_b32_e64 v125, v116, v124, s[64:65]
	v_cndmask_b32_e64 v126, v124, v116, s[64:65]
	v_add_f32_dpp v104, v140, v140 quad_perm:[1,0,3,2] row_mask:0xf bank_mask:0xf
	v_add_f32_dpp v105, v141, v141 quad_perm:[1,0,3,2] row_mask:0xf bank_mask:0xf
	v_add_f32_dpp v106, v142, v142 quad_perm:[1,0,3,2] row_mask:0xf bank_mask:0xf
	v_add_f32_dpp v107, v143, v143 quad_perm:[1,0,3,2] row_mask:0xf bank_mask:0xf
	v_cndmask_b32_e32 v104, v106, v104, vcc
	v_cndmask_b32_e32 v105, v107, v105, vcc
	v_add_f32_dpp v110, v108, v108 quad_perm:[2,3,0,1] row_mask:0xf bank_mask:0xf
	v_add_f32_dpp v111, v109, v109 quad_perm:[2,3,0,1] row_mask:0xf bank_mask:0xf
	v_cndmask_b32_e64 v108, v111, v110, s[4:5]
	s_waitcnt vmcnt(24)
	v_pk_mul_f32 v[140:141], v[236:237], v[96:97] op_sel_hi:[1,0]
	v_pk_mul_f32 v[142:143], v[244:245], v[96:97] op_sel_hi:[1,0]
	v_pk_fma_f32 v[140:141], v[238:239], v[96:97], v[140:141] op_sel:[0,1,0]
	v_pk_fma_f32 v[142:143], v[246:247], v[96:97], v[142:143] op_sel:[0,1,0]
	v_pk_fma_f32 v[140:141], v[240:241], v[98:99], v[140:141] op_sel_hi:[1,0,1]
	v_pk_fma_f32 v[142:143], v[248:249], v[98:99], v[142:143] op_sel_hi:[1,0,1]
	v_pk_fma_f32 v[140:141], v[242:243], v[98:99], v[140:141] op_sel:[0,1,0]
	v_pk_fma_f32 v[142:143], v[250:251], v[98:99], v[142:143] op_sel:[0,1,0]
	v_add_f32_dpp v124, v126, v125 row_ror:8 row_mask:0xf bank_mask:0xf
	v_add_f32_dpp v100, v252, v252 quad_perm:[1,0,3,2] row_mask:0xf bank_mask:0xf
	v_add_f32_dpp v101, v253, v253 quad_perm:[1,0,3,2] row_mask:0xf bank_mask:0xf
	v_add_f32_dpp v102, v254, v254 quad_perm:[1,0,3,2] row_mask:0xf bank_mask:0xf
	v_add_f32_dpp v103, v255, v255 quad_perm:[1,0,3,2] row_mask:0xf bank_mask:0xf
	v_cndmask_b32_e32 v100, v102, v100, vcc
	v_cndmask_b32_e32 v101, v103, v101, vcc
	v_add_f32_dpp v106, v104, v104 quad_perm:[2,3,0,1] row_mask:0xf bank_mask:0xf
	v_add_f32_dpp v107, v105, v105 quad_perm:[2,3,0,1] row_mask:0xf bank_mask:0xf
	v_cndmask_b32_e64 v104, v107, v106, s[4:5]
	v_cndmask_b32_e64 v109, v104, v108, s[6:7]
	v_cndmask_b32_e64 v110, v108, v104, s[6:7]
	s_waitcnt vmcnt(23)
; DI void attn_sample_item(const Params& p, int item, ldsp lds, int tid_) {
;     ...
;   SC_SCORE(kvA, 0)
;   SC_SCORE(kvB, 1)
	v_pk_mul_f32 v[252:253], v[236:237], v[92:93] op_sel_hi:[1,0]
	v_pk_mul_f32 v[254:255], v[244:245], v[92:93] op_sel_hi:[1,0]
	v_pk_fma_f32 v[252:253], v[238:239], v[92:93], v[252:253] op_sel:[0,1,0]
	v_pk_fma_f32 v[254:255], v[246:247], v[92:93], v[254:255] op_sel:[0,1,0]
	v_pk_fma_f32 v[252:253], v[240:241], v[94:95], v[252:253] op_sel_hi:[1,0,1]
	v_pk_fma_f32 v[254:255], v[248:249], v[94:95], v[254:255] op_sel_hi:[1,0,1]
	v_pk_fma_f32 v[252:253], v[242:243], v[94:95], v[252:253] op_sel:[0,1,0]
	v_pk_fma_f32 v[254:255], v[250:251], v[94:95], v[254:255] op_sel:[0,1,0]
	v_add_f32_dpp v108, v110, v109 row_ror:4 row_mask:0xf bank_mask:0xf
	v_add_f32_dpp v96, v140, v140 quad_perm:[1,0,3,2] row_mask:0xf bank_mask:0xf
	v_add_f32_dpp v97, v141, v141 quad_perm:[1,0,3,2] row_mask:0xf bank_mask:0xf
	v_add_f32_dpp v98, v142, v142 quad_perm:[1,0,3,2] row_mask:0xf bank_mask:0xf
	v_add_f32_dpp v99, v143, v143 quad_perm:[1,0,3,2] row_mask:0xf bank_mask:0xf
	v_cndmask_b32_e32 v96, v98, v96, vcc
	v_cndmask_b32_e32 v97, v99, v97, vcc
	v_add_f32_dpp v102, v100, v100 quad_perm:[2,3,0,1] row_mask:0xf bank_mask:0xf
	v_add_f32_dpp v103, v101, v101 quad_perm:[2,3,0,1] row_mask:0xf bank_mask:0xf
	v_cndmask_b32_e64 v100, v103, v102, s[4:5]
	s_waitcnt vmcnt(22)
	v_pk_mul_f32 v[140:141], v[236:237], v[88:89] op_sel_hi:[1,0]
	v_pk_mul_f32 v[142:143], v[244:245], v[88:89] op_sel_hi:[1,0]
	v_pk_fma_f32 v[140:141], v[238:239], v[88:89], v[140:141] op_sel:[0,1,0]
	v_pk_fma_f32 v[142:143], v[246:247], v[88:89], v[142:143] op_sel:[0,1,0]
	v_pk_fma_f32 v[140:141], v[240:241], v[90:91], v[140:141] op_sel_hi:[1,0,1]
	v_pk_fma_f32 v[142:143], v[248:249], v[90:91], v[142:143] op_sel_hi:[1,0,1]
	v_pk_fma_f32 v[140:141], v[242:243], v[90:91], v[140:141] op_sel:[0,1,0]
	v_pk_fma_f32 v[142:143], v[250:251], v[90:91], v[142:143] op_sel:[0,1,0]
	v_add_f32_dpp v92, v252, v252 quad_perm:[1,0,3,2] row_mask:0xf bank_mask:0xf
	v_add_f32_dpp v93, v253, v253 quad_perm:[1,0,3,2] row_mask:0xf bank_mask:0xf
	v_add_f32_dpp v94, v254, v254 quad_perm:[1,0,3,2] row_mask:0xf bank_mask:0xf
	v_add_f32_dpp v95, v255, v255 quad_perm:[1,0,3,2] row_mask:0xf bank_mask:0xf
	v_cndmask_b32_e32 v92, v94, v92, vcc
	v_cndmask_b32_e32 v93, v95, v93, vcc
	v_add_f32_dpp v98, v96, v96 quad_perm:[2,3,0,1] row_mask:0xf bank_mask:0xf
	v_add_f32_dpp v99, v97, v97 quad_perm:[2,3,0,1] row_mask:0xf bank_mask:0xf
	v_cndmask_b32_e64 v96, v99, v98, s[4:5]
	v_cndmask_b32_e64 v101, v96, v100, s[6:7]
	v_cndmask_b32_e64 v102, v100, v96, s[6:7]
	s_waitcnt vmcnt(21)
	v_pk_mul_f32 v[252:253], v[236:237], v[84:85] op_sel_hi:[1,0]
	v_pk_mul_f32 v[254:255], v[244:245], v[84:85] op_sel_hi:[1,0]
	v_pk_fma_f32 v[252:253], v[238:239], v[84:85], v[252:253] op_sel:[0,1,0]
	v_pk_fma_f32 v[254:255], v[246:247], v[84:85], v[254:255] op_sel:[0,1,0]
	v_pk_fma_f32 v[252:253], v[240:241], v[86:87], v[252:253] op_sel_hi:[1,0,1]
	v_pk_fma_f32 v[254:255], v[248:249], v[86:87], v[254:255] op_sel_hi:[1,0,1]
	v_pk_fma_f32 v[252:253], v[242:243], v[86:87], v[252:253] op_sel:[0,1,0]
	v_pk_fma_f32 v[254:255], v[250:251], v[86:87], v[254:255] op_sel:[0,1,0]
	v_add_f32_dpp v100, v102, v101 row_ror:4 row_mask:0xf bank_mask:0xf
	v_cndmask_b32_e64 v109, v100, v108, s[64:65]
	v_cndmask_b32_e64 v110, v108, v100, s[64:65]
	v_add_f32_dpp v88, v140, v140 quad_perm:[1,0,3,2] row_mask:0xf bank_mask:0xf
	v_add_f32_dpp v89, v141, v141 quad_perm:[1,0,3,2] row_mask:0xf bank_mask:0xf
	v_add_f32_dpp v90, v142, v142 quad_perm:[1,0,3,2] row_mask:0xf bank_mask:0xf
	v_add_f32_dpp v91, v143, v143 quad_perm:[1,0,3,2] row_mask:0xf bank_mask:0xf
	v_cndmask_b32_e32 v88, v90, v88, vcc
	v_cndmask_b32_e32 v89, v91, v89, vcc
	v_add_f32_dpp v94, v92, v92 quad_perm:[2,3,0,1] row_mask:0xf bank_mask:0xf
	v_add_f32_dpp v95, v93, v93 quad_perm:[2,3,0,1] row_mask:0xf bank_mask:0xf
	v_cndmask_b32_e64 v92, v95, v94, s[4:5]
	s_waitcnt vmcnt(20)
	v_pk_mul_f32 v[140:141], v[236:237], v[80:81] op_sel_hi:[1,0]
	v_pk_mul_f32 v[142:143], v[244:245], v[80:81] op_sel_hi:[1,0]
	v_pk_fma_f32 v[140:141], v[238:239], v[80:81], v[140:141] op_sel:[0,1,0]
	v_pk_fma_f32 v[142:143], v[246:247], v[80:81], v[142:143] op_sel:[0,1,0]
	v_pk_fma_f32 v[140:141], v[240:241], v[82:83], v[140:141] op_sel_hi:[1,0,1]
	v_pk_fma_f32 v[142:143], v[248:249], v[82:83], v[142:143] op_sel_hi:[1,0,1]
	v_pk_fma_f32 v[140:141], v[242:243], v[82:83], v[140:141] op_sel:[0,1,0]
	v_pk_fma_f32 v[142:143], v[250:251], v[82:83], v[142:143] op_sel:[0,1,0]
	v_add_f32_dpp v108, v110, v109 row_ror:8 row_mask:0xf bank_mask:0xf
	v_add_f32_dpp v84, v252, v252 quad_perm:[1,0,3,2] row_mask:0xf bank_mask:0xf
	v_add_f32_dpp v85, v253, v253 quad_perm:[1,0,3,2] row_mask:0xf bank_mask:0xf
	v_add_f32_dpp v86, v254, v254 quad_perm:[1,0,3,2] row_mask:0xf bank_mask:0xf
	v_add_f32_dpp v87, v255, v255 quad_perm:[1,0,3,2] row_mask:0xf bank_mask:0xf
	v_cndmask_b32_e32 v84, v86, v84, vcc
	v_cndmask_b32_e32 v85, v87, v85, vcc
	v_add_f32_dpp v90, v88, v88 quad_perm:[2,3,0,1] row_mask:0xf bank_mask:0xf
	v_add_f32_dpp v91, v89, v89 quad_perm:[2,3,0,1] row_mask:0xf bank_mask:0xf
	v_cndmask_b32_e64 v88, v91, v90, s[4:5]
	v_cndmask_b32_e64 v93, v88, v92, s[6:7]
	v_cndmask_b32_e64 v94, v92, v88, s[6:7]
	s_waitcnt vmcnt(19)
	v_pk_mul_f32 v[252:253], v[236:237], v[76:77] op_sel_hi:[1,0]
	v_pk_mul_f32 v[254:255], v[244:245], v[76:77] op_sel_hi:[1,0]
	v_pk_fma_f32 v[252:253], v[238:239], v[76:77], v[252:253] op_sel:[0,1,0]
	v_pk_fma_f32 v[254:255], v[246:247], v[76:77], v[254:255] op_sel:[0,1,0]
	v_pk_fma_f32 v[252:253], v[240:241], v[78:79], v[252:253] op_sel_hi:[1,0,1]
	v_pk_fma_f32 v[254:255], v[248:249], v[78:79], v[254:255] op_sel_hi:[1,0,1]
	v_pk_fma_f32 v[252:253], v[242:243], v[78:79], v[252:253] op_sel:[0,1,0]
	v_pk_fma_f32 v[254:255], v[250:251], v[78:79], v[254:255] op_sel:[0,1,0]
	v_permlane16_swap_b32_e32 v124, v108
	v_add_f32_e32 v124, v124, v108
	v_add_f32_dpp v92, v94, v93 row_ror:4 row_mask:0xf bank_mask:0xf
	v_add_f32_dpp v80, v140, v140 quad_perm:[1,0,3,2] row_mask:0xf bank_mask:0xf
	v_add_f32_dpp v81, v141, v141 quad_perm:[1,0,3,2] row_mask:0xf bank_mask:0xf
	v_add_f32_dpp v82, v142, v142 quad_perm:[1,0,3,2] row_mask:0xf bank_mask:0xf
	v_add_f32_dpp v83, v143, v143 quad_perm:[1,0,3,2] row_mask:0xf bank_mask:0xf
	v_cndmask_b32_e32 v80, v82, v80, vcc
	v_cndmask_b32_e32 v81, v83, v81, vcc
	v_add_f32_dpp v86, v84, v84 quad_perm:[2,3,0,1] row_mask:0xf bank_mask:0xf
	v_add_f32_dpp v87, v85, v85 quad_perm:[2,3,0,1] row_mask:0xf bank_mask:0xf
	v_cndmask_b32_e64 v84, v87, v86, s[4:5]
	s_waitcnt vmcnt(18)
	v_pk_mul_f32 v[140:141], v[236:237], v[72:73] op_sel_hi:[1,0]
	v_pk_mul_f32 v[142:143], v[244:245], v[72:73] op_sel_hi:[1,0]
	v_pk_fma_f32 v[140:141], v[238:239], v[72:73], v[140:141] op_sel:[0,1,0]
	v_pk_fma_f32 v[142:143], v[246:247], v[72:73], v[142:143] op_sel:[0,1,0]
	v_pk_fma_f32 v[140:141], v[240:241], v[74:75], v[140:141] op_sel_hi:[1,0,1]
	v_pk_fma_f32 v[142:143], v[248:249], v[74:75], v[142:143] op_sel_hi:[1,0,1]
	v_pk_fma_f32 v[140:141], v[242:243], v[74:75], v[140:141] op_sel:[0,1,0]
	v_pk_fma_f32 v[142:143], v[250:251], v[74:75], v[142:143] op_sel:[0,1,0]
	v_add_f32_dpp v76, v252, v252 quad_perm:[1,0,3,2] row_mask:0xf bank_mask:0xf
	v_add_f32_dpp v77, v253, v253 quad_perm:[1,0,3,2] row_mask:0xf bank_mask:0xf
	v_add_f32_dpp v78, v254, v254 quad_perm:[1,0,3,2] row_mask:0xf bank_mask:0xf
	v_add_f32_dpp v79, v255, v255 quad_perm:[1,0,3,2] row_mask:0xf bank_mask:0xf
	v_cndmask_b32_e32 v76, v78, v76, vcc
	v_cndmask_b32_e32 v77, v79, v77, vcc
	v_add_f32_dpp v82, v80, v80 quad_perm:[2,3,0,1] row_mask:0xf bank_mask:0xf
	v_add_f32_dpp v83, v81, v81 quad_perm:[2,3,0,1] row_mask:0xf bank_mask:0xf
	v_cndmask_b32_e64 v80, v83, v82, s[4:5]
	v_cndmask_b32_e64 v85, v80, v84, s[6:7]
	v_cndmask_b32_e64 v86, v84, v80, s[6:7]
	s_waitcnt vmcnt(17)
	v_pk_mul_f32 v[252:253], v[236:237], v[68:69] op_sel_hi:[1,0]
	v_pk_mul_f32 v[254:255], v[244:245], v[68:69] op_sel_hi:[1,0]
	v_pk_fma_f32 v[252:253], v[238:239], v[68:69], v[252:253] op_sel:[0,1,0]
	v_pk_fma_f32 v[254:255], v[246:247], v[68:69], v[254:255] op_sel:[0,1,0]
	v_pk_fma_f32 v[252:253], v[240:241], v[70:71], v[252:253] op_sel_hi:[1,0,1]
	v_pk_fma_f32 v[254:255], v[248:249], v[70:71], v[254:255] op_sel_hi:[1,0,1]
	v_pk_fma_f32 v[252:253], v[242:243], v[70:71], v[252:253] op_sel:[0,1,0]
	v_pk_fma_f32 v[254:255], v[250:251], v[70:71], v[254:255] op_sel:[0,1,0]
	v_add_f32_dpp v84, v86, v85 row_ror:4 row_mask:0xf bank_mask:0xf
	v_cndmask_b32_e64 v93, v84, v92, s[64:65]
	v_cndmask_b32_e64 v94, v92, v84, s[64:65]
	v_add_f32_dpp v72, v140, v140 quad_perm:[1,0,3,2] row_mask:0xf bank_mask:0xf
	v_add_f32_dpp v73, v141, v141 quad_perm:[1,0,3,2] row_mask:0xf bank_mask:0xf
	v_add_f32_dpp v74, v142, v142 quad_perm:[1,0,3,2] row_mask:0xf bank_mask:0xf
	v_add_f32_dpp v75, v143, v143 quad_perm:[1,0,3,2] row_mask:0xf bank_mask:0xf
	v_cndmask_b32_e32 v72, v74, v72, vcc
	v_cndmask_b32_e32 v73, v75, v73, vcc
	v_add_f32_dpp v78, v76, v76 quad_perm:[2,3,0,1] row_mask:0xf bank_mask:0xf
	v_add_f32_dpp v79, v77, v77 quad_perm:[2,3,0,1] row_mask:0xf bank_mask:0xf
	v_cndmask_b32_e64 v76, v79, v78, s[4:5]
	s_waitcnt vmcnt(16)
	v_pk_mul_f32 v[140:141], v[236:237], v[64:65] op_sel_hi:[1,0]
	v_pk_mul_f32 v[142:143], v[244:245], v[64:65] op_sel_hi:[1,0]
	v_pk_fma_f32 v[140:141], v[238:239], v[64:65], v[140:141] op_sel:[0,1,0]
	v_pk_fma_f32 v[142:143], v[246:247], v[64:65], v[142:143] op_sel:[0,1,0]
	v_pk_fma_f32 v[140:141], v[240:241], v[66:67], v[140:141] op_sel_hi:[1,0,1]
	v_pk_fma_f32 v[142:143], v[248:249], v[66:67], v[142:143] op_sel_hi:[1,0,1]
	v_pk_fma_f32 v[140:141], v[242:243], v[66:67], v[140:141] op_sel:[0,1,0]
	v_pk_fma_f32 v[142:143], v[250:251], v[66:67], v[142:143] op_sel:[0,1,0]
	v_add_f32_dpp v92, v94, v93 row_ror:8 row_mask:0xf bank_mask:0xf
	v_add_f32_dpp v68, v252, v252 quad_perm:[1,0,3,2] row_mask:0xf bank_mask:0xf
	v_add_f32_dpp v69, v253, v253 quad_perm:[1,0,3,2] row_mask:0xf bank_mask:0xf
	v_add_f32_dpp v70, v254, v254 quad_perm:[1,0,3,2] row_mask:0xf bank_mask:0xf
	v_add_f32_dpp v71, v255, v255 quad_perm:[1,0,3,2] row_mask:0xf bank_mask:0xf
	v_cndmask_b32_e32 v68, v70, v68, vcc
	v_cndmask_b32_e32 v69, v71, v69, vcc
	v_add_f32_dpp v74, v72, v72 quad_perm:[2,3,0,1] row_mask:0xf bank_mask:0xf
	v_add_f32_dpp v75, v73, v73 quad_perm:[2,3,0,1] row_mask:0xf bank_mask:0xf
	v_cndmask_b32_e64 v72, v75, v74, s[4:5]
	v_cndmask_b32_e64 v77, v72, v76, s[6:7]
	v_cndmask_b32_e64 v78, v76, v72, s[6:7]
	s_waitcnt vmcnt(15)
	v_pk_mul_f32 v[252:253], v[236:237], v[60:61] op_sel_hi:[1,0]
	v_pk_mul_f32 v[254:255], v[244:245], v[60:61] op_sel_hi:[1,0]
	v_pk_fma_f32 v[252:253], v[238:239], v[60:61], v[252:253] op_sel:[0,1,0]
	v_pk_fma_f32 v[254:255], v[246:247], v[60:61], v[254:255] op_sel:[0,1,0]
	v_pk_fma_f32 v[252:253], v[240:241], v[62:63], v[252:253] op_sel_hi:[1,0,1]
	v_pk_fma_f32 v[254:255], v[248:249], v[62:63], v[254:255] op_sel_hi:[1,0,1]
	v_pk_fma_f32 v[252:253], v[242:243], v[62:63], v[252:253] op_sel:[0,1,0]
	v_pk_fma_f32 v[254:255], v[250:251], v[62:63], v[254:255] op_sel:[0,1,0]
	v_add_f32_dpp v76, v78, v77 row_ror:4 row_mask:0xf bank_mask:0xf
	v_add_f32_dpp v64, v140, v140 quad_perm:[1,0,3,2] row_mask:0xf bank_mask:0xf
	v_add_f32_dpp v65, v141, v141 quad_perm:[1,0,3,2] row_mask:0xf bank_mask:0xf
	v_add_f32_dpp v66, v142, v142 quad_perm:[1,0,3,2] row_mask:0xf bank_mask:0xf
	v_add_f32_dpp v67, v143, v143 quad_perm:[1,0,3,2] row_mask:0xf bank_mask:0xf
	v_cndmask_b32_e32 v64, v66, v64, vcc
	v_cndmask_b32_e32 v65, v67, v65, vcc
	v_add_f32_dpp v70, v68, v68 quad_perm:[2,3,0,1] row_mask:0xf bank_mask:0xf
	v_add_f32_dpp v71, v69, v69 quad_perm:[2,3,0,1] row_mask:0xf bank_mask:0xf
	v_cndmask_b32_e64 v68, v71, v70, s[4:5]
	s_waitcnt vmcnt(14)
	v_pk_mul_f32 v[140:141], v[236:237], v[56:57] op_sel_hi:[1,0]
	v_pk_mul_f32 v[142:143], v[244:245], v[56:57] op_sel_hi:[1,0]
	v_pk_fma_f32 v[140:141], v[238:239], v[56:57], v[140:141] op_sel:[0,1,0]
	v_pk_fma_f32 v[142:143], v[246:247], v[56:57], v[142:143] op_sel:[0,1,0]
	v_pk_fma_f32 v[140:141], v[240:241], v[58:59], v[140:141] op_sel_hi:[1,0,1]
	v_pk_fma_f32 v[142:143], v[248:249], v[58:59], v[142:143] op_sel_hi:[1,0,1]
	v_pk_fma_f32 v[140:141], v[242:243], v[58:59], v[140:141] op_sel:[0,1,0]
	v_pk_fma_f32 v[142:143], v[250:251], v[58:59], v[142:143] op_sel:[0,1,0]
	v_add_f32_dpp v60, v252, v252 quad_perm:[1,0,3,2] row_mask:0xf bank_mask:0xf
	v_add_f32_dpp v61, v253, v253 quad_perm:[1,0,3,2] row_mask:0xf bank_mask:0xf
	v_add_f32_dpp v62, v254, v254 quad_perm:[1,0,3,2] row_mask:0xf bank_mask:0xf
	v_add_f32_dpp v63, v255, v255 quad_perm:[1,0,3,2] row_mask:0xf bank_mask:0xf
	v_cndmask_b32_e32 v60, v62, v60, vcc
	v_cndmask_b32_e32 v61, v63, v61, vcc
	v_add_f32_dpp v66, v64, v64 quad_perm:[2,3,0,1] row_mask:0xf bank_mask:0xf
	v_add_f32_dpp v67, v65, v65 quad_perm:[2,3,0,1] row_mask:0xf bank_mask:0xf
	v_cndmask_b32_e64 v64, v67, v66, s[4:5]
	v_cndmask_b32_e64 v69, v64, v68, s[6:7]
	v_cndmask_b32_e64 v70, v68, v64, s[6:7]
	s_waitcnt vmcnt(13)
	v_pk_mul_f32 v[252:253], v[236:237], v[52:53] op_sel_hi:[1,0]
	v_pk_mul_f32 v[254:255], v[244:245], v[52:53] op_sel_hi:[1,0]
	v_pk_fma_f32 v[252:253], v[238:239], v[52:53], v[252:253] op_sel:[0,1,0]
	v_pk_fma_f32 v[254:255], v[246:247], v[52:53], v[254:255] op_sel:[0,1,0]
	v_pk_fma_f32 v[252:253], v[240:241], v[54:55], v[252:253] op_sel_hi:[1,0,1]
	v_pk_fma_f32 v[254:255], v[248:249], v[54:55], v[254:255] op_sel_hi:[1,0,1]
	v_pk_fma_f32 v[252:253], v[242:243], v[54:55], v[252:253] op_sel:[0,1,0]
	v_pk_fma_f32 v[254:255], v[250:251], v[54:55], v[254:255] op_sel:[0,1,0]
	v_add_f32_dpp v68, v70, v69 row_ror:4 row_mask:0xf bank_mask:0xf
	v_cndmask_b32_e64 v77, v68, v76, s[64:65]
	v_cndmask_b32_e64 v78, v76, v68, s[64:65]
	v_add_f32_dpp v56, v140, v140 quad_perm:[1,0,3,2] row_mask:0xf bank_mask:0xf
	v_add_f32_dpp v57, v141, v141 quad_perm:[1,0,3,2] row_mask:0xf bank_mask:0xf
	v_add_f32_dpp v58, v142, v142 quad_perm:[1,0,3,2] row_mask:0xf bank_mask:0xf
	v_add_f32_dpp v59, v143, v143 quad_perm:[1,0,3,2] row_mask:0xf bank_mask:0xf
	v_cndmask_b32_e32 v56, v58, v56, vcc
	v_cndmask_b32_e32 v57, v59, v57, vcc
	v_add_f32_dpp v62, v60, v60 quad_perm:[2,3,0,1] row_mask:0xf bank_mask:0xf
	v_add_f32_dpp v63, v61, v61 quad_perm:[2,3,0,1] row_mask:0xf bank_mask:0xf
	v_cndmask_b32_e64 v60, v63, v62, s[4:5]
	s_waitcnt vmcnt(12)
	v_pk_mul_f32 v[140:141], v[236:237], v[48:49] op_sel_hi:[1,0]
	v_pk_mul_f32 v[142:143], v[244:245], v[48:49] op_sel_hi:[1,0]
	v_pk_fma_f32 v[140:141], v[238:239], v[48:49], v[140:141] op_sel:[0,1,0]
	v_pk_fma_f32 v[142:143], v[246:247], v[48:49], v[142:143] op_sel:[0,1,0]
	v_pk_fma_f32 v[140:141], v[240:241], v[50:51], v[140:141] op_sel_hi:[1,0,1]
	v_pk_fma_f32 v[142:143], v[248:249], v[50:51], v[142:143] op_sel_hi:[1,0,1]
	v_pk_fma_f32 v[140:141], v[242:243], v[50:51], v[140:141] op_sel:[0,1,0]
	v_pk_fma_f32 v[142:143], v[250:251], v[50:51], v[142:143] op_sel:[0,1,0]
	v_add_f32_dpp v76, v78, v77 row_ror:8 row_mask:0xf bank_mask:0xf
	v_add_f32_dpp v52, v252, v252 quad_perm:[1,0,3,2] row_mask:0xf bank_mask:0xf
	v_add_f32_dpp v53, v253, v253 quad_perm:[1,0,3,2] row_mask:0xf bank_mask:0xf
	v_add_f32_dpp v54, v254, v254 quad_perm:[1,0,3,2] row_mask:0xf bank_mask:0xf
	v_add_f32_dpp v55, v255, v255 quad_perm:[1,0,3,2] row_mask:0xf bank_mask:0xf
	v_cndmask_b32_e32 v52, v54, v52, vcc
	v_cndmask_b32_e32 v53, v55, v53, vcc
	v_add_f32_dpp v58, v56, v56 quad_perm:[2,3,0,1] row_mask:0xf bank_mask:0xf
	v_add_f32_dpp v59, v57, v57 quad_perm:[2,3,0,1] row_mask:0xf bank_mask:0xf
	v_cndmask_b32_e64 v56, v59, v58, s[4:5]
	v_cndmask_b32_e64 v61, v56, v60, s[6:7]
	v_cndmask_b32_e64 v62, v60, v56, s[6:7]
	s_waitcnt vmcnt(11)
; DI void attn_sample_item(const Params& p, int item, ldsp lds, int tid_) {
;     ...
;   SC_SCORE(kvA, 0)
;   SC_SCORE(kvB, 1)
;     ...
;   f32x4 vvA[16], vvB[16];
; #pragma unroll
;   for (int j = 0; j < 16; ++j) vvA[j] = __builtin_nontemporal_load((const f32x4*)(cv + (size_t)(wid * 32 + j) * 1024 + lane * 4));
	v_pk_mul_f32 v[252:253], v[236:237], v[44:45] op_sel_hi:[1,0]
	v_pk_mul_f32 v[254:255], v[244:245], v[44:45] op_sel_hi:[1,0]
	v_pk_fma_f32 v[252:253], v[238:239], v[44:45], v[252:253] op_sel:[0,1,0]
	v_pk_fma_f32 v[254:255], v[246:247], v[44:45], v[254:255] op_sel:[0,1,0]
	v_pk_fma_f32 v[252:253], v[240:241], v[46:47], v[252:253] op_sel_hi:[1,0,1]
	v_pk_fma_f32 v[254:255], v[248:249], v[46:47], v[254:255] op_sel_hi:[1,0,1]
	v_pk_fma_f32 v[252:253], v[242:243], v[46:47], v[252:253] op_sel:[0,1,0]
	v_pk_fma_f32 v[254:255], v[250:251], v[46:47], v[254:255] op_sel:[0,1,0]
	v_permlane16_swap_b32_e32 v92, v76
	v_add_f32_e32 v92, v92, v76
	v_add_f32_dpp v60, v62, v61 row_ror:4 row_mask:0xf bank_mask:0xf
	v_add_f32_dpp v48, v140, v140 quad_perm:[1,0,3,2] row_mask:0xf bank_mask:0xf
	v_add_f32_dpp v49, v141, v141 quad_perm:[1,0,3,2] row_mask:0xf bank_mask:0xf
	v_add_f32_dpp v50, v142, v142 quad_perm:[1,0,3,2] row_mask:0xf bank_mask:0xf
	v_add_f32_dpp v51, v143, v143 quad_perm:[1,0,3,2] row_mask:0xf bank_mask:0xf
	v_cndmask_b32_e32 v48, v50, v48, vcc
	v_cndmask_b32_e32 v49, v51, v49, vcc
	v_add_f32_dpp v54, v52, v52 quad_perm:[2,3,0,1] row_mask:0xf bank_mask:0xf
	v_add_f32_dpp v55, v53, v53 quad_perm:[2,3,0,1] row_mask:0xf bank_mask:0xf
	v_cndmask_b32_e64 v52, v55, v54, s[4:5]
	s_waitcnt vmcnt(10)
	v_pk_mul_f32 v[140:141], v[236:237], v[40:41] op_sel_hi:[1,0]
	v_pk_mul_f32 v[142:143], v[244:245], v[40:41] op_sel_hi:[1,0]
	v_pk_fma_f32 v[140:141], v[238:239], v[40:41], v[140:141] op_sel:[0,1,0]
	v_pk_fma_f32 v[142:143], v[246:247], v[40:41], v[142:143] op_sel:[0,1,0]
	v_pk_fma_f32 v[140:141], v[240:241], v[42:43], v[140:141] op_sel_hi:[1,0,1]
	v_pk_fma_f32 v[142:143], v[248:249], v[42:43], v[142:143] op_sel_hi:[1,0,1]
	v_pk_fma_f32 v[140:141], v[242:243], v[42:43], v[140:141] op_sel:[0,1,0]
	v_pk_fma_f32 v[142:143], v[250:251], v[42:43], v[142:143] op_sel:[0,1,0]
	v_permlane32_swap_b32_e32 v124, v92
	v_add_f32_e32 v124, v124, v92
	ds_write_b32 v235, v124
	v_add_u32_e32 v100, v162, v144
	global_load_dwordx4 v[100:103], v100, s[66:67] nt
	v_add_u32_e32 v92, v166, v144
	global_load_dwordx4 v[92:95], v92, s[66:67] nt
	v_add_u32_e32 v112, v168, v144
	global_load_dwordx4 v[112:115], v112, s[66:67] nt
	v_add_u32_e32 v108, v172, v144
	global_load_dwordx4 v[108:111], v108, s[66:67] nt
	v_add_u32_e32 v120, v176, v144
	global_load_dwordx4 v[120:123], v120, s[66:67] nt
	v_add_u32_e32 v116, v180, v144
	global_load_dwordx4 v[116:119], v116, s[66:67] nt
	v_add_u32_e32 v124, v182, v144
	global_load_dwordx4 v[124:127], v124, s[66:67] nt
	v_add_u32_e32 v104, v186, v144
	global_load_dwordx4 v[104:107], v104, s[66:67] nt
	v_add_u32_e32 v68, v190, v144
	global_load_dwordx4 v[68:71], v68, s[66:67] nt
	v_add_u32_e32 v64, v194, v144
	global_load_dwordx4 v[64:67], v64, s[66:67] nt
	v_add_u32_e32 v80, v198, v144
	global_load_dwordx4 v[80:83], v80, s[66:67] nt
	v_add_u32_e32 v76, v200, v144
	global_load_dwordx4 v[76:79], v76, s[66:67] nt
	v_add_u32_e32 v88, v202, v144
	global_load_dwordx4 v[88:91], v88, s[66:67] nt
	v_add_u32_e32 v84, v204, v144
	global_load_dwordx4 v[84:87], v84, s[66:67] nt
	v_add_u32_e32 v96, v206, v144
	global_load_dwordx4 v[96:99], v96, s[66:67] nt
	v_add_u32_e32 v72, v208, v144
	global_load_dwordx4 v[72:75], v72, s[66:67] nt
	v_add_f32_dpp v44, v252, v252 quad_perm:[1,0,3,2] row_mask:0xf bank_mask:0xf
	v_add_f32_dpp v45, v253, v253 quad_perm:[1,0,3,2] row_mask:0xf bank_mask:0xf
	v_add_f32_dpp v46, v254, v254 quad_perm:[1,0,3,2] row_mask:0xf bank_mask:0xf
	v_add_f32_dpp v47, v255, v255 quad_perm:[1,0,3,2] row_mask:0xf bank_mask:0xf
	v_cndmask_b32_e32 v44, v46, v44, vcc
	v_cndmask_b32_e32 v45, v47, v45, vcc
	v_add_f32_dpp v50, v48, v48 quad_perm:[2,3,0,1] row_mask:0xf bank_mask:0xf
	v_add_f32_dpp v51, v49, v49 quad_perm:[2,3,0,1] row_mask:0xf bank_mask:0xf
	v_cndmask_b32_e64 v48, v51, v50, s[4:5]
	v_cndmask_b32_e64 v53, v48, v52, s[6:7]
	v_cndmask_b32_e64 v54, v52, v48, s[6:7]
	s_waitcnt vmcnt(25)
	v_pk_mul_f32 v[252:253], v[236:237], v[36:37] op_sel_hi:[1,0]
	v_pk_mul_f32 v[254:255], v[244:245], v[36:37] op_sel_hi:[1,0]
	v_pk_fma_f32 v[252:253], v[238:239], v[36:37], v[252:253] op_sel:[0,1,0]
	v_pk_fma_f32 v[254:255], v[246:247], v[36:37], v[254:255] op_sel:[0,1,0]
	v_pk_fma_f32 v[252:253], v[240:241], v[38:39], v[252:253] op_sel_hi:[1,0,1]
	v_pk_fma_f32 v[254:255], v[248:249], v[38:39], v[254:255] op_sel_hi:[1,0,1]
	v_pk_fma_f32 v[252:253], v[242:243], v[38:39], v[252:253] op_sel:[0,1,0]
	v_pk_fma_f32 v[254:255], v[250:251], v[38:39], v[254:255] op_sel:[0,1,0]
	v_add_f32_dpp v52, v54, v53 row_ror:4 row_mask:0xf bank_mask:0xf
	v_cndmask_b32_e64 v61, v52, v60, s[64:65]
	v_cndmask_b32_e64 v62, v60, v52, s[64:65]
	v_add_f32_dpp v40, v140, v140 quad_perm:[1,0,3,2] row_mask:0xf bank_mask:0xf
	v_add_f32_dpp v41, v141, v141 quad_perm:[1,0,3,2] row_mask:0xf bank_mask:0xf
	v_add_f32_dpp v42, v142, v142 quad_perm:[1,0,3,2] row_mask:0xf bank_mask:0xf
	v_add_f32_dpp v43, v143, v143 quad_perm:[1,0,3,2] row_mask:0xf bank_mask:0xf
	v_cndmask_b32_e32 v40, v42, v40, vcc
	v_cndmask_b32_e32 v41, v43, v41, vcc
	v_add_f32_dpp v46, v44, v44 quad_perm:[2,3,0,1] row_mask:0xf bank_mask:0xf
	v_add_f32_dpp v47, v45, v45 quad_perm:[2,3,0,1] row_mask:0xf bank_mask:0xf
	v_cndmask_b32_e64 v44, v47, v46, s[4:5]
	s_waitcnt vmcnt(24)
	v_pk_mul_f32 v[140:141], v[236:237], v[32:33] op_sel_hi:[1,0]
	v_pk_mul_f32 v[142:143], v[244:245], v[32:33] op_sel_hi:[1,0]
	v_pk_fma_f32 v[140:141], v[238:239], v[32:33], v[140:141] op_sel:[0,1,0]
	v_pk_fma_f32 v[142:143], v[246:247], v[32:33], v[142:143] op_sel:[0,1,0]
	v_pk_fma_f32 v[140:141], v[240:241], v[34:35], v[140:141] op_sel_hi:[1,0,1]
	v_pk_fma_f32 v[142:143], v[248:249], v[34:35], v[142:143] op_sel_hi:[1,0,1]
	v_pk_fma_f32 v[140:141], v[242:243], v[34:35], v[140:141] op_sel:[0,1,0]
	v_pk_fma_f32 v[142:143], v[250:251], v[34:35], v[142:143] op_sel:[0,1,0]
	v_add_f32_dpp v60, v62, v61 row_ror:8 row_mask:0xf bank_mask:0xf
	v_add_f32_dpp v36, v252, v252 quad_perm:[1,0,3,2] row_mask:0xf bank_mask:0xf
	v_add_f32_dpp v37, v253, v253 quad_perm:[1,0,3,2] row_mask:0xf bank_mask:0xf
	v_add_f32_dpp v38, v254, v254 quad_perm:[1,0,3,2] row_mask:0xf bank_mask:0xf
	v_add_f32_dpp v39, v255, v255 quad_perm:[1,0,3,2] row_mask:0xf bank_mask:0xf
	v_cndmask_b32_e32 v36, v38, v36, vcc
	v_cndmask_b32_e32 v37, v39, v37, vcc
	v_add_f32_dpp v42, v40, v40 quad_perm:[2,3,0,1] row_mask:0xf bank_mask:0xf
	v_add_f32_dpp v43, v41, v41 quad_perm:[2,3,0,1] row_mask:0xf bank_mask:0xf
	v_cndmask_b32_e64 v40, v43, v42, s[4:5]
	v_cndmask_b32_e64 v45, v40, v44, s[6:7]
	v_cndmask_b32_e64 v46, v44, v40, s[6:7]
	s_waitcnt vmcnt(23)
	v_pk_mul_f32 v[252:253], v[236:237], v[28:29] op_sel_hi:[1,0]
	v_pk_mul_f32 v[254:255], v[244:245], v[28:29] op_sel_hi:[1,0]
	v_pk_fma_f32 v[252:253], v[238:239], v[28:29], v[252:253] op_sel:[0,1,0]
	v_pk_fma_f32 v[254:255], v[246:247], v[28:29], v[254:255] op_sel:[0,1,0]
	v_pk_fma_f32 v[252:253], v[240:241], v[30:31], v[252:253] op_sel_hi:[1,0,1]
	v_pk_fma_f32 v[254:255], v[248:249], v[30:31], v[254:255] op_sel_hi:[1,0,1]
	v_pk_fma_f32 v[252:253], v[242:243], v[30:31], v[252:253] op_sel:[0,1,0]
	v_pk_fma_f32 v[254:255], v[250:251], v[30:31], v[254:255] op_sel:[0,1,0]
	v_add_f32_dpp v44, v46, v45 row_ror:4 row_mask:0xf bank_mask:0xf
	v_add_f32_dpp v32, v140, v140 quad_perm:[1,0,3,2] row_mask:0xf bank_mask:0xf
	v_add_f32_dpp v33, v141, v141 quad_perm:[1,0,3,2] row_mask:0xf bank_mask:0xf
	v_add_f32_dpp v34, v142, v142 quad_perm:[1,0,3,2] row_mask:0xf bank_mask:0xf
	v_add_f32_dpp v35, v143, v143 quad_perm:[1,0,3,2] row_mask:0xf bank_mask:0xf
	v_cndmask_b32_e32 v32, v34, v32, vcc
	v_cndmask_b32_e32 v33, v35, v33, vcc
	v_add_f32_dpp v38, v36, v36 quad_perm:[2,3,0,1] row_mask:0xf bank_mask:0xf
	v_add_f32_dpp v39, v37, v37 quad_perm:[2,3,0,1] row_mask:0xf bank_mask:0xf
	v_cndmask_b32_e64 v36, v39, v38, s[4:5]
	s_waitcnt vmcnt(22)
	v_pk_mul_f32 v[140:141], v[236:237], v[24:25] op_sel_hi:[1,0]
	v_pk_mul_f32 v[142:143], v[244:245], v[24:25] op_sel_hi:[1,0]
	v_pk_fma_f32 v[140:141], v[238:239], v[24:25], v[140:141] op_sel:[0,1,0]
	v_pk_fma_f32 v[142:143], v[246:247], v[24:25], v[142:143] op_sel:[0,1,0]
	v_pk_fma_f32 v[140:141], v[240:241], v[26:27], v[140:141] op_sel_hi:[1,0,1]
	v_pk_fma_f32 v[142:143], v[248:249], v[26:27], v[142:143] op_sel_hi:[1,0,1]
	v_pk_fma_f32 v[140:141], v[242:243], v[26:27], v[140:141] op_sel:[0,1,0]
	v_pk_fma_f32 v[142:143], v[250:251], v[26:27], v[142:143] op_sel:[0,1,0]
	v_add_f32_dpp v28, v252, v252 quad_perm:[1,0,3,2] row_mask:0xf bank_mask:0xf
	v_add_f32_dpp v29, v253, v253 quad_perm:[1,0,3,2] row_mask:0xf bank_mask:0xf
	v_add_f32_dpp v30, v254, v254 quad_perm:[1,0,3,2] row_mask:0xf bank_mask:0xf
	v_add_f32_dpp v31, v255, v255 quad_perm:[1,0,3,2] row_mask:0xf bank_mask:0xf
	v_cndmask_b32_e32 v28, v30, v28, vcc
	v_cndmask_b32_e32 v29, v31, v29, vcc
	v_add_f32_dpp v34, v32, v32 quad_perm:[2,3,0,1] row_mask:0xf bank_mask:0xf
	v_add_f32_dpp v35, v33, v33 quad_perm:[2,3,0,1] row_mask:0xf bank_mask:0xf
	v_cndmask_b32_e64 v32, v35, v34, s[4:5]
	v_cndmask_b32_e64 v37, v32, v36, s[6:7]
	v_cndmask_b32_e64 v38, v36, v32, s[6:7]
	s_waitcnt vmcnt(21)
	v_pk_mul_f32 v[252:253], v[236:237], v[20:21] op_sel_hi:[1,0]
	v_pk_mul_f32 v[254:255], v[244:245], v[20:21] op_sel_hi:[1,0]
	v_pk_fma_f32 v[252:253], v[238:239], v[20:21], v[252:253] op_sel:[0,1,0]
	v_pk_fma_f32 v[254:255], v[246:247], v[20:21], v[254:255] op_sel:[0,1,0]
	v_pk_fma_f32 v[252:253], v[240:241], v[22:23], v[252:253] op_sel_hi:[1,0,1]
	v_pk_fma_f32 v[254:255], v[248:249], v[22:23], v[254:255] op_sel_hi:[1,0,1]
	v_pk_fma_f32 v[252:253], v[242:243], v[22:23], v[252:253] op_sel:[0,1,0]
	v_pk_fma_f32 v[254:255], v[250:251], v[22:23], v[254:255] op_sel:[0,1,0]
	v_add_f32_dpp v36, v38, v37 row_ror:4 row_mask:0xf bank_mask:0xf
	v_cndmask_b32_e64 v45, v36, v44, s[64:65]
	v_cndmask_b32_e64 v46, v44, v36, s[64:65]
	v_add_f32_dpp v24, v140, v140 quad_perm:[1,0,3,2] row_mask:0xf bank_mask:0xf
	v_add_f32_dpp v25, v141, v141 quad_perm:[1,0,3,2] row_mask:0xf bank_mask:0xf
	v_add_f32_dpp v26, v142, v142 quad_perm:[1,0,3,2] row_mask:0xf bank_mask:0xf
	v_add_f32_dpp v27, v143, v143 quad_perm:[1,0,3,2] row_mask:0xf bank_mask:0xf
	v_cndmask_b32_e32 v24, v26, v24, vcc
	v_cndmask_b32_e32 v25, v27, v25, vcc
	v_add_f32_dpp v30, v28, v28 quad_perm:[2,3,0,1] row_mask:0xf bank_mask:0xf
	v_add_f32_dpp v31, v29, v29 quad_perm:[2,3,0,1] row_mask:0xf bank_mask:0xf
	v_cndmask_b32_e64 v28, v31, v30, s[4:5]
	s_waitcnt vmcnt(20)
	v_pk_mul_f32 v[140:141], v[236:237], v[16:17] op_sel_hi:[1,0]
	v_pk_mul_f32 v[142:143], v[244:245], v[16:17] op_sel_hi:[1,0]
	v_pk_fma_f32 v[140:141], v[238:239], v[16:17], v[140:141] op_sel:[0,1,0]
	v_pk_fma_f32 v[142:143], v[246:247], v[16:17], v[142:143] op_sel:[0,1,0]
	v_pk_fma_f32 v[140:141], v[240:241], v[18:19], v[140:141] op_sel_hi:[1,0,1]
	v_pk_fma_f32 v[142:143], v[248:249], v[18:19], v[142:143] op_sel_hi:[1,0,1]
	v_pk_fma_f32 v[140:141], v[242:243], v[18:19], v[140:141] op_sel:[0,1,0]
	v_pk_fma_f32 v[142:143], v[250:251], v[18:19], v[142:143] op_sel:[0,1,0]
	v_add_f32_dpp v44, v46, v45 row_ror:8 row_mask:0xf bank_mask:0xf
	v_add_f32_dpp v20, v252, v252 quad_perm:[1,0,3,2] row_mask:0xf bank_mask:0xf
	v_add_f32_dpp v21, v253, v253 quad_perm:[1,0,3,2] row_mask:0xf bank_mask:0xf
	v_add_f32_dpp v22, v254, v254 quad_perm:[1,0,3,2] row_mask:0xf bank_mask:0xf
	v_add_f32_dpp v23, v255, v255 quad_perm:[1,0,3,2] row_mask:0xf bank_mask:0xf
	v_cndmask_b32_e32 v20, v22, v20, vcc
	v_cndmask_b32_e32 v21, v23, v21, vcc
	v_add_f32_dpp v26, v24, v24 quad_perm:[2,3,0,1] row_mask:0xf bank_mask:0xf
	v_add_f32_dpp v27, v25, v25 quad_perm:[2,3,0,1] row_mask:0xf bank_mask:0xf
	v_cndmask_b32_e64 v24, v27, v26, s[4:5]
	v_cndmask_b32_e64 v29, v24, v28, s[6:7]
	v_cndmask_b32_e64 v30, v28, v24, s[6:7]
	s_waitcnt vmcnt(19)
	v_pk_mul_f32 v[252:253], v[236:237], v[12:13] op_sel_hi:[1,0]
	v_pk_mul_f32 v[254:255], v[244:245], v[12:13] op_sel_hi:[1,0]
	v_pk_fma_f32 v[252:253], v[238:239], v[12:13], v[252:253] op_sel:[0,1,0]
	v_pk_fma_f32 v[254:255], v[246:247], v[12:13], v[254:255] op_sel:[0,1,0]
	v_pk_fma_f32 v[252:253], v[240:241], v[14:15], v[252:253] op_sel_hi:[1,0,1]
	v_pk_fma_f32 v[254:255], v[248:249], v[14:15], v[254:255] op_sel_hi:[1,0,1]
	v_pk_fma_f32 v[252:253], v[242:243], v[14:15], v[252:253] op_sel:[0,1,0]
	v_pk_fma_f32 v[254:255], v[250:251], v[14:15], v[254:255] op_sel:[0,1,0]
	v_permlane16_swap_b32_e32 v60, v44
	v_add_f32_e32 v60, v60, v44
	v_add_f32_dpp v28, v30, v29 row_ror:4 row_mask:0xf bank_mask:0xf
	v_add_f32_dpp v16, v140, v140 quad_perm:[1,0,3,2] row_mask:0xf bank_mask:0xf
	v_add_f32_dpp v17, v141, v141 quad_perm:[1,0,3,2] row_mask:0xf bank_mask:0xf
	v_add_f32_dpp v18, v142, v142 quad_perm:[1,0,3,2] row_mask:0xf bank_mask:0xf
	v_add_f32_dpp v19, v143, v143 quad_perm:[1,0,3,2] row_mask:0xf bank_mask:0xf
	v_cndmask_b32_e32 v16, v18, v16, vcc
	v_cndmask_b32_e32 v17, v19, v17, vcc
	v_add_f32_dpp v22, v20, v20 quad_perm:[2,3,0,1] row_mask:0xf bank_mask:0xf
	v_add_f32_dpp v23, v21, v21 quad_perm:[2,3,0,1] row_mask:0xf bank_mask:0xf
	v_cndmask_b32_e64 v20, v23, v22, s[4:5]
	s_waitcnt vmcnt(18)
	v_pk_mul_f32 v[140:141], v[236:237], v[8:9] op_sel_hi:[1,0]
	v_pk_mul_f32 v[142:143], v[244:245], v[8:9] op_sel_hi:[1,0]
	v_pk_fma_f32 v[140:141], v[238:239], v[8:9], v[140:141] op_sel:[0,1,0]
	v_pk_fma_f32 v[142:143], v[246:247], v[8:9], v[142:143] op_sel:[0,1,0]
	v_pk_fma_f32 v[140:141], v[240:241], v[10:11], v[140:141] op_sel_hi:[1,0,1]
	v_pk_fma_f32 v[142:143], v[248:249], v[10:11], v[142:143] op_sel_hi:[1,0,1]
	v_pk_fma_f32 v[140:141], v[242:243], v[10:11], v[140:141] op_sel:[0,1,0]
	v_pk_fma_f32 v[142:143], v[250:251], v[10:11], v[142:143] op_sel:[0,1,0]
	v_add_f32_dpp v12, v252, v252 quad_perm:[1,0,3,2] row_mask:0xf bank_mask:0xf
	v_add_f32_dpp v13, v253, v253 quad_perm:[1,0,3,2] row_mask:0xf bank_mask:0xf
	v_add_f32_dpp v14, v254, v254 quad_perm:[1,0,3,2] row_mask:0xf bank_mask:0xf
	v_add_f32_dpp v15, v255, v255 quad_perm:[1,0,3,2] row_mask:0xf bank_mask:0xf
	v_cndmask_b32_e32 v12, v14, v12, vcc
	v_cndmask_b32_e32 v13, v15, v13, vcc
	v_add_f32_dpp v18, v16, v16 quad_perm:[2,3,0,1] row_mask:0xf bank_mask:0xf
	v_add_f32_dpp v19, v17, v17 quad_perm:[2,3,0,1] row_mask:0xf bank_mask:0xf
	v_cndmask_b32_e64 v16, v19, v18, s[4:5]
	v_cndmask_b32_e64 v21, v16, v20, s[6:7]
	v_cndmask_b32_e64 v22, v20, v16, s[6:7]
	s_waitcnt vmcnt(17)
	v_pk_mul_f32 v[252:253], v[236:237], v[4:5] op_sel_hi:[1,0]
	v_pk_mul_f32 v[254:255], v[244:245], v[4:5] op_sel_hi:[1,0]
	v_pk_fma_f32 v[252:253], v[238:239], v[4:5], v[252:253] op_sel:[0,1,0]
	v_pk_fma_f32 v[254:255], v[246:247], v[4:5], v[254:255] op_sel:[0,1,0]
	v_pk_fma_f32 v[252:253], v[240:241], v[6:7], v[252:253] op_sel_hi:[1,0,1]
	v_pk_fma_f32 v[254:255], v[248:249], v[6:7], v[254:255] op_sel_hi:[1,0,1]
	v_pk_fma_f32 v[252:253], v[242:243], v[6:7], v[252:253] op_sel:[0,1,0]
	v_pk_fma_f32 v[254:255], v[250:251], v[6:7], v[254:255] op_sel:[0,1,0]
	v_add_f32_dpp v20, v22, v21 row_ror:4 row_mask:0xf bank_mask:0xf
	v_cndmask_b32_e64 v29, v20, v28, s[64:65]
	v_cndmask_b32_e64 v30, v28, v20, s[64:65]
	v_add_f32_dpp v8, v140, v140 quad_perm:[1,0,3,2] row_mask:0xf bank_mask:0xf
	v_add_f32_dpp v9, v141, v141 quad_perm:[1,0,3,2] row_mask:0xf bank_mask:0xf
	v_add_f32_dpp v10, v142, v142 quad_perm:[1,0,3,2] row_mask:0xf bank_mask:0xf
	v_add_f32_dpp v11, v143, v143 quad_perm:[1,0,3,2] row_mask:0xf bank_mask:0xf
	v_cndmask_b32_e32 v8, v10, v8, vcc
	v_cndmask_b32_e32 v9, v11, v9, vcc
	v_add_f32_dpp v14, v12, v12 quad_perm:[2,3,0,1] row_mask:0xf bank_mask:0xf
	v_add_f32_dpp v15, v13, v13 quad_perm:[2,3,0,1] row_mask:0xf bank_mask:0xf
	v_cndmask_b32_e64 v12, v15, v14, s[4:5]
	s_waitcnt vmcnt(16)
; DI void attn_sample_item(const Params& p, int item, ldsp lds, int tid_) {
;     ...
;   SC_SCORE(kvA, 0)
;   SC_SCORE(kvB, 1)
;     ...
;   f32x4 vvA[16], vvB[16];
; #pragma unroll
;   for (int j = 0; j < 16; ++j) vvA[j] = __builtin_nontemporal_load((const f32x4*)(cv + (size_t)(wid * 32 + j) * 1024 + lane * 4));
;     ...
;   for (int j = 0; j < 16; ++j) vvB[j] = __builtin_nontemporal_load((const f32x4*)(cv + (size_t)(wid * 32 + 16 + j) * 1024 + lane * 4));
	v_pk_mul_f32 v[140:141], v[236:237], v[0:1] op_sel_hi:[1,0]
	v_pk_mul_f32 v[142:143], v[244:245], v[0:1] op_sel_hi:[1,0]
	v_pk_fma_f32 v[140:141], v[238:239], v[0:1], v[140:141] op_sel:[0,1,0]
	v_pk_fma_f32 v[142:143], v[246:247], v[0:1], v[142:143] op_sel:[0,1,0]
	v_pk_fma_f32 v[140:141], v[240:241], v[2:3], v[140:141] op_sel_hi:[1,0,1]
	v_pk_fma_f32 v[142:143], v[248:249], v[2:3], v[142:143] op_sel_hi:[1,0,1]
	v_pk_fma_f32 v[140:141], v[242:243], v[2:3], v[140:141] op_sel:[0,1,0]
	v_pk_fma_f32 v[142:143], v[250:251], v[2:3], v[142:143] op_sel:[0,1,0]
	v_add_f32_dpp v28, v30, v29 row_ror:8 row_mask:0xf bank_mask:0xf
	v_add_f32_dpp v4, v252, v252 quad_perm:[1,0,3,2] row_mask:0xf bank_mask:0xf
	v_add_f32_dpp v5, v253, v253 quad_perm:[1,0,3,2] row_mask:0xf bank_mask:0xf
	v_add_f32_dpp v6, v254, v254 quad_perm:[1,0,3,2] row_mask:0xf bank_mask:0xf
	v_add_f32_dpp v7, v255, v255 quad_perm:[1,0,3,2] row_mask:0xf bank_mask:0xf
	v_cndmask_b32_e32 v4, v6, v4, vcc
	v_cndmask_b32_e32 v5, v7, v5, vcc
	v_add_f32_dpp v10, v8, v8 quad_perm:[2,3,0,1] row_mask:0xf bank_mask:0xf
	v_add_f32_dpp v11, v9, v9 quad_perm:[2,3,0,1] row_mask:0xf bank_mask:0xf
	v_cndmask_b32_e64 v8, v11, v10, s[4:5]
	v_cndmask_b32_e64 v13, v8, v12, s[6:7]
	v_cndmask_b32_e64 v14, v12, v8, s[6:7]
	s_nop 1
	v_add_f32_dpp v12, v14, v13 row_ror:4 row_mask:0xf bank_mask:0xf
	v_add_f32_dpp v0, v140, v140 quad_perm:[1,0,3,2] row_mask:0xf bank_mask:0xf
	v_add_f32_dpp v1, v141, v141 quad_perm:[1,0,3,2] row_mask:0xf bank_mask:0xf
	v_add_f32_dpp v2, v142, v142 quad_perm:[1,0,3,2] row_mask:0xf bank_mask:0xf
	v_add_f32_dpp v3, v143, v143 quad_perm:[1,0,3,2] row_mask:0xf bank_mask:0xf
	v_cndmask_b32_e32 v0, v2, v0, vcc
	v_cndmask_b32_e32 v1, v3, v1, vcc
	v_add_f32_dpp v6, v4, v4 quad_perm:[2,3,0,1] row_mask:0xf bank_mask:0xf
	v_add_f32_dpp v7, v5, v5 quad_perm:[2,3,0,1] row_mask:0xf bank_mask:0xf
	v_cndmask_b32_e64 v4, v7, v6, s[4:5]
	v_add_f32_dpp v2, v0, v0 quad_perm:[2,3,0,1] row_mask:0xf bank_mask:0xf
	v_add_f32_dpp v3, v1, v1 quad_perm:[2,3,0,1] row_mask:0xf bank_mask:0xf
	v_cndmask_b32_e64 v0, v3, v2, s[4:5]
	v_cndmask_b32_e64 v5, v0, v4, s[6:7]
	v_cndmask_b32_e64 v6, v4, v0, s[6:7]
	s_nop 1
	v_add_f32_dpp v4, v6, v5 row_ror:4 row_mask:0xf bank_mask:0xf
	v_cndmask_b32_e64 v13, v4, v12, s[64:65]
	v_cndmask_b32_e64 v14, v12, v4, s[64:65]
	s_nop 1
	v_add_f32_dpp v12, v14, v13 row_ror:8 row_mask:0xf bank_mask:0xf
	s_nop 1
	v_permlane16_swap_b32_e32 v28, v12
	v_add_f32_e32 v28, v28, v12
	s_nop 1
	v_permlane32_swap_b32_e32 v60, v28
	v_add_f32_e32 v60, v60, v28
	ds_write_b32 v235, v60 offset:64
	v_add_u32_e32 v40, v146, v144
	global_load_dwordx4 v[40:43], v40, s[66:67] nt
	v_add_u32_e32 v36, v148, v144
	global_load_dwordx4 v[36:39], v36, s[66:67] nt
	v_add_u32_e32 v48, v150, v144
	global_load_dwordx4 v[48:51], v48, s[66:67] nt
	v_add_u32_e32 v44, v152, v144
	global_load_dwordx4 v[44:47], v44, s[66:67] nt
	v_add_u32_e32 v56, v154, v144
	global_load_dwordx4 v[56:59], v56, s[66:67] nt
	v_add_u32_e32 v52, v156, v144
	global_load_dwordx4 v[52:55], v52, s[66:67] nt
	v_add_u32_e32 v60, v158, v144
	global_load_dwordx4 v[60:63], v60, s[66:67] nt
	v_add_u32_e32 v32, v160, v144
	global_load_dwordx4 v[32:35], v32, s[66:67] nt
	v_add_u32_e32 v12, v164, v144
	global_load_dwordx4 v[12:15], v12, s[66:67] nt
	v_add_u32_e32 v4, v170, v144
	global_load_dwordx4 v[4:7], v4, s[66:67] nt
	v_add_u32_e32 v20, v174, v144
	global_load_dwordx4 v[20:23], v20, s[66:67] nt
	v_add_u32_e32 v8, v178, v144
	global_load_dwordx4 v[8:11], v8, s[66:67] nt
	v_add_u32_e32 v24, v184, v144
	global_load_dwordx4 v[24:27], v24, s[66:67] nt
	v_add_u32_e32 v16, v188, v144
	global_load_dwordx4 v[16:19], v16, s[66:67] nt
	v_add_u32_e32 v28, v192, v144
	global_load_dwordx4 v[28:31], v28, s[66:67] nt
	v_add_u32_e32 v0, v196, v144
	global_load_dwordx4 v[0:3], v0, s[66:67] nt
	v_lshlrev_b32_e32 v240, 2, v223
	s_waitcnt lgkmcnt(0)
	s_barrier
	v_cmp_gt_i32_e32 vcc, 4, v210
	s_and_saveexec_b64 s[4:5], vcc
	s_cbranch_execz .LBB0_1603

; DI float wave_sum(float v) { for (int o = 32; o >= 1; o >>= 1) v += __shfl_xor(v, o); return v; }
; DI void attn_sample_item(const Params& p, int item, ldsp lds, int tid_) {
;     ...
;   if (wid < 4) {
;     float v[4]; float mx = -1e30f;
; #pragma unroll
;     for (int j = 0; j < 4; ++j) { v[j] = SC[wid * 256 + j * 64 + lane]; mx = fmaxf(mx, v[j]); }
;     for (int o = 32; o >= 1; o >>= 1) mx = fmaxf(mx, __shfl_xor(mx, o));
;     float s = 0.f;
; #pragma unroll
;     for (int j = 0; j < 4; ++j) { v[j] = __expf(v[j] - mx); s += v[j]; }
;     s = wave_sum(s); const float inv = 1.f / s;
; #pragma unroll
;     for (int j = 0; j < 4; ++j) SC[wid * 256 + j * 64 + lane] = v[j] * inv;
;   }
	v_lshlrev_b32_e32 v241, 10, v210
	v_add3_u32 v244, 16, v241, v240
	ds_read2st64_b32 v[240:241], v244 offset1:1
	ds_read2st64_b32 v[242:243], v244 offset0:2 offset1:3
	s_waitcnt lgkmcnt(1)
	v_max3_f32 v245, v240, s39, v241
	s_waitcnt lgkmcnt(0)
	v_max3_f32 v245, v245, v242, v243
	ds_bpermute_b32 v246, v133, v245
	s_waitcnt lgkmcnt(0)
	v_max_f32_e32 v246, v246, v246
	v_max_f32_e32 v245, v245, v246
	ds_bpermute_b32 v246, v132, v245
	s_waitcnt lgkmcnt(0)
	v_max_f32_e32 v246, v246, v246
	v_max_f32_e32 v245, v245, v246
	ds_bpermute_b32 v246, v131, v245
	s_waitcnt lgkmcnt(0)
	v_max_f32_e32 v246, v246, v246
	v_max_f32_e32 v245, v245, v246
	ds_bpermute_b32 v246, v130, v245
	s_waitcnt lgkmcnt(0)
	v_max_f32_e32 v246, v246, v246
	v_max_f32_e32 v245, v245, v246
	ds_bpermute_b32 v246, v129, v245
	s_waitcnt lgkmcnt(0)
	v_max_f32_e32 v246, v246, v246
	v_max_f32_e32 v245, v245, v246
	ds_bpermute_b32 v246, v128, v245
	s_waitcnt lgkmcnt(0)
	v_max_f32_e32 v246, v246, v246
	v_max_f32_e32 v245, v245, v246
	v_sub_f32_e32 v240, v240, v245
	v_sub_f32_e32 v241, v241, v245
	v_mul_f32_e32 v240, 0x3fb8aa3b, v240
	v_sub_f32_e32 v242, v242, v245
	v_mul_f32_e32 v241, 0x3fb8aa3b, v241
	v_exp_f32_e32 v240, v240
	v_sub_f32_e32 v243, v243, v245
	v_mul_f32_e32 v242, 0x3fb8aa3b, v242
	v_exp_f32_e32 v241, v241
	v_mul_f32_e32 v243, 0x3fb8aa3b, v243
	v_exp_f32_e32 v242, v242
	v_exp_f32_e32 v243, v243
	v_add_f32_e32 v245, 0, v240
	v_add_f32_e32 v245, v241, v245
	v_add_f32_e32 v245, v242, v245
	v_add_f32_e32 v245, v243, v245
	ds_bpermute_b32 v246, v133, v245
	s_waitcnt lgkmcnt(0)
	v_add_f32_e32 v245, v245, v246
	ds_bpermute_b32 v246, v132, v245
	s_waitcnt lgkmcnt(0)
	v_add_f32_e32 v245, v245, v246
	ds_bpermute_b32 v246, v131, v245
	s_waitcnt lgkmcnt(0)
	v_add_f32_e32 v245, v245, v246
	ds_bpermute_b32 v246, v130, v245
	s_waitcnt lgkmcnt(0)
	v_add_f32_e32 v245, v245, v246
	ds_bpermute_b32 v246, v129, v245
	s_waitcnt lgkmcnt(0)
	v_add_f32_e32 v245, v245, v246
	ds_bpermute_b32 v246, v128, v245
	s_waitcnt lgkmcnt(0)
	v_add_f32_e32 v245, v245, v246
	v_div_scale_f32 v246, s[6:7], v245, v245, 1.0
	v_rcp_f32_e32 v247, v246
	v_div_scale_f32 v248, vcc, 1.0, v245, 1.0
	v_fma_f32 v249, -v246, v247, 1.0
	v_fmac_f32_e32 v247, v249, v247
	v_mul_f32_e32 v249, v248, v247
	v_fma_f32 v250, -v246, v249, v248
	v_fmac_f32_e32 v249, v250, v247
	v_fma_f32 v246, -v246, v249, v248
	v_div_fmas_f32 v246, v246, v247, v249
	v_div_fixup_f32 v245, v246, v245, 1.0
	v_mul_f32_e32 v240, v240, v245
	v_mul_f32_e32 v241, v241, v245
	v_mul_f32_e32 v242, v242, v245
	v_mul_f32_e32 v243, v243, v245
	ds_write2st64_b32 v244, v240, v241 offset1:1
	ds_write2st64_b32 v244, v242, v243 offset0:2 offset1:3
	s_branch .LBB0_1603

; #define LAS __attribute__((address_space(3)))
; DI void lbar() { asm volatile("s_waitcnt lgkmcnt(0)" ::: "memory"); __builtin_amdgcn_s_barrier(); asm volatile("" ::: "memory"); }
; DI void attn_sample_item(const Params& p, int item, ldsp lds, int tid_) {
;     ...
; #pragma unroll
;   for (int j = 0; j < 16; ++j) vvB[j] = __builtin_nontemporal_load((const f32x4*)(cv + (size_t)(wid * 32 + 16 + j) * 1024 + lane * 4));
;   lbar();
;   {
;     f32x4 acc[4];
; #pragma unroll
;     for (int t = 0; t < 4; ++t) acc[t] = (f32x4){0.f, 0.f, 0.f, 0.f};
; #pragma unroll
;     for (int t = 0; t < 4; ++t)
; #pragma unroll
;       for (int j4 = 0; j4 < 4; ++j4) { const f32x4 pp = *(const LAS f32x4*)(SC + t * 256 + wid * 32 + j4 * 4);
; #pragma unroll
;         for (int e = 0; e < 4; ++e) acc[t] += pp[e] * vvA[j4 * 4 + e]; }
; #pragma unroll
;     for (int t = 0; t < 4; ++t)
; #pragma unroll
;       for (int j4 = 0; j4 < 4; ++j4) { const f32x4 pp = *(const LAS f32x4*)(SC + t * 256 + wid * 32 + 16 + j4 * 4);
; #pragma unroll
;         for (int e = 0; e < 4; ++e) acc[t] += pp[e] * vvB[j4 * 4 + e]; }
; #pragma unroll
;     for (int t = 0; t < 4; ++t) *(LAS f32x4*)(PART + (wid * 4 + t) * 256 + lane * 4) = acc[t];
.LBB0_1675:
	s_or_b64 exec, exec, s[4:5]
	s_waitcnt lgkmcnt(0)
	s_barrier
	ds_read_b128 v[128:131], v136
	ds_read_b128 v[132:135], v136 offset:16
	ds_read_b128 v[138:141], v136 offset:32
	ds_read_b128 v[146:149], v136 offset:48
	s_add_i32 s4, s26, 0x4000
	s_waitcnt vmcnt(31) lgkmcnt(3)
	v_pk_fma_f32 v[142:143], v[100:101], v[128:129], 0 op_sel_hi:[1,0,0]
	v_pk_fma_f32 v[150:151], v[102:103], v[128:129], 0 op_sel_hi:[1,0,0]
	s_lshl_b32 s24, s24, 1
	s_waitcnt vmcnt(30)
	v_pk_fma_f32 v[150:151], v[94:95], v[128:129], v[150:151] op_sel:[0,1,0]
	v_pk_fma_f32 v[128:129], v[92:93], v[128:129], v[142:143] op_sel:[0,1,0]
	s_waitcnt vmcnt(29)
	v_pk_fma_f32 v[142:143], v[114:115], v[130:131], v[150:151] op_sel_hi:[1,0,1]
	v_pk_fma_f32 v[128:129], v[112:113], v[130:131], v[128:129] op_sel_hi:[1,0,1]
	v_mov_b32_e32 v130, v131
	s_waitcnt vmcnt(28)
	v_pk_fma_f32 v[128:129], v[108:109], v[130:131], v[128:129] op_sel_hi:[1,0,1]
	v_pk_fma_f32 v[130:131], v[110:111], v[130:131], v[142:143] op_sel_hi:[1,0,1]
	s_waitcnt vmcnt(27) lgkmcnt(2)
	v_pk_fma_f32 v[128:129], v[120:121], v[132:133], v[128:129] op_sel_hi:[1,0,1]
	v_pk_fma_f32 v[130:131], v[122:123], v[132:133], v[130:131] op_sel_hi:[1,0,1]
	s_waitcnt vmcnt(26)
	v_pk_fma_f32 v[128:129], v[116:117], v[132:133], v[128:129] op_sel:[0,1,0]
	v_pk_fma_f32 v[130:131], v[118:119], v[132:133], v[130:131] op_sel:[0,1,0]
	s_waitcnt vmcnt(25)
	v_pk_fma_f32 v[128:129], v[124:125], v[134:135], v[128:129] op_sel_hi:[1,0,1]
	v_pk_fma_f32 v[130:131], v[126:127], v[134:135], v[130:131] op_sel_hi:[1,0,1]
	v_mov_b32_e32 v132, v135
	s_waitcnt vmcnt(24)
	v_pk_fma_f32 v[128:129], v[104:105], v[132:133], v[128:129] op_sel_hi:[1,0,1]
	v_pk_fma_f32 v[130:131], v[106:107], v[132:133], v[130:131] op_sel_hi:[1,0,1]
	s_waitcnt vmcnt(23) lgkmcnt(1)
	v_pk_fma_f32 v[128:129], v[68:69], v[138:139], v[128:129] op_sel_hi:[1,0,1]
	v_pk_fma_f32 v[130:131], v[70:71], v[138:139], v[130:131] op_sel_hi:[1,0,1]
	s_waitcnt vmcnt(22)
	v_pk_fma_f32 v[128:129], v[64:65], v[138:139], v[128:129] op_sel:[0,1,0]
	v_pk_fma_f32 v[130:131], v[66:67], v[138:139], v[130:131] op_sel:[0,1,0]
	s_waitcnt vmcnt(21)
	v_pk_fma_f32 v[128:129], v[80:81], v[140:141], v[128:129] op_sel_hi:[1,0,1]
	v_pk_fma_f32 v[130:131], v[82:83], v[140:141], v[130:131] op_sel_hi:[1,0,1]
	v_mov_b32_e32 v132, v141
	s_waitcnt vmcnt(20)
	v_pk_fma_f32 v[128:129], v[76:77], v[132:133], v[128:129] op_sel_hi:[1,0,1]
	v_pk_fma_f32 v[130:131], v[78:79], v[132:133], v[130:131] op_sel_hi:[1,0,1]
	s_waitcnt vmcnt(19) lgkmcnt(0)
	v_pk_fma_f32 v[128:129], v[88:89], v[146:147], v[128:129] op_sel_hi:[1,0,1]
	v_pk_fma_f32 v[130:131], v[90:91], v[146:147], v[130:131] op_sel_hi:[1,0,1]
	s_waitcnt vmcnt(18)
	v_pk_fma_f32 v[128:129], v[84:85], v[146:147], v[128:129] op_sel:[0,1,0]
	v_pk_fma_f32 v[130:131], v[86:87], v[146:147], v[130:131] op_sel:[0,1,0]
	s_waitcnt vmcnt(17)
	v_pk_fma_f32 v[134:135], v[96:97], v[148:149], v[128:129] op_sel_hi:[1,0,1]
	v_pk_fma_f32 v[132:133], v[98:99], v[148:149], v[130:131] op_sel_hi:[1,0,1]
	ds_read_b128 v[128:131], v136 offset:1024
	v_mov_b32_e32 v138, v149
	s_waitcnt vmcnt(16)
	v_pk_fma_f32 v[142:143], v[72:73], v[138:139], v[134:135] op_sel_hi:[1,0,1]
	v_pk_fma_f32 v[150:151], v[74:75], v[138:139], v[132:133] op_sel_hi:[1,0,1]
	ds_read_b128 v[132:135], v136 offset:1040
	s_waitcnt lgkmcnt(1)
	v_pk_fma_f32 v[138:139], v[100:101], v[128:129], 0 op_sel_hi:[1,0,0]
	v_pk_fma_f32 v[140:141], v[102:103], v[128:129], 0 op_sel_hi:[1,0,0]
	ds_read_b128 v[146:149], v136 offset:2064
	v_pk_fma_f32 v[140:141], v[94:95], v[128:129], v[140:141] op_sel:[0,1,0]
	v_pk_fma_f32 v[128:129], v[92:93], v[128:129], v[138:139] op_sel:[0,1,0]
	v_pk_fma_f32 v[138:139], v[114:115], v[130:131], v[140:141] op_sel_hi:[1,0,1]
	v_pk_fma_f32 v[128:129], v[112:113], v[130:131], v[128:129] op_sel_hi:[1,0,1]
	v_mov_b32_e32 v130, v131
	v_pk_fma_f32 v[128:129], v[108:109], v[130:131], v[128:129] op_sel_hi:[1,0,1]
	v_pk_fma_f32 v[130:131], v[110:111], v[130:131], v[138:139] op_sel_hi:[1,0,1]
	s_waitcnt lgkmcnt(1)
	v_pk_fma_f32 v[128:129], v[120:121], v[132:133], v[128:129] op_sel_hi:[1,0,1]
	v_pk_fma_f32 v[130:131], v[122:123], v[132:133], v[130:131] op_sel_hi:[1,0,1]
	v_pk_fma_f32 v[128:129], v[116:117], v[132:133], v[128:129] op_sel:[0,1,0]
	v_pk_fma_f32 v[130:131], v[118:119], v[132:133], v[130:131] op_sel:[0,1,0]
	v_pk_fma_f32 v[138:139], v[124:125], v[134:135], v[128:129] op_sel_hi:[1,0,1]
	v_pk_fma_f32 v[132:133], v[126:127], v[134:135], v[130:131] op_sel_hi:[1,0,1]
	ds_read_b128 v[128:131], v136 offset:1056
	v_mov_b32_e32 v134, v135
	v_pk_fma_f32 v[138:139], v[104:105], v[134:135], v[138:139] op_sel_hi:[1,0,1]
	v_pk_fma_f32 v[140:141], v[106:107], v[134:135], v[132:133] op_sel_hi:[1,0,1]
	ds_read_b128 v[132:135], v136 offset:1072
	s_waitcnt lgkmcnt(1)
	v_pk_fma_f32 v[140:141], v[70:71], v[128:129], v[140:141] op_sel_hi:[1,0,1]
	v_pk_fma_f32 v[138:139], v[68:69], v[128:129], v[138:139] op_sel_hi:[1,0,1]
	s_add_i32 s38, s38, s94
	v_pk_fma_f32 v[138:139], v[64:65], v[128:129], v[138:139] op_sel:[0,1,0]
	v_pk_fma_f32 v[128:129], v[66:67], v[128:129], v[140:141] op_sel:[0,1,0]
	v_pk_fma_f32 v[138:139], v[80:81], v[130:131], v[138:139] op_sel_hi:[1,0,1]
	v_pk_fma_f32 v[128:129], v[82:83], v[130:131], v[128:129] op_sel_hi:[1,0,1]
	v_mov_b32_e32 v130, v131
	v_pk_fma_f32 v[138:139], v[76:77], v[130:131], v[138:139] op_sel_hi:[1,0,1]
	v_pk_fma_f32 v[128:129], v[78:79], v[130:131], v[128:129] op_sel_hi:[1,0,1]
	s_waitcnt lgkmcnt(0)
; #define LAS __attribute__((address_space(3)))
; DI void attn_sample_item(const Params& p, int item, ldsp lds, int tid_) {
;     ...
; #pragma unroll
;     for (int t = 0; t < 4; ++t)
; #pragma unroll
;       for (int j4 = 0; j4 < 4; ++j4) { const f32x4 pp = *(const LAS f32x4*)(SC + t * 256 + wid * 32 + j4 * 4);
; #pragma unroll
;         for (int e = 0; e < 4; ++e) acc[t] += pp[e] * vvA[j4 * 4 + e]; }
; #pragma unroll
;     for (int t = 0; t < 4; ++t)
; #pragma unroll
;       for (int j4 = 0; j4 < 4; ++j4) { const f32x4 pp = *(const LAS f32x4*)(SC + t * 256 + wid * 32 + 16 + j4 * 4);
; #pragma unroll
;         for (int e = 0; e < 4; ++e) acc[t] += pp[e] * vvB[j4 * 4 + e]; }
	v_pk_fma_f32 v[130:131], v[88:89], v[132:133], v[138:139] op_sel_hi:[1,0,1]
	ds_read_b128 v[138:141], v136 offset:2048
	v_pk_fma_f32 v[128:129], v[90:91], v[132:133], v[128:129] op_sel_hi:[1,0,1]
	v_pk_fma_f32 v[130:131], v[84:85], v[132:133], v[130:131] op_sel:[0,1,0]
	v_pk_fma_f32 v[128:129], v[86:87], v[132:133], v[128:129] op_sel:[0,1,0]
	s_add_i32 s0, s0, s1
	v_pk_fma_f32 v[132:133], v[98:99], v[134:135], v[128:129] op_sel_hi:[1,0,1]
	v_pk_fma_f32 v[128:129], v[96:97], v[134:135], v[130:131] op_sel_hi:[1,0,1]
	v_mov_b32_e32 v130, v135
	v_pk_fma_f32 v[128:129], v[72:73], v[130:131], v[128:129] op_sel_hi:[1,0,1]
	v_pk_fma_f32 v[132:133], v[74:75], v[130:131], v[132:133] op_sel_hi:[1,0,1]
	s_waitcnt lgkmcnt(0)
	v_pk_fma_f32 v[130:131], v[100:101], v[138:139], 0 op_sel_hi:[1,0,0]
	v_pk_fma_f32 v[134:135], v[102:103], v[138:139], 0 op_sel_hi:[1,0,0]
	v_pk_fma_f32 v[130:131], v[92:93], v[138:139], v[130:131] op_sel:[0,1,0]
	v_pk_fma_f32 v[134:135], v[94:95], v[138:139], v[134:135] op_sel:[0,1,0]
	v_pk_fma_f32 v[130:131], v[112:113], v[140:141], v[130:131] op_sel_hi:[1,0,1]
	v_pk_fma_f32 v[134:135], v[114:115], v[140:141], v[134:135] op_sel_hi:[1,0,1]
	v_mov_b32_e32 v138, v141
	v_pk_fma_f32 v[130:131], v[108:109], v[138:139], v[130:131] op_sel_hi:[1,0,1]
	v_pk_fma_f32 v[134:135], v[110:111], v[138:139], v[134:135] op_sel_hi:[1,0,1]
	ds_read_b128 v[138:141], v136 offset:2080
	v_pk_fma_f32 v[134:135], v[122:123], v[146:147], v[134:135] op_sel_hi:[1,0,1]
	v_pk_fma_f32 v[130:131], v[120:121], v[146:147], v[130:131] op_sel_hi:[1,0,1]
	v_pk_fma_f32 v[134:135], v[118:119], v[146:147], v[134:135] op_sel:[0,1,0]
	v_pk_fma_f32 v[130:131], v[116:117], v[146:147], v[130:131] op_sel:[0,1,0]
	v_pk_fma_f32 v[134:135], v[126:127], v[148:149], v[134:135] op_sel_hi:[1,0,1]
	v_pk_fma_f32 v[130:131], v[124:125], v[148:149], v[130:131] op_sel_hi:[1,0,1]
	v_mov_b32_e32 v146, v149
	v_pk_fma_f32 v[130:131], v[104:105], v[146:147], v[130:131] op_sel_hi:[1,0,1]
	v_pk_fma_f32 v[134:135], v[106:107], v[146:147], v[134:135] op_sel_hi:[1,0,1]
	ds_read_b128 v[146:149], v136 offset:2096
	s_waitcnt lgkmcnt(1)
	v_pk_fma_f32 v[134:135], v[70:71], v[138:139], v[134:135] op_sel_hi:[1,0,1]
	v_pk_fma_f32 v[130:131], v[68:69], v[138:139], v[130:131] op_sel_hi:[1,0,1]
	v_pk_fma_f32 v[134:135], v[66:67], v[138:139], v[134:135] op_sel:[0,1,0]
	v_pk_fma_f32 v[130:131], v[64:65], v[138:139], v[130:131] op_sel:[0,1,0]
	v_pk_fma_f32 v[134:135], v[82:83], v[140:141], v[134:135] op_sel_hi:[1,0,1]
	v_pk_fma_f32 v[130:131], v[80:81], v[140:141], v[130:131] op_sel_hi:[1,0,1]
	v_mov_b32_e32 v138, v141
	v_pk_fma_f32 v[130:131], v[76:77], v[138:139], v[130:131] op_sel_hi:[1,0,1]
	v_pk_fma_f32 v[134:135], v[78:79], v[138:139], v[134:135] op_sel_hi:[1,0,1]
	ds_read_b128 v[138:141], v136 offset:3072
	s_waitcnt lgkmcnt(1)
	v_pk_fma_f32 v[134:135], v[90:91], v[146:147], v[134:135] op_sel_hi:[1,0,1]
	v_pk_fma_f32 v[130:131], v[88:89], v[146:147], v[130:131] op_sel_hi:[1,0,1]
	v_pk_fma_f32 v[134:135], v[86:87], v[146:147], v[134:135] op_sel:[0,1,0]
	v_pk_fma_f32 v[130:131], v[84:85], v[146:147], v[130:131] op_sel:[0,1,0]
	v_pk_fma_f32 v[134:135], v[98:99], v[148:149], v[134:135] op_sel_hi:[1,0,1]
	v_pk_fma_f32 v[130:131], v[96:97], v[148:149], v[130:131] op_sel_hi:[1,0,1]
	v_mov_b32_e32 v146, v149
	v_pk_fma_f32 v[130:131], v[72:73], v[146:147], v[130:131] op_sel_hi:[1,0,1]
	v_pk_fma_f32 v[134:135], v[74:75], v[146:147], v[134:135] op_sel_hi:[1,0,1]
	ds_read_b128 v[146:149], v136 offset:3088
	s_waitcnt lgkmcnt(1)
	v_pk_fma_f32 v[100:101], v[100:101], v[138:139], 0 op_sel_hi:[1,0,0]
	v_pk_fma_f32 v[102:103], v[102:103], v[138:139], 0 op_sel_hi:[1,0,0]
	v_pk_fma_f32 v[92:93], v[92:93], v[138:139], v[100:101] op_sel:[0,1,0]
	v_pk_fma_f32 v[94:95], v[94:95], v[138:139], v[102:103] op_sel:[0,1,0]
	v_pk_fma_f32 v[92:93], v[112:113], v[140:141], v[92:93] op_sel_hi:[1,0,1]
	v_pk_fma_f32 v[94:95], v[114:115], v[140:141], v[94:95] op_sel_hi:[1,0,1]
	v_mov_b32_e32 v100, v141
	v_pk_fma_f32 v[92:93], v[108:109], v[100:101], v[92:93] op_sel_hi:[1,0,1]
	v_pk_fma_f32 v[94:95], v[110:111], v[100:101], v[94:95] op_sel_hi:[1,0,1]
	s_waitcnt lgkmcnt(0)
	v_pk_fma_f32 v[92:93], v[120:121], v[146:147], v[92:93] op_sel_hi:[1,0,1]
	v_pk_fma_f32 v[94:95], v[122:123], v[146:147], v[94:95] op_sel_hi:[1,0,1]
	v_pk_fma_f32 v[92:93], v[116:117], v[146:147], v[92:93] op_sel:[0,1,0]
	v_pk_fma_f32 v[94:95], v[118:119], v[146:147], v[94:95] op_sel:[0,1,0]
	v_pk_fma_f32 v[102:103], v[124:125], v[148:149], v[92:93] op_sel_hi:[1,0,1]
	v_pk_fma_f32 v[100:101], v[126:127], v[148:149], v[94:95] op_sel_hi:[1,0,1]
	ds_read_b128 v[92:95], v136 offset:3104
	v_mov_b32_e32 v108, v149
	v_pk_fma_f32 v[104:105], v[104:105], v[108:109], v[102:103] op_sel_hi:[1,0,1]
	v_pk_fma_f32 v[106:107], v[106:107], v[108:109], v[100:101] op_sel_hi:[1,0,1]
	ds_read_b128 v[100:103], v136 offset:3120
	s_waitcnt lgkmcnt(1)
	v_pk_fma_f32 v[70:71], v[70:71], v[92:93], v[106:107] op_sel_hi:[1,0,1]
	v_pk_fma_f32 v[68:69], v[68:69], v[92:93], v[104:105] op_sel_hi:[1,0,1]
	v_pk_fma_f32 v[66:67], v[66:67], v[92:93], v[70:71] op_sel:[0,1,0]
	v_pk_fma_f32 v[64:65], v[64:65], v[92:93], v[68:69] op_sel:[0,1,0]
	v_pk_fma_f32 v[66:67], v[82:83], v[94:95], v[66:67] op_sel_hi:[1,0,1]
	v_pk_fma_f32 v[64:65], v[80:81], v[94:95], v[64:65] op_sel_hi:[1,0,1]
	v_mov_b32_e32 v68, v95
	v_pk_fma_f32 v[64:65], v[76:77], v[68:69], v[64:65] op_sel_hi:[1,0,1]
	v_pk_fma_f32 v[66:67], v[78:79], v[68:69], v[66:67] op_sel_hi:[1,0,1]
	ds_read_b128 v[68:71], v136 offset:64
	s_waitcnt lgkmcnt(1)
; #define LAS __attribute__((address_space(3)))
; DI void attn_sample_item(const Params& p, int item, ldsp lds, int tid_) {
;     ...
; #pragma unroll
;     for (int t = 0; t < 4; ++t)
; #pragma unroll
;       for (int j4 = 0; j4 < 4; ++j4) { const f32x4 pp = *(const LAS f32x4*)(SC + t * 256 + wid * 32 + j4 * 4);
; #pragma unroll
;         for (int e = 0; e < 4; ++e) acc[t] += pp[e] * vvA[j4 * 4 + e]; }
; #pragma unroll
;     for (int t = 0; t < 4; ++t)
; #pragma unroll
;       for (int j4 = 0; j4 < 4; ++j4) { const f32x4 pp = *(const LAS f32x4*)(SC + t * 256 + wid * 32 + 16 + j4 * 4);
; #pragma unroll
;         for (int e = 0; e < 4; ++e) acc[t] += pp[e] * vvB[j4 * 4 + e]; }
	v_pk_fma_f32 v[66:67], v[90:91], v[100:101], v[66:67] op_sel_hi:[1,0,1]
	v_pk_fma_f32 v[64:65], v[88:89], v[100:101], v[64:65] op_sel_hi:[1,0,1]
	v_pk_fma_f32 v[66:67], v[86:87], v[100:101], v[66:67] op_sel:[0,1,0]
	v_pk_fma_f32 v[64:65], v[84:85], v[100:101], v[64:65] op_sel:[0,1,0]
	v_pk_fma_f32 v[66:67], v[98:99], v[102:103], v[66:67] op_sel_hi:[1,0,1]
	v_pk_fma_f32 v[64:65], v[96:97], v[102:103], v[64:65] op_sel_hi:[1,0,1]
	v_mov_b32_e32 v76, v103
	v_pk_fma_f32 v[64:65], v[72:73], v[76:77], v[64:65] op_sel_hi:[1,0,1]
	v_pk_fma_f32 v[66:67], v[74:75], v[76:77], v[66:67] op_sel_hi:[1,0,1]
	ds_read_b128 v[72:75], v136 offset:80
	s_waitcnt vmcnt(15) lgkmcnt(1)
	v_pk_fma_f32 v[76:77], v[42:43], v[68:69], v[150:151] op_sel_hi:[1,0,1]
	v_pk_fma_f32 v[78:79], v[40:41], v[68:69], v[142:143] op_sel_hi:[1,0,1]
	s_waitcnt vmcnt(14)
	v_pk_fma_f32 v[76:77], v[38:39], v[68:69], v[76:77] op_sel:[0,1,0]
	v_pk_fma_f32 v[68:69], v[36:37], v[68:69], v[78:79] op_sel:[0,1,0]
	s_waitcnt vmcnt(13)
	v_pk_fma_f32 v[76:77], v[50:51], v[70:71], v[76:77] op_sel_hi:[1,0,1]
	v_pk_fma_f32 v[68:69], v[48:49], v[70:71], v[68:69] op_sel_hi:[1,0,1]
	v_mov_b32_e32 v70, v71
	s_waitcnt vmcnt(12)
	v_pk_fma_f32 v[76:77], v[46:47], v[70:71], v[76:77] op_sel_hi:[1,0,1]
	v_pk_fma_f32 v[68:69], v[44:45], v[70:71], v[68:69] op_sel_hi:[1,0,1]
	s_waitcnt vmcnt(11) lgkmcnt(0)
	v_pk_fma_f32 v[70:71], v[58:59], v[72:73], v[76:77] op_sel_hi:[1,0,1]
	v_pk_fma_f32 v[68:69], v[56:57], v[72:73], v[68:69] op_sel_hi:[1,0,1]
	s_waitcnt vmcnt(10)
	v_pk_fma_f32 v[70:71], v[54:55], v[72:73], v[70:71] op_sel:[0,1,0]
	v_pk_fma_f32 v[68:69], v[52:53], v[72:73], v[68:69] op_sel:[0,1,0]
	s_waitcnt vmcnt(9)
	v_pk_fma_f32 v[72:73], v[62:63], v[74:75], v[70:71] op_sel_hi:[1,0,1]
	v_pk_fma_f32 v[76:77], v[60:61], v[74:75], v[68:69] op_sel_hi:[1,0,1]
	ds_read_b128 v[68:71], v136 offset:96
	v_mov_b32_e32 v74, v75
	s_waitcnt vmcnt(8)
	v_pk_fma_f32 v[78:79], v[34:35], v[74:75], v[72:73] op_sel_hi:[1,0,1]
	v_pk_fma_f32 v[76:77], v[32:33], v[74:75], v[76:77] op_sel_hi:[1,0,1]
	ds_read_b128 v[72:75], v136 offset:112
	s_waitcnt vmcnt(7) lgkmcnt(1)
	v_pk_fma_f32 v[78:79], v[14:15], v[68:69], v[78:79] op_sel_hi:[1,0,1]
	v_pk_fma_f32 v[76:77], v[12:13], v[68:69], v[76:77] op_sel_hi:[1,0,1]
	s_waitcnt vmcnt(6)
	v_pk_fma_f32 v[78:79], v[6:7], v[68:69], v[78:79] op_sel:[0,1,0]
	v_pk_fma_f32 v[68:69], v[4:5], v[68:69], v[76:77] op_sel:[0,1,0]
	s_waitcnt vmcnt(5)
	v_pk_fma_f32 v[76:77], v[22:23], v[70:71], v[78:79] op_sel_hi:[1,0,1]
	v_pk_fma_f32 v[68:69], v[20:21], v[70:71], v[68:69] op_sel_hi:[1,0,1]
	v_mov_b32_e32 v70, v71
	s_waitcnt vmcnt(4)
	v_pk_fma_f32 v[76:77], v[10:11], v[70:71], v[76:77] op_sel_hi:[1,0,1]
	v_pk_fma_f32 v[68:69], v[8:9], v[70:71], v[68:69] op_sel_hi:[1,0,1]
	s_waitcnt vmcnt(3) lgkmcnt(0)
	v_pk_fma_f32 v[70:71], v[26:27], v[72:73], v[76:77] op_sel_hi:[1,0,1]
	v_pk_fma_f32 v[68:69], v[24:25], v[72:73], v[68:69] op_sel_hi:[1,0,1]
	s_waitcnt vmcnt(2)
	v_pk_fma_f32 v[70:71], v[18:19], v[72:73], v[70:71] op_sel:[0,1,0]
	v_pk_fma_f32 v[68:69], v[16:17], v[72:73], v[68:69] op_sel:[0,1,0]
	s_waitcnt vmcnt(1)
	v_pk_fma_f32 v[72:73], v[30:31], v[74:75], v[70:71] op_sel_hi:[1,0,1]
	v_pk_fma_f32 v[76:77], v[28:29], v[74:75], v[68:69] op_sel_hi:[1,0,1]
	ds_read_b128 v[68:71], v136 offset:1088
	v_mov_b32_e32 v78, v75
	s_waitcnt vmcnt(0)
	v_pk_fma_f32 v[74:75], v[2:3], v[78:79], v[72:73] op_sel_hi:[1,0,1]
	v_pk_fma_f32 v[72:73], v[0:1], v[78:79], v[76:77] op_sel_hi:[1,0,1]
	ds_read_b128 v[76:79], v136 offset:1104
	s_waitcnt lgkmcnt(1)
	v_pk_fma_f32 v[80:81], v[42:43], v[68:69], v[132:133] op_sel_hi:[1,0,1]
	v_pk_fma_f32 v[82:83], v[40:41], v[68:69], v[128:129] op_sel_hi:[1,0,1]
	v_pk_fma_f32 v[80:81], v[38:39], v[68:69], v[80:81] op_sel:[0,1,0]
	v_pk_fma_f32 v[68:69], v[36:37], v[68:69], v[82:83] op_sel:[0,1,0]
	v_pk_fma_f32 v[80:81], v[50:51], v[70:71], v[80:81] op_sel_hi:[1,0,1]
	v_pk_fma_f32 v[68:69], v[48:49], v[70:71], v[68:69] op_sel_hi:[1,0,1]
	v_mov_b32_e32 v70, v71
	v_pk_fma_f32 v[80:81], v[46:47], v[70:71], v[80:81] op_sel_hi:[1,0,1]
	v_pk_fma_f32 v[68:69], v[44:45], v[70:71], v[68:69] op_sel_hi:[1,0,1]
	s_waitcnt lgkmcnt(0)
	v_pk_fma_f32 v[70:71], v[58:59], v[76:77], v[80:81] op_sel_hi:[1,0,1]
	v_pk_fma_f32 v[68:69], v[56:57], v[76:77], v[68:69] op_sel_hi:[1,0,1]
	v_pk_fma_f32 v[70:71], v[54:55], v[76:77], v[70:71] op_sel:[0,1,0]
	v_pk_fma_f32 v[68:69], v[52:53], v[76:77], v[68:69] op_sel:[0,1,0]
	v_pk_fma_f32 v[76:77], v[62:63], v[78:79], v[70:71] op_sel_hi:[1,0,1]
	v_pk_fma_f32 v[80:81], v[60:61], v[78:79], v[68:69] op_sel_hi:[1,0,1]
	ds_read_b128 v[68:71], v136 offset:1120
	v_mov_b32_e32 v78, v79
	v_pk_fma_f32 v[82:83], v[34:35], v[78:79], v[76:77] op_sel_hi:[1,0,1]
	v_pk_fma_f32 v[80:81], v[32:33], v[78:79], v[80:81] op_sel_hi:[1,0,1]
	ds_read_b128 v[76:79], v136 offset:1136
	s_waitcnt lgkmcnt(1)
	v_pk_fma_f32 v[82:83], v[14:15], v[68:69], v[82:83] op_sel_hi:[1,0,1]
	v_pk_fma_f32 v[80:81], v[12:13], v[68:69], v[80:81] op_sel_hi:[1,0,1]
	v_pk_fma_f32 v[82:83], v[6:7], v[68:69], v[82:83] op_sel:[0,1,0]
	v_pk_fma_f32 v[68:69], v[4:5], v[68:69], v[80:81] op_sel:[0,1,0]
	v_pk_fma_f32 v[80:81], v[22:23], v[70:71], v[82:83] op_sel_hi:[1,0,1]
	v_pk_fma_f32 v[68:69], v[20:21], v[70:71], v[68:69] op_sel_hi:[1,0,1]
	v_mov_b32_e32 v70, v71
	v_pk_fma_f32 v[80:81], v[10:11], v[70:71], v[80:81] op_sel_hi:[1,0,1]
	v_pk_fma_f32 v[68:69], v[8:9], v[70:71], v[68:69] op_sel_hi:[1,0,1]
	s_waitcnt lgkmcnt(0)
; #define LAS __attribute__((address_space(3)))
; DI void lbar() { asm volatile("s_waitcnt lgkmcnt(0)" ::: "memory"); __builtin_amdgcn_s_barrier(); asm volatile("" ::: "memory"); }
; DI void attn_sample_item(const Params& p, int item, ldsp lds, int tid_) {
;     ...
; #pragma unroll
;     for (int t = 0; t < 4; ++t)
; #pragma unroll
;       for (int j4 = 0; j4 < 4; ++j4) { const f32x4 pp = *(const LAS f32x4*)(SC + t * 256 + wid * 32 + j4 * 4);
; #pragma unroll
;         for (int e = 0; e < 4; ++e) acc[t] += pp[e] * vvA[j4 * 4 + e]; }
; #pragma unroll
;     for (int t = 0; t < 4; ++t)
; #pragma unroll
;       for (int j4 = 0; j4 < 4; ++j4) { const f32x4 pp = *(const LAS f32x4*)(SC + t * 256 + wid * 32 + 16 + j4 * 4);
; #pragma unroll
;         for (int e = 0; e < 4; ++e) acc[t] += pp[e] * vvB[j4 * 4 + e]; }
; #pragma unroll
;     for (int t = 0; t < 4; ++t) *(LAS f32x4*)(PART + (wid * 4 + t) * 256 + lane * 4) = acc[t];
;   }
;   lbar();
;   {
;     const int e0 = tid * 2, t = e0 >> 8, d = e0 & 255;
	v_pk_fma_f32 v[70:71], v[26:27], v[76:77], v[80:81] op_sel_hi:[1,0,1]
	v_pk_fma_f32 v[68:69], v[24:25], v[76:77], v[68:69] op_sel_hi:[1,0,1]
	v_pk_fma_f32 v[70:71], v[18:19], v[76:77], v[70:71] op_sel:[0,1,0]
	v_pk_fma_f32 v[68:69], v[16:17], v[76:77], v[68:69] op_sel:[0,1,0]
	v_pk_fma_f32 v[76:77], v[30:31], v[78:79], v[70:71] op_sel_hi:[1,0,1]
	v_pk_fma_f32 v[80:81], v[28:29], v[78:79], v[68:69] op_sel_hi:[1,0,1]
	ds_read_b128 v[68:71], v136 offset:2112
	v_mov_b32_e32 v82, v79
	v_pk_fma_f32 v[78:79], v[2:3], v[82:83], v[76:77] op_sel_hi:[1,0,1]
	v_pk_fma_f32 v[76:77], v[0:1], v[82:83], v[80:81] op_sel_hi:[1,0,1]
	ds_read_b128 v[80:83], v136 offset:2128
	s_waitcnt lgkmcnt(1)
	v_pk_fma_f32 v[84:85], v[42:43], v[68:69], v[134:135] op_sel_hi:[1,0,1]
	v_pk_fma_f32 v[86:87], v[40:41], v[68:69], v[130:131] op_sel_hi:[1,0,1]
	v_pk_fma_f32 v[84:85], v[38:39], v[68:69], v[84:85] op_sel:[0,1,0]
	v_pk_fma_f32 v[68:69], v[36:37], v[68:69], v[86:87] op_sel:[0,1,0]
	v_pk_fma_f32 v[84:85], v[50:51], v[70:71], v[84:85] op_sel_hi:[1,0,1]
	v_pk_fma_f32 v[68:69], v[48:49], v[70:71], v[68:69] op_sel_hi:[1,0,1]
	v_mov_b32_e32 v70, v71
	v_pk_fma_f32 v[84:85], v[46:47], v[70:71], v[84:85] op_sel_hi:[1,0,1]
	v_pk_fma_f32 v[68:69], v[44:45], v[70:71], v[68:69] op_sel_hi:[1,0,1]
	s_waitcnt lgkmcnt(0)
	v_pk_fma_f32 v[70:71], v[58:59], v[80:81], v[84:85] op_sel_hi:[1,0,1]
	v_pk_fma_f32 v[68:69], v[56:57], v[80:81], v[68:69] op_sel_hi:[1,0,1]
	v_pk_fma_f32 v[70:71], v[54:55], v[80:81], v[70:71] op_sel:[0,1,0]
	v_pk_fma_f32 v[68:69], v[52:53], v[80:81], v[68:69] op_sel:[0,1,0]
	v_pk_fma_f32 v[80:81], v[62:63], v[82:83], v[70:71] op_sel_hi:[1,0,1]
	v_pk_fma_f32 v[84:85], v[60:61], v[82:83], v[68:69] op_sel_hi:[1,0,1]
	ds_read_b128 v[68:71], v136 offset:2144
	v_mov_b32_e32 v82, v83
	v_pk_fma_f32 v[86:87], v[34:35], v[82:83], v[80:81] op_sel_hi:[1,0,1]
	v_pk_fma_f32 v[84:85], v[32:33], v[82:83], v[84:85] op_sel_hi:[1,0,1]
	ds_read_b128 v[80:83], v136 offset:2160
	s_waitcnt lgkmcnt(1)
	v_pk_fma_f32 v[86:87], v[14:15], v[68:69], v[86:87] op_sel_hi:[1,0,1]
	v_pk_fma_f32 v[84:85], v[12:13], v[68:69], v[84:85] op_sel_hi:[1,0,1]
	v_pk_fma_f32 v[86:87], v[6:7], v[68:69], v[86:87] op_sel:[0,1,0]
	v_pk_fma_f32 v[68:69], v[4:5], v[68:69], v[84:85] op_sel:[0,1,0]
	v_pk_fma_f32 v[84:85], v[22:23], v[70:71], v[86:87] op_sel_hi:[1,0,1]
	v_pk_fma_f32 v[68:69], v[20:21], v[70:71], v[68:69] op_sel_hi:[1,0,1]
	v_mov_b32_e32 v70, v71
	v_pk_fma_f32 v[84:85], v[10:11], v[70:71], v[84:85] op_sel_hi:[1,0,1]
	v_pk_fma_f32 v[68:69], v[8:9], v[70:71], v[68:69] op_sel_hi:[1,0,1]
	s_waitcnt lgkmcnt(0)
	v_pk_fma_f32 v[70:71], v[26:27], v[80:81], v[84:85] op_sel_hi:[1,0,1]
	v_pk_fma_f32 v[68:69], v[24:25], v[80:81], v[68:69] op_sel_hi:[1,0,1]
	v_pk_fma_f32 v[70:71], v[18:19], v[80:81], v[70:71] op_sel:[0,1,0]
	v_pk_fma_f32 v[68:69], v[16:17], v[80:81], v[68:69] op_sel:[0,1,0]
	v_pk_fma_f32 v[80:81], v[30:31], v[82:83], v[70:71] op_sel_hi:[1,0,1]
	v_pk_fma_f32 v[84:85], v[28:29], v[82:83], v[68:69] op_sel_hi:[1,0,1]
	ds_read_b128 v[68:71], v136 offset:3136
	v_mov_b32_e32 v86, v83
	v_pk_fma_f32 v[82:83], v[2:3], v[86:87], v[80:81] op_sel_hi:[1,0,1]
	v_pk_fma_f32 v[80:81], v[0:1], v[86:87], v[84:85] op_sel_hi:[1,0,1]
	ds_read_b128 v[84:87], v136 offset:3152
	s_waitcnt lgkmcnt(1)
	v_pk_fma_f32 v[42:43], v[42:43], v[68:69], v[66:67] op_sel_hi:[1,0,1]
	v_pk_fma_f32 v[40:41], v[40:41], v[68:69], v[64:65] op_sel_hi:[1,0,1]
	v_pk_fma_f32 v[38:39], v[38:39], v[68:69], v[42:43] op_sel:[0,1,0]
	v_pk_fma_f32 v[36:37], v[36:37], v[68:69], v[40:41] op_sel:[0,1,0]
	v_pk_fma_f32 v[38:39], v[50:51], v[70:71], v[38:39] op_sel_hi:[1,0,1]
	v_pk_fma_f32 v[36:37], v[48:49], v[70:71], v[36:37] op_sel_hi:[1,0,1]
	v_mov_b32_e32 v40, v71
	v_pk_fma_f32 v[38:39], v[46:47], v[40:41], v[38:39] op_sel_hi:[1,0,1]
	v_pk_fma_f32 v[36:37], v[44:45], v[40:41], v[36:37] op_sel_hi:[1,0,1]
	s_waitcnt lgkmcnt(0)
	v_pk_fma_f32 v[38:39], v[58:59], v[84:85], v[38:39] op_sel_hi:[1,0,1]
	v_pk_fma_f32 v[36:37], v[56:57], v[84:85], v[36:37] op_sel_hi:[1,0,1]
	v_pk_fma_f32 v[38:39], v[54:55], v[84:85], v[38:39] op_sel:[0,1,0]
	v_pk_fma_f32 v[36:37], v[52:53], v[84:85], v[36:37] op_sel:[0,1,0]
	v_pk_fma_f32 v[40:41], v[62:63], v[86:87], v[38:39] op_sel_hi:[1,0,1]
	v_pk_fma_f32 v[42:43], v[60:61], v[86:87], v[36:37] op_sel_hi:[1,0,1]
	ds_read_b128 v[36:39], v136 offset:3168
	v_mov_b32_e32 v44, v87
	v_pk_fma_f32 v[40:41], v[34:35], v[44:45], v[40:41] op_sel_hi:[1,0,1]
	v_pk_fma_f32 v[42:43], v[32:33], v[44:45], v[42:43] op_sel_hi:[1,0,1]
	ds_read_b128 v[32:35], v136 offset:3184
	s_waitcnt lgkmcnt(1)
	v_pk_fma_f32 v[12:13], v[12:13], v[36:37], v[42:43] op_sel_hi:[1,0,1]
	v_pk_fma_f32 v[14:15], v[14:15], v[36:37], v[40:41] op_sel_hi:[1,0,1]
	v_pk_fma_f32 v[4:5], v[4:5], v[36:37], v[12:13] op_sel:[0,1,0]
	v_mov_b32_e32 v12, v39
	v_pk_fma_f32 v[4:5], v[20:21], v[38:39], v[4:5] op_sel_hi:[1,0,1]
	v_pk_fma_f32 v[6:7], v[6:7], v[36:37], v[14:15] op_sel:[0,1,0]
	v_pk_fma_f32 v[4:5], v[8:9], v[12:13], v[4:5] op_sel_hi:[1,0,1]
	v_pk_fma_f32 v[6:7], v[22:23], v[38:39], v[6:7] op_sel_hi:[1,0,1]
	s_waitcnt lgkmcnt(0)
	v_pk_fma_f32 v[4:5], v[24:25], v[32:33], v[4:5] op_sel_hi:[1,0,1]
	v_pk_fma_f32 v[6:7], v[10:11], v[12:13], v[6:7] op_sel_hi:[1,0,1]
	v_pk_fma_f32 v[4:5], v[16:17], v[32:33], v[4:5] op_sel:[0,1,0]
	v_pk_fma_f32 v[6:7], v[26:27], v[32:33], v[6:7] op_sel_hi:[1,0,1]
	v_pk_fma_f32 v[4:5], v[28:29], v[34:35], v[4:5] op_sel_hi:[1,0,1]
	v_mov_b32_e32 v8, v35
	v_pk_fma_f32 v[6:7], v[18:19], v[32:33], v[6:7] op_sel:[0,1,0]
	v_pk_fma_f32 v[0:1], v[0:1], v[8:9], v[4:5] op_sel_hi:[1,0,1]
	v_lshlrev_b32_e32 v4, 12, v210
	v_pk_fma_f32 v[6:7], v[30:31], v[34:35], v[6:7] op_sel_hi:[1,0,1]
	v_add3_u32 v4, 16, v4, v144
	v_pk_fma_f32 v[2:3], v[2:3], v[8:9], v[6:7] op_sel_hi:[1,0,1]
	ds_write_b128 v4, v[72:75] offset:4096
	ds_write_b128 v4, v[76:79] offset:5120
	ds_write_b128 v4, v[80:83] offset:6144
	ds_write_b128 v4, v[0:3] offset:7168
	v_lshlrev_b32_e32 v0, 1, v222
	v_ashrrev_i32_e32 v16, 7, v222
	v_and_b32_e32 v17, 0xfe, v0
	v_lshlrev_b32_e32 v0, 10, v16
	v_lshlrev_b32_e32 v1, 2, v17
	s_waitcnt lgkmcnt(0)
	s_barrier
; #define LAS __attribute__((address_space(3)))
; DI unsigned pk2(float lo, float hi) { f32x2 v = {lo, hi}; return __builtin_bit_cast(unsigned, __builtin_convertvector(v, bf16x2v)); }
; DI void lbar() { asm volatile("s_waitcnt lgkmcnt(0)" ::: "memory"); __builtin_amdgcn_s_barrier(); asm volatile("" ::: "memory"); }
; DI void attn_sample_item(const Params& p, int item, ldsp lds, int tid_) {
;     ...
;   for (int t = 0; t < 4; ++t) { f32x4 a = {0.f, 0.f, 0.f, 0.f}; const float* pp = (const float*)(p.ws + B_PART) + (size_t)(b * 4 + t) * 1024 + h * 256 + lane * 4;
; #pragma unroll
;     for (int kp = 0; kp < 4; ++kp) a += *(const f32x4*)(pp + (size_t)kp * 512 * 1024);
;     q[t][0] = a[0] * 0.0625f; q[t][1] = a[1] * 0.0625f; q[t][2] = a[2] * 0.0625f; q[t][3] = a[3] * 0.0625f; }
;     ...
;   {
;     const int e0 = tid * 2, t = e0 >> 8, d = e0 & 255;
;     float s0 = 0.f, s1 = 0.f;
; #pragma unroll
;     for (int w = 0; w < 8; ++w) { const f32x2 v = *(const LAS f32x2*)(PART + (w * 4 + t) * 256 + d); s0 += v[0]; s1 += v[1]; }
;     *(unsigned*)((bf16_t*)(p.ws + B_XA) + (size_t)(TP + b * 4 + t) * D + h * 256 + d) = pk2(s0, s1);
;   }
;   lbar();
	v_add3_u32 v12, 16, v0, v1
	ds_read2st64_b64 v[0:3], v12 offset0:8 offset1:16
	ds_read2st64_b64 v[4:7], v12 offset0:24 offset1:32
	ds_read2st64_b64 v[8:11], v12 offset0:40 offset1:48
	ds_read2st64_b64 v[12:15], v12 offset0:56 offset1:64
	v_lshlrev_b32_e32 v144, 1, v17
	s_waitcnt lgkmcnt(3)
	v_pk_add_f32 v[0:1], v[0:1], 0 op_sel_hi:[1,0]
	s_cmpk_lt_i32 s38, 0x200
	v_pk_add_f32 v[0:1], v[0:1], v[2:3]
	s_waitcnt lgkmcnt(2)
	v_pk_add_f32 v[0:1], v[0:1], v[4:5]
	s_nop 0
	v_pk_add_f32 v[0:1], v[0:1], v[6:7]
	s_waitcnt lgkmcnt(1)
	v_pk_add_f32 v[0:1], v[0:1], v[8:9]
	s_nop 0
	v_pk_add_f32 v[0:1], v[0:1], v[10:11]
	s_waitcnt lgkmcnt(0)
	v_pk_add_f32 v[0:1], v[0:1], v[12:13]
	s_nop 0
	v_pk_add_f32 v[0:1], v[0:1], v[14:15]
	s_nop 0
	v_cvt_pk_bf16_f32 v2, v0, v1
	v_add_u32_e32 v0, s4, v16
	v_ashrrev_i32_e32 v1, 31, v0
	v_lshlrev_b64 v[0:1], 11, v[0:1]
	v_lshl_add_u64 v[0:1], s[22:23], 0, v[0:1]
	v_lshl_add_u64 v[0:1], v[0:1], 0, s[24:25]
	v_lshl_add_u64 v[0:1], v[0:1], 0, v[144:145]
	global_store_dword v[0:1], v2, off
	s_waitcnt lgkmcnt(0)
	s_barrier
	s_cbranch_scc0 .LBB0_1742
.LBB0_1676:
	s_ashr_i32 s4, s38, 2
	s_ashr_i32 s5, s4, 31
	s_lshl_b64 s[4:5], s[4:5], 18
	s_and_b32 s24, s0, 0x300
	v_mov_b32_e32 v222, v212
	s_or_b32 s4, s4, s24
	s_and_b32 s26, s38, -4
	s_lshl_b32 s6, s24, 2
	s_add_u32 s6, s36, s6
	v_and_b32_e32 v223, 63, v222
	s_addc_u32 s7, s37, 0
	v_lshlrev_b32_e32 v144, 4, v223
	s_ashr_i32 s27, s26, 31
	v_lshl_add_u64 v[48:49], s[6:7], 0, v[144:145]
	s_lshl_b64 s[6:7], s[26:27], 12
	v_lshl_add_u64 v[8:9], v[48:49], 0, s[6:7]
	v_add_co_u32_e32 v10, vcc, s3, v8
	s_or_b32 s6, s26, 1
	s_nop 0
	v_addc_co_u32_e32 v11, vcc, 0, v9, vcc
	global_load_dwordx4 v[0:3], v[8:9], off
	global_load_dwordx4 v[4:7], v[10:11], off
	v_add_co_u32_e32 v10, vcc, s33, v8
	s_ashr_i32 s7, s6, 31
	s_nop 0
	v_addc_co_u32_e32 v11, vcc, 0, v9, vcc
	v_add_co_u32_e32 v12, vcc, s34, v8
	s_lshl_b64 s[6:7], s[6:7], 12
	s_nop 0
	v_addc_co_u32_e32 v13, vcc, 0, v9, vcc
	v_lshl_add_u64 v[24:25], v[48:49], 0, s[6:7]
	v_add_co_u32_e32 v20, vcc, s3, v24
	s_or_b32 s6, s26, 2
	s_nop 0
	v_addc_co_u32_e32 v21, vcc, 0, v25, vcc
	v_add_co_u32_e32 v26, vcc, s33, v24
	s_ashr_i32 s7, s6, 31
	s_nop 0
	v_addc_co_u32_e32 v27, vcc, 0, v25, vcc
	v_add_co_u32_e32 v28, vcc, s34, v24
	s_lshl_b64 s[6:7], s[6:7], 12
	s_nop 0
	v_addc_co_u32_e32 v29, vcc, 0, v25, vcc
	v_lshl_add_u64 v[44:45], v[48:49], 0, s[6:7]
	global_load_dwordx4 v[8:11], v[10:11], off
	s_nop 0
	global_load_dwordx4 v[12:15], v[12:13], off
	s_nop 0
	global_load_dwordx4 v[16:19], v[24:25], off
	s_nop 0
	global_load_dwordx4 v[20:23], v[20:21], off
	v_add_co_u32_e32 v36, vcc, s3, v44
	global_load_dwordx4 v[24:27], v[26:27], off
	s_nop 0
	global_load_dwordx4 v[28:31], v[28:29], off
	v_addc_co_u32_e32 v37, vcc, 0, v45, vcc
	v_add_co_u32_e32 v40, vcc, s33, v44
	global_load_dwordx4 v[32:35], v[44:45], off
	s_nop 0
	global_load_dwordx4 v[36:39], v[36:37], off
	v_addc_co_u32_e32 v41, vcc, 0, v45, vcc
	v_add_co_u32_e32 v44, vcc, s34, v44
	global_load_dwordx4 v[40:43], v[40:41], off
	s_nop 0
	v_addc_co_u32_e32 v45, vcc, 0, v45, vcc
	global_load_dwordx4 v[44:47], v[44:45], off
	s_or_b32 s6, s38, 3
	s_ashr_i32 s7, s6, 31
	s_lshl_b64 s[6:7], s[6:7], 12
	s_lshl_b64 s[28:29], s[4:5], 2
	s_add_u32 s4, s12, s28
	s_addc_u32 s5, s13, s29
	s_waitcnt vmcnt(11)
	v_pk_add_f32 v[2:3], v[2:3], 0 op_sel_hi:[1,0]
	v_pk_add_f32 v[0:1], v[0:1], 0 op_sel_hi:[1,0]
	s_waitcnt vmcnt(10)
	v_pk_add_f32 v[2:3], v[2:3], v[6:7]
	v_pk_add_f32 v[0:1], v[0:1], v[4:5]
	s_waitcnt vmcnt(9)
	v_pk_add_f32 v[2:3], v[2:3], v[10:11]
	s_waitcnt vmcnt(7)
	v_pk_add_f32 v[4:5], v[18:19], 0 op_sel_hi:[1,0]
	v_pk_add_f32 v[6:7], v[16:17], 0 op_sel_hi:[1,0]
	v_pk_add_f32 v[0:1], v[0:1], v[8:9]
	s_waitcnt vmcnt(6)
	v_pk_add_f32 v[4:5], v[4:5], v[22:23]
	v_pk_add_f32 v[6:7], v[6:7], v[20:21]
	v_pk_add_f32 v[2:3], v[2:3], v[14:15]
	v_pk_add_f32 v[0:1], v[0:1], v[12:13]
	s_waitcnt vmcnt(5)
	v_pk_add_f32 v[4:5], v[4:5], v[26:27]
	v_pk_add_f32 v[6:7], v[6:7], v[24:25]
	v_mul_f32_e32 v228, 0x3d800000, v0
	v_mul_f32_e32 v231, 0x3d800000, v1
	v_mul_f32_e32 v229, 0x3d800000, v2
	v_mul_f32_e32 v225, 0x3d800000, v3
	s_waitcnt vmcnt(4)
	v_pk_add_f32 v[0:1], v[4:5], v[30:31]
	v_pk_add_f32 v[2:3], v[6:7], v[28:29]
	v_mul_f32_e32 v227, 0x3d800000, v0
	v_mul_f32_e32 v226, 0x3d800000, v2
	v_mul_f32_e32 v230, 0x3d800000, v3
	v_mul_f32_e32 v224, 0x3d800000, v1
	s_waitcnt vmcnt(3)
	v_pk_add_f32 v[0:1], v[34:35], 0 op_sel_hi:[1,0]
	v_pk_add_f32 v[2:3], v[32:33], 0 op_sel_hi:[1,0]
	s_waitcnt vmcnt(2)
	v_pk_add_f32 v[0:1], v[0:1], v[38:39]
	v_pk_add_f32 v[2:3], v[2:3], v[36:37]
	s_waitcnt vmcnt(1)
	v_pk_add_f32 v[0:1], v[0:1], v[42:43]
	v_pk_add_f32 v[2:3], v[2:3], v[40:41]
	s_waitcnt vmcnt(0)
; DI void attn_sample_item(const Params& p, int item, ldsp lds, int tid_) {
;     ...
;   for (int t = 0; t < 4; ++t) { f32x4 a = {0.f, 0.f, 0.f, 0.f}; const float* pp = (const float*)(p.ws + B_PART) + (size_t)(b * 4 + t) * 1024 + h * 256 + lane * 4;
; #pragma unroll
;     for (int kp = 0; kp < 4; ++kp) a += *(const f32x4*)(pp + (size_t)kp * 512 * 1024);
;     q[t][0] = a[0] * 0.0625f; q[t][1] = a[1] * 0.0625f; q[t][2] = a[2] * 0.0625f; q[t][3] = a[3] * 0.0625f; }
;   const bool b0 = lane & 1, b1 = lane & 2;
;   f32x4 kvA[16], kvB[16];
; #pragma unroll
;   for (int j = 0; j < 16; ++j) kvA[j] = __builtin_nontemporal_load((const f32x4*)(ck + (size_t)(wid * 32 + j) * 1024 + lane * 4));
; #pragma unroll
;   for (int j = 0; j < 16; ++j) kvB[j] = __builtin_nontemporal_load((const f32x4*)(ck + (size_t)(wid * 32 + 16 + j) * 1024 + lane * 4));
	v_pk_add_f32 v[210:211], v[0:1], v[46:47]
	v_pk_add_f32 v[0:1], v[2:3], v[44:45]
	v_mul_f32_e32 v233, 0x3d800000, v210
	v_mul_f32_e32 v232, 0x3d800000, v0
	v_mul_f32_e32 v234, 0x3d800000, v1
	v_lshl_add_u64 v[0:1], v[48:49], 0, s[6:7]
	v_add_co_u32_e32 v2, vcc, s3, v0
	v_ashrrev_i32_e32 v210, 6, v222
	s_nop 0
	v_addc_co_u32_e32 v3, vcc, 0, v1, vcc
	global_load_dwordx4 v[128:131], v[0:1], off
	global_load_dwordx4 v[132:135], v[2:3], off
	v_add_co_u32_e32 v2, vcc, s33, v0
	v_mul_f32_e32 v211, 0x3d800000, v211
	s_nop 0
	v_addc_co_u32_e32 v3, vcc, 0, v1, vcc
	v_add_co_u32_e32 v0, vcc, s34, v0
	v_cmp_lt_i32_e64 s[6:7], v218, v216
	s_nop 0
	v_addc_co_u32_e32 v1, vcc, 0, v1, vcc
	global_load_dwordx4 v[136:139], v[2:3], off
	global_load_dwordx4 v[140:143], v[0:1], off
	v_lshlrev_b32_e32 v0, 5, v210
	v_ashrrev_i32_e32 v1, 31, v0
	v_or_b32_e32 v6, 1, v0
	v_lshl_add_u64 v[2:3], s[4:5], 0, v[144:145]
	v_lshlrev_b64 v[158:159], 12, v[0:1]
	v_ashrrev_i32_e32 v7, 31, v6
	v_lshl_add_u64 v[4:5], v[2:3], 0, v[158:159]
	v_lshlrev_b64 v[162:163], 12, v[6:7]
	v_lshl_add_u64 v[6:7], v[2:3], 0, v[162:163]
	global_load_dwordx4 v[124:127], v[4:5], off nt
	global_load_dwordx4 v[120:123], v[6:7], off nt
	v_or_b32_e32 v4, 2, v0
	v_ashrrev_i32_e32 v5, 31, v4
	v_or_b32_e32 v6, 3, v0
	v_lshlrev_b64 v[164:165], 12, v[4:5]
	v_ashrrev_i32_e32 v7, 31, v6
	v_lshl_add_u64 v[4:5], v[2:3], 0, v[164:165]
	v_lshlrev_b64 v[168:169], 12, v[6:7]
	v_lshl_add_u64 v[6:7], v[2:3], 0, v[168:169]
	global_load_dwordx4 v[116:119], v[4:5], off nt
	global_load_dwordx4 v[112:115], v[6:7], off nt
	v_or_b32_e32 v4, 4, v0
	v_ashrrev_i32_e32 v5, 31, v4
	v_or_b32_e32 v6, 5, v0
	v_lshlrev_b64 v[172:173], 12, v[4:5]
	v_ashrrev_i32_e32 v7, 31, v6
	v_lshl_add_u64 v[4:5], v[2:3], 0, v[172:173]
	v_lshlrev_b64 v[176:177], 12, v[6:7]
	v_lshl_add_u64 v[6:7], v[2:3], 0, v[176:177]
	global_load_dwordx4 v[108:111], v[4:5], off nt
	global_load_dwordx4 v[104:107], v[6:7], off nt
	v_or_b32_e32 v4, 6, v0
	v_ashrrev_i32_e32 v5, 31, v4
	v_or_b32_e32 v6, 7, v0
	v_lshlrev_b64 v[180:181], 12, v[4:5]
	v_ashrrev_i32_e32 v7, 31, v6
	v_lshl_add_u64 v[4:5], v[2:3], 0, v[180:181]
	v_lshlrev_b64 v[184:185], 12, v[6:7]
	v_lshl_add_u64 v[6:7], v[2:3], 0, v[184:185]
	global_load_dwordx4 v[100:103], v[4:5], off nt
	global_load_dwordx4 v[96:99], v[6:7], off nt
	v_or_b32_e32 v4, 8, v0
	v_ashrrev_i32_e32 v5, 31, v4
	v_or_b32_e32 v6, 9, v0
	v_lshlrev_b64 v[188:189], 12, v[4:5]
	v_ashrrev_i32_e32 v7, 31, v6
	v_lshl_add_u64 v[4:5], v[2:3], 0, v[188:189]
	v_lshlrev_b64 v[192:193], 12, v[6:7]
	v_lshl_add_u64 v[6:7], v[2:3], 0, v[192:193]
	global_load_dwordx4 v[92:95], v[4:5], off nt
	global_load_dwordx4 v[88:91], v[6:7], off nt
	v_or_b32_e32 v4, 10, v0
	v_ashrrev_i32_e32 v5, 31, v4
	v_or_b32_e32 v6, 11, v0
	v_lshlrev_b64 v[196:197], 12, v[4:5]
	v_ashrrev_i32_e32 v7, 31, v6
	v_lshl_add_u64 v[4:5], v[2:3], 0, v[196:197]
	v_lshlrev_b64 v[200:201], 12, v[6:7]
	v_lshl_add_u64 v[6:7], v[2:3], 0, v[200:201]
	global_load_dwordx4 v[84:87], v[4:5], off nt
	global_load_dwordx4 v[80:83], v[6:7], off nt
	v_or_b32_e32 v4, 12, v0
	v_ashrrev_i32_e32 v5, 31, v4
	v_or_b32_e32 v6, 13, v0
	v_lshlrev_b64 v[202:203], 12, v[4:5]
	v_ashrrev_i32_e32 v7, 31, v6
	v_lshl_add_u64 v[4:5], v[2:3], 0, v[202:203]
	v_lshlrev_b64 v[204:205], 12, v[6:7]
	v_lshl_add_u64 v[6:7], v[2:3], 0, v[204:205]
	global_load_dwordx4 v[76:79], v[4:5], off nt
	global_load_dwordx4 v[72:75], v[6:7], off nt
	v_or_b32_e32 v4, 14, v0
	v_ashrrev_i32_e32 v5, 31, v4
	v_or_b32_e32 v6, 15, v0
	v_lshlrev_b64 v[206:207], 12, v[4:5]
	v_ashrrev_i32_e32 v7, 31, v6
	v_lshl_add_u64 v[4:5], v[2:3], 0, v[206:207]
	v_lshlrev_b64 v[208:209], 12, v[6:7]
	v_lshl_add_u64 v[6:7], v[2:3], 0, v[208:209]
	global_load_dwordx4 v[68:71], v[4:5], off nt
	global_load_dwordx4 v[64:67], v[6:7], off nt
	v_or_b32_e32 v4, 16, v0
	v_ashrrev_i32_e32 v5, 31, v4
	v_or_b32_e32 v6, 17, v0
	v_lshlrev_b64 v[146:147], 12, v[4:5]
	v_ashrrev_i32_e32 v7, 31, v6
	v_lshl_add_u64 v[4:5], v[2:3], 0, v[146:147]
	v_lshlrev_b64 v[148:149], 12, v[6:7]
	v_lshl_add_u64 v[6:7], v[2:3], 0, v[148:149]
	global_load_dwordx4 v[60:63], v[4:5], off nt
	global_load_dwordx4 v[56:59], v[6:7], off nt
	v_or_b32_e32 v4, 18, v0
	v_ashrrev_i32_e32 v5, 31, v4
	v_or_b32_e32 v6, 19, v0
	v_lshlrev_b64 v[150:151], 12, v[4:5]
	v_ashrrev_i32_e32 v7, 31, v6
	v_lshl_add_u64 v[4:5], v[2:3], 0, v[150:151]
	v_lshlrev_b64 v[152:153], 12, v[6:7]
	v_lshl_add_u64 v[6:7], v[2:3], 0, v[152:153]
	global_load_dwordx4 v[52:55], v[4:5], off nt
	global_load_dwordx4 v[48:51], v[6:7], off nt
	v_or_b32_e32 v4, 20, v0
	v_ashrrev_i32_e32 v5, 31, v4
	v_or_b32_e32 v6, 21, v0
	v_lshlrev_b64 v[154:155], 12, v[4:5]
	v_ashrrev_i32_e32 v7, 31, v6
	v_lshl_add_u64 v[4:5], v[2:3], 0, v[154:155]
	v_lshlrev_b64 v[156:157], 12, v[6:7]
	v_lshl_add_u64 v[6:7], v[2:3], 0, v[156:157]
	global_load_dwordx4 v[44:47], v[4:5], off nt
	global_load_dwordx4 v[40:43], v[6:7], off nt
	v_or_b32_e32 v4, 22, v0
	v_ashrrev_i32_e32 v5, 31, v4
	v_or_b32_e32 v6, 23, v0
	v_lshlrev_b64 v[160:161], 12, v[4:5]
	v_ashrrev_i32_e32 v7, 31, v6
	v_lshl_add_u64 v[4:5], v[2:3], 0, v[160:161]
	v_lshlrev_b64 v[166:167], 12, v[6:7]
	v_lshl_add_u64 v[6:7], v[2:3], 0, v[166:167]
	global_load_dwordx4 v[36:39], v[4:5], off nt
	global_load_dwordx4 v[32:35], v[6:7], off nt
	v_or_b32_e32 v4, 24, v0
	v_ashrrev_i32_e32 v5, 31, v4
	v_or_b32_e32 v6, 25, v0
	v_lshlrev_b64 v[170:171], 12, v[4:5]
	v_ashrrev_i32_e32 v7, 31, v6
	v_lshl_add_u64 v[4:5], v[2:3], 0, v[170:171]
	v_lshlrev_b64 v[174:175], 12, v[6:7]
	v_lshl_add_u64 v[6:7], v[2:3], 0, v[174:175]
	global_load_dwordx4 v[28:31], v[4:5], off nt
	global_load_dwordx4 v[24:27], v[6:7], off nt
	v_or_b32_e32 v4, 26, v0
	v_ashrrev_i32_e32 v5, 31, v4
	v_or_b32_e32 v6, 27, v0
	v_lshlrev_b64 v[178:179], 12, v[4:5]
	v_ashrrev_i32_e32 v7, 31, v6
	v_lshl_add_u64 v[4:5], v[2:3], 0, v[178:179]
	v_lshlrev_b64 v[182:183], 12, v[6:7]
	v_lshl_add_u64 v[6:7], v[2:3], 0, v[182:183]
	global_load_dwordx4 v[20:23], v[4:5], off nt
	global_load_dwordx4 v[16:19], v[6:7], off nt
	v_or_b32_e32 v4, 28, v0
	v_ashrrev_i32_e32 v5, 31, v4
	v_or_b32_e32 v6, 29, v0
	v_lshlrev_b64 v[186:187], 12, v[4:5]
	v_ashrrev_i32_e32 v7, 31, v6
	v_lshl_add_u64 v[4:5], v[2:3], 0, v[186:187]
	v_lshlrev_b64 v[190:191], 12, v[6:7]
	v_lshl_add_u64 v[6:7], v[2:3], 0, v[190:191]
	global_load_dwordx4 v[12:15], v[4:5], off nt
	global_load_dwordx4 v[8:11], v[6:7], off nt
	v_or_b32_e32 v4, 30, v0
	v_or_b32_e32 v0, 31, v0
	v_ashrrev_i32_e32 v5, 31, v4
	v_ashrrev_i32_e32 v1, 31, v0
	v_lshlrev_b64 v[194:195], 12, v[4:5]
	v_lshlrev_b64 v[198:199], 12, v[0:1]
	v_lshl_add_u64 v[4:5], v[2:3], 0, v[194:195]
	v_lshl_add_u64 v[0:1], v[2:3], 0, v[198:199]
	global_load_dwordx4 v[4:7], v[4:5], off nt
	s_nop 0
	global_load_dwordx4 v[0:3], v[0:1], off nt
	s_waitcnt vmcnt(35)
; DI void attn_sample_item(const Params& p, int item, ldsp lds, int tid_) {
;     ...
;     q[t][0] = a[0] * 0.0625f; q[t][1] = a[1] * 0.0625f; q[t][2] = a[2] * 0.0625f; q[t][3] = a[3] * 0.0625f; }
	v_pk_add_f32 v[128:129], v[128:129], 0 op_sel_hi:[1,0]
	v_pk_add_f32 v[130:131], v[130:131], 0 op_sel_hi:[1,0]
	s_waitcnt vmcnt(34)
	v_pk_add_f32 v[128:129], v[128:129], v[132:133]
	v_pk_add_f32 v[130:131], v[130:131], v[134:135]
	s_waitcnt vmcnt(33)
	v_pk_add_f32 v[128:129], v[128:129], v[136:137]
	v_pk_add_f32 v[130:131], v[130:131], v[138:139]
	s_waitcnt vmcnt(32)
	v_pk_add_f32 v[128:129], v[128:129], v[140:141]
	v_pk_add_f32 v[130:131], v[130:131], v[142:143]
	v_mul_f32_e32 v138, 0x3d800000, v129
	v_mul_f32_e32 v135, 0x3d800000, v128
	v_mul_f32_e32 v134, 0x3d800000, v131
	s_add_u32 s66, s14, s28
	s_addc_u32 s67, s15, s29
	v_mul_f32_e32 v137, 0x3d800000, v130
	v_lshlrev_b32_e32 v128, 2, v215
	v_lshlrev_b32_e32 v129, 2, v217
	v_lshlrev_b32_e32 v130, 2, v218
	v_lshlrev_b32_e32 v131, 2, v219
	v_lshlrev_b32_e32 v132, 2, v220
	v_lshlrev_b32_e32 v133, 2, v221
	v_lshl_add_u32 v136, v210, 7, 16
	v_and_b32_e32 v139, 3, v223
	v_bfrev_b32_e32 v139, v139
	v_lshrrev_b32_e32 v139, 20, v139
	v_and_b32_e32 v235, -4, v223
	v_add3_u32 v235, v136, v139, v235
	v_mov_b32_e32 v236, v228
	v_mov_b32_e32 v237, v226
	v_mov_b32_e32 v238, v231
	v_mov_b32_e32 v239, v230
	v_mov_b32_e32 v240, v229
	v_mov_b32_e32 v241, v227
	v_mov_b32_e32 v242, v225
	v_mov_b32_e32 v243, v224
	v_mov_b32_e32 v244, v232
	v_mov_b32_e32 v245, v135
	v_mov_b32_e32 v246, v234
	v_mov_b32_e32 v247, v138
	v_mov_b32_e32 v248, v233
	v_mov_b32_e32 v249, v137
	v_mov_b32_e32 v250, v211
	v_mov_b32_e32 v251, v134
	s_mov_b32 vcc_lo, 0x55555555
	s_mov_b32 vcc_hi, 0x55555555
	s_mov_b32 s4, 0x33333333
	s_mov_b32 s5, 0x33333333
	s_mov_b32 s6, 0x0f0f0f0f
	s_mov_b32 s7, 0x0f0f0f0f
	s_mov_b32 s64, 0x00ff00ff
	s_mov_b32 s65, 0x00ff00ff
	s_waitcnt vmcnt(31)
	v_pk_mul_f32 v[252:253], v[236:237], v[124:125] op_sel_hi:[1,0]
	v_pk_mul_f32 v[254:255], v[244:245], v[124:125] op_sel_hi:[1,0]
	v_pk_fma_f32 v[252:253], v[238:239], v[124:125], v[252:253] op_sel:[0,1,0]
	v_pk_fma_f32 v[254:255], v[246:247], v[124:125], v[254:255] op_sel:[0,1,0]
	v_pk_fma_f32 v[252:253], v[240:241], v[126:127], v[252:253] op_sel_hi:[1,0,1]
	v_pk_fma_f32 v[254:255], v[248:249], v[126:127], v[254:255] op_sel_hi:[1,0,1]
	v_pk_fma_f32 v[252:253], v[242:243], v[126:127], v[252:253] op_sel:[0,1,0]
	v_pk_fma_f32 v[254:255], v[250:251], v[126:127], v[254:255] op_sel:[0,1,0]
	s_waitcnt vmcnt(30)
	v_pk_mul_f32 v[140:141], v[236:237], v[120:121] op_sel_hi:[1,0]
	v_pk_mul_f32 v[142:143], v[244:245], v[120:121] op_sel_hi:[1,0]
	v_pk_fma_f32 v[140:141], v[238:239], v[120:121], v[140:141] op_sel:[0,1,0]
	v_pk_fma_f32 v[142:143], v[246:247], v[120:121], v[142:143] op_sel:[0,1,0]
	v_pk_fma_f32 v[140:141], v[240:241], v[122:123], v[140:141] op_sel_hi:[1,0,1]
	v_pk_fma_f32 v[142:143], v[248:249], v[122:123], v[142:143] op_sel_hi:[1,0,1]
	v_pk_fma_f32 v[140:141], v[242:243], v[122:123], v[140:141] op_sel:[0,1,0]
	v_pk_fma_f32 v[142:143], v[250:251], v[122:123], v[142:143] op_sel:[0,1,0]
	v_add_f32_dpp v124, v252, v252 quad_perm:[1,0,3,2] row_mask:0xf bank_mask:0xf
	v_add_f32_dpp v125, v253, v253 quad_perm:[1,0,3,2] row_mask:0xf bank_mask:0xf
	v_add_f32_dpp v126, v254, v254 quad_perm:[1,0,3,2] row_mask:0xf bank_mask:0xf
	v_add_f32_dpp v127, v255, v255 quad_perm:[1,0,3,2] row_mask:0xf bank_mask:0xf
	v_cndmask_b32_e32 v124, v126, v124, vcc
	v_cndmask_b32_e32 v125, v127, v125, vcc
	s_waitcnt vmcnt(29)
	v_pk_mul_f32 v[252:253], v[236:237], v[116:117] op_sel_hi:[1,0]
	v_pk_mul_f32 v[254:255], v[244:245], v[116:117] op_sel_hi:[1,0]
	v_pk_fma_f32 v[252:253], v[238:239], v[116:117], v[252:253] op_sel:[0,1,0]
	v_pk_fma_f32 v[254:255], v[246:247], v[116:117], v[254:255] op_sel:[0,1,0]
	v_pk_fma_f32 v[252:253], v[240:241], v[118:119], v[252:253] op_sel_hi:[1,0,1]
	v_pk_fma_f32 v[254:255], v[248:249], v[118:119], v[254:255] op_sel_hi:[1,0,1]
	v_pk_fma_f32 v[252:253], v[242:243], v[118:119], v[252:253] op_sel:[0,1,0]
	v_pk_fma_f32 v[254:255], v[250:251], v[118:119], v[254:255] op_sel:[0,1,0]
	v_add_f32_dpp v120, v140, v140 quad_perm:[1,0,3,2] row_mask:0xf bank_mask:0xf
	v_add_f32_dpp v121, v141, v141 quad_perm:[1,0,3,2] row_mask:0xf bank_mask:0xf
	v_add_f32_dpp v122, v142, v142 quad_perm:[1,0,3,2] row_mask:0xf bank_mask:0xf
	v_add_f32_dpp v123, v143, v143 quad_perm:[1,0,3,2] row_mask:0xf bank_mask:0xf
	v_cndmask_b32_e32 v120, v122, v120, vcc
	v_cndmask_b32_e32 v121, v123, v121, vcc
	v_add_f32_dpp v126, v124, v124 quad_perm:[2,3,0,1] row_mask:0xf bank_mask:0xf
	v_add_f32_dpp v127, v125, v125 quad_perm:[2,3,0,1] row_mask:0xf bank_mask:0xf
	v_cndmask_b32_e64 v124, v127, v126, s[4:5]
	s_waitcnt vmcnt(28)
	v_pk_mul_f32 v[140:141], v[236:237], v[112:113] op_sel_hi:[1,0]
	v_pk_mul_f32 v[142:143], v[244:245], v[112:113] op_sel_hi:[1,0]
	v_pk_fma_f32 v[140:141], v[238:239], v[112:113], v[140:141] op_sel:[0,1,0]
	v_pk_fma_f32 v[142:143], v[246:247], v[112:113], v[142:143] op_sel:[0,1,0]
	v_pk_fma_f32 v[140:141], v[240:241], v[114:115], v[140:141] op_sel_hi:[1,0,1]
	v_pk_fma_f32 v[142:143], v[248:249], v[114:115], v[142:143] op_sel_hi:[1,0,1]
	v_pk_fma_f32 v[140:141], v[242:243], v[114:115], v[140:141] op_sel:[0,1,0]
	v_pk_fma_f32 v[142:143], v[250:251], v[114:115], v[142:143] op_sel:[0,1,0]
	v_add_f32_dpp v116, v252, v252 quad_perm:[1,0,3,2] row_mask:0xf bank_mask:0xf
	v_add_f32_dpp v117, v253, v253 quad_perm:[1,0,3,2] row_mask:0xf bank_mask:0xf
	v_add_f32_dpp v118, v254, v254 quad_perm:[1,0,3,2] row_mask:0xf bank_mask:0xf
	v_add_f32_dpp v119, v255, v255 quad_perm:[1,0,3,2] row_mask:0xf bank_mask:0xf
	v_cndmask_b32_e32 v116, v118, v116, vcc
	v_cndmask_b32_e32 v117, v119, v117, vcc
	v_add_f32_dpp v122, v120, v120 quad_perm:[2,3,0,1] row_mask:0xf bank_mask:0xf
	v_add_f32_dpp v123, v121, v121 quad_perm:[2,3,0,1] row_mask:0xf bank_mask:0xf
	v_cndmask_b32_e64 v120, v123, v122, s[4:5]
	v_cndmask_b32_e64 v125, v120, v124, s[6:7]
	v_cndmask_b32_e64 v126, v124, v120, s[6:7]
	s_waitcnt vmcnt(27)
	v_pk_mul_f32 v[252:253], v[236:237], v[108:109] op_sel_hi:[1,0]
	v_pk_mul_f32 v[254:255], v[244:245], v[108:109] op_sel_hi:[1,0]
	v_pk_fma_f32 v[252:253], v[238:239], v[108:109], v[252:253] op_sel:[0,1,0]
	v_pk_fma_f32 v[254:255], v[246:247], v[108:109], v[254:255] op_sel:[0,1,0]
	v_pk_fma_f32 v[252:253], v[240:241], v[110:111], v[252:253] op_sel_hi:[1,0,1]
	v_pk_fma_f32 v[254:255], v[248:249], v[110:111], v[254:255] op_sel_hi:[1,0,1]
	v_pk_fma_f32 v[252:253], v[242:243], v[110:111], v[252:253] op_sel:[0,1,0]
	v_pk_fma_f32 v[254:255], v[250:251], v[110:111], v[254:255] op_sel:[0,1,0]
	v_add_f32_dpp v124, v126, v125 row_ror:4 row_mask:0xf bank_mask:0xf
	v_add_f32_dpp v112, v140, v140 quad_perm:[1,0,3,2] row_mask:0xf bank_mask:0xf
	v_add_f32_dpp v113, v141, v141 quad_perm:[1,0,3,2] row_mask:0xf bank_mask:0xf
	v_add_f32_dpp v114, v142, v142 quad_perm:[1,0,3,2] row_mask:0xf bank_mask:0xf
	v_add_f32_dpp v115, v143, v143 quad_perm:[1,0,3,2] row_mask:0xf bank_mask:0xf
	v_cndmask_b32_e32 v112, v114, v112, vcc
	v_cndmask_b32_e32 v113, v115, v113, vcc
	v_add_f32_dpp v118, v116, v116 quad_perm:[2,3,0,1] row_mask:0xf bank_mask:0xf
	v_add_f32_dpp v119, v117, v117 quad_perm:[2,3,0,1] row_mask:0xf bank_mask:0xf
	v_cndmask_b32_e64 v116, v119, v118, s[4:5]
	s_waitcnt vmcnt(26)
	v_pk_mul_f32 v[140:141], v[236:237], v[104:105] op_sel_hi:[1,0]
	v_pk_mul_f32 v[142:143], v[244:245], v[104:105] op_sel_hi:[1,0]
	v_pk_fma_f32 v[140:141], v[238:239], v[104:105], v[140:141] op_sel:[0,1,0]
	v_pk_fma_f32 v[142:143], v[246:247], v[104:105], v[142:143] op_sel:[0,1,0]
	v_pk_fma_f32 v[140:141], v[240:241], v[106:107], v[140:141] op_sel_hi:[1,0,1]
	v_pk_fma_f32 v[142:143], v[248:249], v[106:107], v[142:143] op_sel_hi:[1,0,1]
	v_pk_fma_f32 v[140:141], v[242:243], v[106:107], v[140:141] op_sel:[0,1,0]
	v_pk_fma_f32 v[142:143], v[250:251], v[106:107], v[142:143] op_sel:[0,1,0]
	v_add_f32_dpp v108, v252, v252 quad_perm:[1,0,3,2] row_mask:0xf bank_mask:0xf
	v_add_f32_dpp v109, v253, v253 quad_perm:[1,0,3,2] row_mask:0xf bank_mask:0xf
	v_add_f32_dpp v110, v254, v254 quad_perm:[1,0,3,2] row_mask:0xf bank_mask:0xf
	v_add_f32_dpp v111, v255, v255 quad_perm:[1,0,3,2] row_mask:0xf bank_mask:0xf
	v_cndmask_b32_e32 v108, v110, v108, vcc
	v_cndmask_b32_e32 v109, v111, v109, vcc
	v_add_f32_dpp v114, v112, v112 quad_perm:[2,3,0,1] row_mask:0xf bank_mask:0xf
	v_add_f32_dpp v115, v113, v113 quad_perm:[2,3,0,1] row_mask:0xf bank_mask:0xf
	v_cndmask_b32_e64 v112, v115, v114, s[4:5]
	v_cndmask_b32_e64 v117, v112, v116, s[6:7]
	v_cndmask_b32_e64 v118, v116, v112, s[6:7]
	s_waitcnt vmcnt(25)
	v_pk_mul_f32 v[252:253], v[236:237], v[100:101] op_sel_hi:[1,0]
	v_pk_mul_f32 v[254:255], v[244:245], v[100:101] op_sel_hi:[1,0]
	v_pk_fma_f32 v[252:253], v[238:239], v[100:101], v[252:253] op_sel:[0,1,0]
	v_pk_fma_f32 v[254:255], v[246:247], v[100:101], v[254:255] op_sel:[0,1,0]
	v_pk_fma_f32 v[252:253], v[240:241], v[102:103], v[252:253] op_sel_hi:[1,0,1]
	v_pk_fma_f32 v[254:255], v[248:249], v[102:103], v[254:255] op_sel_hi:[1,0,1]
	v_pk_fma_f32 v[252:253], v[242:243], v[102:103], v[252:253] op_sel:[0,1,0]
	v_pk_fma_f32 v[254:255], v[250:251], v[102:103], v[254:255] op_sel:[0,1,0]
	v_add_f32_dpp v116, v118, v117 row_ror:4 row_mask:0xf bank_mask:0xf
	v_cndmask_b32_e64 v125, v116, v124, s[64:65]
	v_cndmask_b32_e64 v126, v124, v116, s[64:65]
	v_add_f32_dpp v104, v140, v140 quad_perm:[1,0,3,2] row_mask:0xf bank_mask:0xf
	v_add_f32_dpp v105, v141, v141 quad_perm:[1,0,3,2] row_mask:0xf bank_mask:0xf
	v_add_f32_dpp v106, v142, v142 quad_perm:[1,0,3,2] row_mask:0xf bank_mask:0xf
	v_add_f32_dpp v107, v143, v143 quad_perm:[1,0,3,2] row_mask:0xf bank_mask:0xf
	v_cndmask_b32_e32 v104, v106, v104, vcc
	v_cndmask_b32_e32 v105, v107, v105, vcc
	v_add_f32_dpp v110, v108, v108 quad_perm:[2,3,0,1] row_mask:0xf bank_mask:0xf
	v_add_f32_dpp v111, v109, v109 quad_perm:[2,3,0,1] row_mask:0xf bank_mask:0xf
	v_cndmask_b32_e64 v108, v111, v110, s[4:5]
	s_waitcnt vmcnt(24)
	v_pk_mul_f32 v[140:141], v[236:237], v[96:97] op_sel_hi:[1,0]
	v_pk_mul_f32 v[142:143], v[244:245], v[96:97] op_sel_hi:[1,0]
	v_pk_fma_f32 v[140:141], v[238:239], v[96:97], v[140:141] op_sel:[0,1,0]
	v_pk_fma_f32 v[142:143], v[246:247], v[96:97], v[142:143] op_sel:[0,1,0]
	v_pk_fma_f32 v[140:141], v[240:241], v[98:99], v[140:141] op_sel_hi:[1,0,1]
	v_pk_fma_f32 v[142:143], v[248:249], v[98:99], v[142:143] op_sel_hi:[1,0,1]
	v_pk_fma_f32 v[140:141], v[242:243], v[98:99], v[140:141] op_sel:[0,1,0]
	v_pk_fma_f32 v[142:143], v[250:251], v[98:99], v[142:143] op_sel:[0,1,0]
	v_add_f32_dpp v124, v126, v125 row_ror:8 row_mask:0xf bank_mask:0xf
	v_add_f32_dpp v100, v252, v252 quad_perm:[1,0,3,2] row_mask:0xf bank_mask:0xf
	v_add_f32_dpp v101, v253, v253 quad_perm:[1,0,3,2] row_mask:0xf bank_mask:0xf
	v_add_f32_dpp v102, v254, v254 quad_perm:[1,0,3,2] row_mask:0xf bank_mask:0xf
	v_add_f32_dpp v103, v255, v255 quad_perm:[1,0,3,2] row_mask:0xf bank_mask:0xf
	v_cndmask_b32_e32 v100, v102, v100, vcc
	v_cndmask_b32_e32 v101, v103, v101, vcc
	v_add_f32_dpp v106, v104, v104 quad_perm:[2,3,0,1] row_mask:0xf bank_mask:0xf
	v_add_f32_dpp v107, v105, v105 quad_perm:[2,3,0,1] row_mask:0xf bank_mask:0xf
	v_cndmask_b32_e64 v104, v107, v106, s[4:5]
	v_cndmask_b32_e64 v109, v104, v108, s[6:7]
	v_cndmask_b32_e64 v110, v108, v104, s[6:7]
	s_waitcnt vmcnt(23)
	v_pk_mul_f32 v[252:253], v[236:237], v[92:93] op_sel_hi:[1,0]
	v_pk_mul_f32 v[254:255], v[244:245], v[92:93] op_sel_hi:[1,0]
	v_pk_fma_f32 v[252:253], v[238:239], v[92:93], v[252:253] op_sel:[0,1,0]
	v_pk_fma_f32 v[254:255], v[246:247], v[92:93], v[254:255] op_sel:[0,1,0]
	v_pk_fma_f32 v[252:253], v[240:241], v[94:95], v[252:253] op_sel_hi:[1,0,1]
	v_pk_fma_f32 v[254:255], v[248:249], v[94:95], v[254:255] op_sel_hi:[1,0,1]
	v_pk_fma_f32 v[252:253], v[242:243], v[94:95], v[252:253] op_sel:[0,1,0]
	v_pk_fma_f32 v[254:255], v[250:251], v[94:95], v[254:255] op_sel:[0,1,0]
	v_add_f32_dpp v108, v110, v109 row_ror:4 row_mask:0xf bank_mask:0xf
	v_add_f32_dpp v96, v140, v140 quad_perm:[1,0,3,2] row_mask:0xf bank_mask:0xf
	v_add_f32_dpp v97, v141, v141 quad_perm:[1,0,3,2] row_mask:0xf bank_mask:0xf
	v_add_f32_dpp v98, v142, v142 quad_perm:[1,0,3,2] row_mask:0xf bank_mask:0xf
	v_add_f32_dpp v99, v143, v143 quad_perm:[1,0,3,2] row_mask:0xf bank_mask:0xf
	v_cndmask_b32_e32 v96, v98, v96, vcc
	v_cndmask_b32_e32 v97, v99, v97, vcc
	v_add_f32_dpp v102, v100, v100 quad_perm:[2,3,0,1] row_mask:0xf bank_mask:0xf
	v_add_f32_dpp v103, v101, v101 quad_perm:[2,3,0,1] row_mask:0xf bank_mask:0xf
	v_cndmask_b32_e64 v100, v103, v102, s[4:5]
	s_waitcnt vmcnt(22)
	v_pk_mul_f32 v[140:141], v[236:237], v[88:89] op_sel_hi:[1,0]
	v_pk_mul_f32 v[142:143], v[244:245], v[88:89] op_sel_hi:[1,0]
	v_pk_fma_f32 v[140:141], v[238:239], v[88:89], v[140:141] op_sel:[0,1,0]
	v_pk_fma_f32 v[142:143], v[246:247], v[88:89], v[142:143] op_sel:[0,1,0]
	v_pk_fma_f32 v[140:141], v[240:241], v[90:91], v[140:141] op_sel_hi:[1,0,1]
	v_pk_fma_f32 v[142:143], v[248:249], v[90:91], v[142:143] op_sel_hi:[1,0,1]
	v_pk_fma_f32 v[140:141], v[242:243], v[90:91], v[140:141] op_sel:[0,1,0]
	v_pk_fma_f32 v[142:143], v[250:251], v[90:91], v[142:143] op_sel:[0,1,0]
	v_add_f32_dpp v92, v252, v252 quad_perm:[1,0,3,2] row_mask:0xf bank_mask:0xf
	v_add_f32_dpp v93, v253, v253 quad_perm:[1,0,3,2] row_mask:0xf bank_mask:0xf
	v_add_f32_dpp v94, v254, v254 quad_perm:[1,0,3,2] row_mask:0xf bank_mask:0xf
	v_add_f32_dpp v95, v255, v255 quad_perm:[1,0,3,2] row_mask:0xf bank_mask:0xf
	v_cndmask_b32_e32 v92, v94, v92, vcc
	v_cndmask_b32_e32 v93, v95, v93, vcc
	v_add_f32_dpp v98, v96, v96 quad_perm:[2,3,0,1] row_mask:0xf bank_mask:0xf
	v_add_f32_dpp v99, v97, v97 quad_perm:[2,3,0,1] row_mask:0xf bank_mask:0xf
	v_cndmask_b32_e64 v96, v99, v98, s[4:5]
	v_cndmask_b32_e64 v101, v96, v100, s[6:7]
	v_cndmask_b32_e64 v102, v100, v96, s[6:7]
	s_waitcnt vmcnt(21)
	v_pk_mul_f32 v[252:253], v[236:237], v[84:85] op_sel_hi:[1,0]
	v_pk_mul_f32 v[254:255], v[244:245], v[84:85] op_sel_hi:[1,0]
	v_pk_fma_f32 v[252:253], v[238:239], v[84:85], v[252:253] op_sel:[0,1,0]
	v_pk_fma_f32 v[254:255], v[246:247], v[84:85], v[254:255] op_sel:[0,1,0]
	v_pk_fma_f32 v[252:253], v[240:241], v[86:87], v[252:253] op_sel_hi:[1,0,1]
	v_pk_fma_f32 v[254:255], v[248:249], v[86:87], v[254:255] op_sel_hi:[1,0,1]
	v_pk_fma_f32 v[252:253], v[242:243], v[86:87], v[252:253] op_sel:[0,1,0]
	v_pk_fma_f32 v[254:255], v[250:251], v[86:87], v[254:255] op_sel:[0,1,0]
	v_add_f32_dpp v100, v102, v101 row_ror:4 row_mask:0xf bank_mask:0xf
	v_cndmask_b32_e64 v109, v100, v108, s[64:65]
	v_cndmask_b32_e64 v110, v108, v100, s[64:65]
	v_add_f32_dpp v88, v140, v140 quad_perm:[1,0,3,2] row_mask:0xf bank_mask:0xf
	v_add_f32_dpp v89, v141, v141 quad_perm:[1,0,3,2] row_mask:0xf bank_mask:0xf
	v_add_f32_dpp v90, v142, v142 quad_perm:[1,0,3,2] row_mask:0xf bank_mask:0xf
	v_add_f32_dpp v91, v143, v143 quad_perm:[1,0,3,2] row_mask:0xf bank_mask:0xf
	v_cndmask_b32_e32 v88, v90, v88, vcc
	v_cndmask_b32_e32 v89, v91, v89, vcc
	v_add_f32_dpp v94, v92, v92 quad_perm:[2,3,0,1] row_mask:0xf bank_mask:0xf
	v_add_f32_dpp v95, v93, v93 quad_perm:[2,3,0,1] row_mask:0xf bank_mask:0xf
	v_cndmask_b32_e64 v92, v95, v94, s[4:5]
	s_waitcnt vmcnt(20)
	v_pk_mul_f32 v[140:141], v[236:237], v[80:81] op_sel_hi:[1,0]
	v_pk_mul_f32 v[142:143], v[244:245], v[80:81] op_sel_hi:[1,0]
	v_pk_fma_f32 v[140:141], v[238:239], v[80:81], v[140:141] op_sel:[0,1,0]
	v_pk_fma_f32 v[142:143], v[246:247], v[80:81], v[142:143] op_sel:[0,1,0]
	v_pk_fma_f32 v[140:141], v[240:241], v[82:83], v[140:141] op_sel_hi:[1,0,1]
	v_pk_fma_f32 v[142:143], v[248:249], v[82:83], v[142:143] op_sel_hi:[1,0,1]
	v_pk_fma_f32 v[140:141], v[242:243], v[82:83], v[140:141] op_sel:[0,1,0]
	v_pk_fma_f32 v[142:143], v[250:251], v[82:83], v[142:143] op_sel:[0,1,0]
	v_add_f32_dpp v108, v110, v109 row_ror:8 row_mask:0xf bank_mask:0xf
	v_add_f32_dpp v84, v252, v252 quad_perm:[1,0,3,2] row_mask:0xf bank_mask:0xf
	v_add_f32_dpp v85, v253, v253 quad_perm:[1,0,3,2] row_mask:0xf bank_mask:0xf
	v_add_f32_dpp v86, v254, v254 quad_perm:[1,0,3,2] row_mask:0xf bank_mask:0xf
	v_add_f32_dpp v87, v255, v255 quad_perm:[1,0,3,2] row_mask:0xf bank_mask:0xf
	v_cndmask_b32_e32 v84, v86, v84, vcc
	v_cndmask_b32_e32 v85, v87, v85, vcc
	v_add_f32_dpp v90, v88, v88 quad_perm:[2,3,0,1] row_mask:0xf bank_mask:0xf
	v_add_f32_dpp v91, v89, v89 quad_perm:[2,3,0,1] row_mask:0xf bank_mask:0xf
	v_cndmask_b32_e64 v88, v91, v90, s[4:5]
	v_cndmask_b32_e64 v93, v88, v92, s[6:7]
	v_cndmask_b32_e64 v94, v92, v88, s[6:7]
	s_waitcnt vmcnt(19)
	v_pk_mul_f32 v[252:253], v[236:237], v[76:77] op_sel_hi:[1,0]
	v_pk_mul_f32 v[254:255], v[244:245], v[76:77] op_sel_hi:[1,0]
	v_pk_fma_f32 v[252:253], v[238:239], v[76:77], v[252:253] op_sel:[0,1,0]
	v_pk_fma_f32 v[254:255], v[246:247], v[76:77], v[254:255] op_sel:[0,1,0]
	v_pk_fma_f32 v[252:253], v[240:241], v[78:79], v[252:253] op_sel_hi:[1,0,1]
	v_pk_fma_f32 v[254:255], v[248:249], v[78:79], v[254:255] op_sel_hi:[1,0,1]
	v_pk_fma_f32 v[252:253], v[242:243], v[78:79], v[252:253] op_sel:[0,1,0]
	v_pk_fma_f32 v[254:255], v[250:251], v[78:79], v[254:255] op_sel:[0,1,0]
	v_permlane16_swap_b32_e32 v124, v108
	v_add_f32_e32 v124, v124, v108
	v_add_f32_dpp v92, v94, v93 row_ror:4 row_mask:0xf bank_mask:0xf
	v_add_f32_dpp v80, v140, v140 quad_perm:[1,0,3,2] row_mask:0xf bank_mask:0xf
	v_add_f32_dpp v81, v141, v141 quad_perm:[1,0,3,2] row_mask:0xf bank_mask:0xf
	v_add_f32_dpp v82, v142, v142 quad_perm:[1,0,3,2] row_mask:0xf bank_mask:0xf
	v_add_f32_dpp v83, v143, v143 quad_perm:[1,0,3,2] row_mask:0xf bank_mask:0xf
	v_cndmask_b32_e32 v80, v82, v80, vcc
	v_cndmask_b32_e32 v81, v83, v81, vcc
	v_add_f32_dpp v86, v84, v84 quad_perm:[2,3,0,1] row_mask:0xf bank_mask:0xf
	v_add_f32_dpp v87, v85, v85 quad_perm:[2,3,0,1] row_mask:0xf bank_mask:0xf
	v_cndmask_b32_e64 v84, v87, v86, s[4:5]
	s_waitcnt vmcnt(18)
	v_pk_mul_f32 v[140:141], v[236:237], v[72:73] op_sel_hi:[1,0]
	v_pk_mul_f32 v[142:143], v[244:245], v[72:73] op_sel_hi:[1,0]
	v_pk_fma_f32 v[140:141], v[238:239], v[72:73], v[140:141] op_sel:[0,1,0]
	v_pk_fma_f32 v[142:143], v[246:247], v[72:73], v[142:143] op_sel:[0,1,0]
	v_pk_fma_f32 v[140:141], v[240:241], v[74:75], v[140:141] op_sel_hi:[1,0,1]
	v_pk_fma_f32 v[142:143], v[248:249], v[74:75], v[142:143] op_sel_hi:[1,0,1]
	v_pk_fma_f32 v[140:141], v[242:243], v[74:75], v[140:141] op_sel:[0,1,0]
	v_pk_fma_f32 v[142:143], v[250:251], v[74:75], v[142:143] op_sel:[0,1,0]
	v_add_f32_dpp v76, v252, v252 quad_perm:[1,0,3,2] row_mask:0xf bank_mask:0xf
	v_add_f32_dpp v77, v253, v253 quad_perm:[1,0,3,2] row_mask:0xf bank_mask:0xf
	v_add_f32_dpp v78, v254, v254 quad_perm:[1,0,3,2] row_mask:0xf bank_mask:0xf
	v_add_f32_dpp v79, v255, v255 quad_perm:[1,0,3,2] row_mask:0xf bank_mask:0xf
	v_cndmask_b32_e32 v76, v78, v76, vcc
	v_cndmask_b32_e32 v77, v79, v77, vcc
	v_add_f32_dpp v82, v80, v80 quad_perm:[2,3,0,1] row_mask:0xf bank_mask:0xf
	v_add_f32_dpp v83, v81, v81 quad_perm:[2,3,0,1] row_mask:0xf bank_mask:0xf
	v_cndmask_b32_e64 v80, v83, v82, s[4:5]
	v_cndmask_b32_e64 v85, v80, v84, s[6:7]
	v_cndmask_b32_e64 v86, v84, v80, s[6:7]
	s_waitcnt vmcnt(17)
	v_pk_mul_f32 v[252:253], v[236:237], v[68:69] op_sel_hi:[1,0]
	v_pk_mul_f32 v[254:255], v[244:245], v[68:69] op_sel_hi:[1,0]
	v_pk_fma_f32 v[252:253], v[238:239], v[68:69], v[252:253] op_sel:[0,1,0]
	v_pk_fma_f32 v[254:255], v[246:247], v[68:69], v[254:255] op_sel:[0,1,0]
	v_pk_fma_f32 v[252:253], v[240:241], v[70:71], v[252:253] op_sel_hi:[1,0,1]
	v_pk_fma_f32 v[254:255], v[248:249], v[70:71], v[254:255] op_sel_hi:[1,0,1]
	v_pk_fma_f32 v[252:253], v[242:243], v[70:71], v[252:253] op_sel:[0,1,0]
	v_pk_fma_f32 v[254:255], v[250:251], v[70:71], v[254:255] op_sel:[0,1,0]
	v_add_f32_dpp v84, v86, v85 row_ror:4 row_mask:0xf bank_mask:0xf
	v_cndmask_b32_e64 v93, v84, v92, s[64:65]
	v_cndmask_b32_e64 v94, v92, v84, s[64:65]
	v_add_f32_dpp v72, v140, v140 quad_perm:[1,0,3,2] row_mask:0xf bank_mask:0xf
	v_add_f32_dpp v73, v141, v141 quad_perm:[1,0,3,2] row_mask:0xf bank_mask:0xf
	v_add_f32_dpp v74, v142, v142 quad_perm:[1,0,3,2] row_mask:0xf bank_mask:0xf
	v_add_f32_dpp v75, v143, v143 quad_perm:[1,0,3,2] row_mask:0xf bank_mask:0xf
	v_cndmask_b32_e32 v72, v74, v72, vcc
	v_cndmask_b32_e32 v73, v75, v73, vcc
	v_add_f32_dpp v78, v76, v76 quad_perm:[2,3,0,1] row_mask:0xf bank_mask:0xf
	v_add_f32_dpp v79, v77, v77 quad_perm:[2,3,0,1] row_mask:0xf bank_mask:0xf
	v_cndmask_b32_e64 v76, v79, v78, s[4:5]
	s_waitcnt vmcnt(16)
	v_pk_mul_f32 v[140:141], v[236:237], v[64:65] op_sel_hi:[1,0]
	v_pk_mul_f32 v[142:143], v[244:245], v[64:65] op_sel_hi:[1,0]
	v_pk_fma_f32 v[140:141], v[238:239], v[64:65], v[140:141] op_sel:[0,1,0]
	v_pk_fma_f32 v[142:143], v[246:247], v[64:65], v[142:143] op_sel:[0,1,0]
	v_pk_fma_f32 v[140:141], v[240:241], v[66:67], v[140:141] op_sel_hi:[1,0,1]
	v_pk_fma_f32 v[142:143], v[248:249], v[66:67], v[142:143] op_sel_hi:[1,0,1]
	v_pk_fma_f32 v[140:141], v[242:243], v[66:67], v[140:141] op_sel:[0,1,0]
	v_pk_fma_f32 v[142:143], v[250:251], v[66:67], v[142:143] op_sel:[0,1,0]
	v_add_f32_dpp v92, v94, v93 row_ror:8 row_mask:0xf bank_mask:0xf
	v_add_f32_dpp v68, v252, v252 quad_perm:[1,0,3,2] row_mask:0xf bank_mask:0xf
	v_add_f32_dpp v69, v253, v253 quad_perm:[1,0,3,2] row_mask:0xf bank_mask:0xf
	v_add_f32_dpp v70, v254, v254 quad_perm:[1,0,3,2] row_mask:0xf bank_mask:0xf
	v_add_f32_dpp v71, v255, v255 quad_perm:[1,0,3,2] row_mask:0xf bank_mask:0xf
	v_cndmask_b32_e32 v68, v70, v68, vcc
	v_cndmask_b32_e32 v69, v71, v69, vcc
	v_add_f32_dpp v74, v72, v72 quad_perm:[2,3,0,1] row_mask:0xf bank_mask:0xf
	v_add_f32_dpp v75, v73, v73 quad_perm:[2,3,0,1] row_mask:0xf bank_mask:0xf
	v_cndmask_b32_e64 v72, v75, v74, s[4:5]
	v_cndmask_b32_e64 v77, v72, v76, s[6:7]
	v_cndmask_b32_e64 v78, v76, v72, s[6:7]
	s_waitcnt vmcnt(15)
	v_pk_mul_f32 v[252:253], v[236:237], v[60:61] op_sel_hi:[1,0]
	v_pk_mul_f32 v[254:255], v[244:245], v[60:61] op_sel_hi:[1,0]
	v_pk_fma_f32 v[252:253], v[238:239], v[60:61], v[252:253] op_sel:[0,1,0]
	v_pk_fma_f32 v[254:255], v[246:247], v[60:61], v[254:255] op_sel:[0,1,0]
	v_pk_fma_f32 v[252:253], v[240:241], v[62:63], v[252:253] op_sel_hi:[1,0,1]
	v_pk_fma_f32 v[254:255], v[248:249], v[62:63], v[254:255] op_sel_hi:[1,0,1]
	v_pk_fma_f32 v[252:253], v[242:243], v[62:63], v[252:253] op_sel:[0,1,0]
	v_pk_fma_f32 v[254:255], v[250:251], v[62:63], v[254:255] op_sel:[0,1,0]
	v_add_f32_dpp v76, v78, v77 row_ror:4 row_mask:0xf bank_mask:0xf
	v_add_f32_dpp v64, v140, v140 quad_perm:[1,0,3,2] row_mask:0xf bank_mask:0xf
	v_add_f32_dpp v65, v141, v141 quad_perm:[1,0,3,2] row_mask:0xf bank_mask:0xf
	v_add_f32_dpp v66, v142, v142 quad_perm:[1,0,3,2] row_mask:0xf bank_mask:0xf
	v_add_f32_dpp v67, v143, v143 quad_perm:[1,0,3,2] row_mask:0xf bank_mask:0xf
	v_cndmask_b32_e32 v64, v66, v64, vcc
	v_cndmask_b32_e32 v65, v67, v65, vcc
	v_add_f32_dpp v70, v68, v68 quad_perm:[2,3,0,1] row_mask:0xf bank_mask:0xf
	v_add_f32_dpp v71, v69, v69 quad_perm:[2,3,0,1] row_mask:0xf bank_mask:0xf
	v_cndmask_b32_e64 v68, v71, v70, s[4:5]
	s_waitcnt vmcnt(14)
	v_pk_mul_f32 v[140:141], v[236:237], v[56:57] op_sel_hi:[1,0]
	v_pk_mul_f32 v[142:143], v[244:245], v[56:57] op_sel_hi:[1,0]
	v_pk_fma_f32 v[140:141], v[238:239], v[56:57], v[140:141] op_sel:[0,1,0]
	v_pk_fma_f32 v[142:143], v[246:247], v[56:57], v[142:143] op_sel:[0,1,0]
	v_pk_fma_f32 v[140:141], v[240:241], v[58:59], v[140:141] op_sel_hi:[1,0,1]
	v_pk_fma_f32 v[142:143], v[248:249], v[58:59], v[142:143] op_sel_hi:[1,0,1]
	v_pk_fma_f32 v[140:141], v[242:243], v[58:59], v[140:141] op_sel:[0,1,0]
	v_pk_fma_f32 v[142:143], v[250:251], v[58:59], v[142:143] op_sel:[0,1,0]
	v_add_f32_dpp v60, v252, v252 quad_perm:[1,0,3,2] row_mask:0xf bank_mask:0xf
	v_add_f32_dpp v61, v253, v253 quad_perm:[1,0,3,2] row_mask:0xf bank_mask:0xf
	v_add_f32_dpp v62, v254, v254 quad_perm:[1,0,3,2] row_mask:0xf bank_mask:0xf
	v_add_f32_dpp v63, v255, v255 quad_perm:[1,0,3,2] row_mask:0xf bank_mask:0xf
	v_cndmask_b32_e32 v60, v62, v60, vcc
	v_cndmask_b32_e32 v61, v63, v61, vcc
	v_add_f32_dpp v66, v64, v64 quad_perm:[2,3,0,1] row_mask:0xf bank_mask:0xf
	v_add_f32_dpp v67, v65, v65 quad_perm:[2,3,0,1] row_mask:0xf bank_mask:0xf
	v_cndmask_b32_e64 v64, v67, v66, s[4:5]
	v_cndmask_b32_e64 v69, v64, v68, s[6:7]
	v_cndmask_b32_e64 v70, v68, v64, s[6:7]
	s_waitcnt vmcnt(13)
	v_pk_mul_f32 v[252:253], v[236:237], v[52:53] op_sel_hi:[1,0]
	v_pk_mul_f32 v[254:255], v[244:245], v[52:53] op_sel_hi:[1,0]
	v_pk_fma_f32 v[252:253], v[238:239], v[52:53], v[252:253] op_sel:[0,1,0]
	v_pk_fma_f32 v[254:255], v[246:247], v[52:53], v[254:255] op_sel:[0,1,0]
	v_pk_fma_f32 v[252:253], v[240:241], v[54:55], v[252:253] op_sel_hi:[1,0,1]
	v_pk_fma_f32 v[254:255], v[248:249], v[54:55], v[254:255] op_sel_hi:[1,0,1]
	v_pk_fma_f32 v[252:253], v[242:243], v[54:55], v[252:253] op_sel:[0,1,0]
	v_pk_fma_f32 v[254:255], v[250:251], v[54:55], v[254:255] op_sel:[0,1,0]
	v_add_f32_dpp v68, v70, v69 row_ror:4 row_mask:0xf bank_mask:0xf
	v_cndmask_b32_e64 v77, v68, v76, s[64:65]
	v_cndmask_b32_e64 v78, v76, v68, s[64:65]
	v_add_f32_dpp v56, v140, v140 quad_perm:[1,0,3,2] row_mask:0xf bank_mask:0xf
	v_add_f32_dpp v57, v141, v141 quad_perm:[1,0,3,2] row_mask:0xf bank_mask:0xf
	v_add_f32_dpp v58, v142, v142 quad_perm:[1,0,3,2] row_mask:0xf bank_mask:0xf
	v_add_f32_dpp v59, v143, v143 quad_perm:[1,0,3,2] row_mask:0xf bank_mask:0xf
	v_cndmask_b32_e32 v56, v58, v56, vcc
	v_cndmask_b32_e32 v57, v59, v57, vcc
	v_add_f32_dpp v62, v60, v60 quad_perm:[2,3,0,1] row_mask:0xf bank_mask:0xf
	v_add_f32_dpp v63, v61, v61 quad_perm:[2,3,0,1] row_mask:0xf bank_mask:0xf
	v_cndmask_b32_e64 v60, v63, v62, s[4:5]
	s_waitcnt vmcnt(12)
	v_pk_mul_f32 v[140:141], v[236:237], v[48:49] op_sel_hi:[1,0]
	v_pk_mul_f32 v[142:143], v[244:245], v[48:49] op_sel_hi:[1,0]
	v_pk_fma_f32 v[140:141], v[238:239], v[48:49], v[140:141] op_sel:[0,1,0]
	v_pk_fma_f32 v[142:143], v[246:247], v[48:49], v[142:143] op_sel:[0,1,0]
	v_pk_fma_f32 v[140:141], v[240:241], v[50:51], v[140:141] op_sel_hi:[1,0,1]
	v_pk_fma_f32 v[142:143], v[248:249], v[50:51], v[142:143] op_sel_hi:[1,0,1]
	v_pk_fma_f32 v[140:141], v[242:243], v[50:51], v[140:141] op_sel:[0,1,0]
	v_pk_fma_f32 v[142:143], v[250:251], v[50:51], v[142:143] op_sel:[0,1,0]
	v_add_f32_dpp v76, v78, v77 row_ror:8 row_mask:0xf bank_mask:0xf
	v_add_f32_dpp v52, v252, v252 quad_perm:[1,0,3,2] row_mask:0xf bank_mask:0xf
	v_add_f32_dpp v53, v253, v253 quad_perm:[1,0,3,2] row_mask:0xf bank_mask:0xf
	v_add_f32_dpp v54, v254, v254 quad_perm:[1,0,3,2] row_mask:0xf bank_mask:0xf
	v_add_f32_dpp v55, v255, v255 quad_perm:[1,0,3,2] row_mask:0xf bank_mask:0xf
	v_cndmask_b32_e32 v52, v54, v52, vcc
	v_cndmask_b32_e32 v53, v55, v53, vcc
	v_add_f32_dpp v58, v56, v56 quad_perm:[2,3,0,1] row_mask:0xf bank_mask:0xf
	v_add_f32_dpp v59, v57, v57 quad_perm:[2,3,0,1] row_mask:0xf bank_mask:0xf
	v_cndmask_b32_e64 v56, v59, v58, s[4:5]
	v_cndmask_b32_e64 v61, v56, v60, s[6:7]
	v_cndmask_b32_e64 v62, v60, v56, s[6:7]
	s_waitcnt vmcnt(11)
; DI void attn_sample_item(const Params& p, int item, ldsp lds, int tid_) {
;     ...
;   SC_SCORE(kvA, 0)
;   SC_SCORE(kvB, 1)
;     ...
;   f32x4 vvA[16], vvB[16];
; #pragma unroll
;   for (int j = 0; j < 16; ++j) vvA[j] = __builtin_nontemporal_load((const f32x4*)(cv + (size_t)(wid * 32 + j) * 1024 + lane * 4));
	v_pk_mul_f32 v[252:253], v[236:237], v[44:45] op_sel_hi:[1,0]
	v_pk_mul_f32 v[254:255], v[244:245], v[44:45] op_sel_hi:[1,0]
	v_pk_fma_f32 v[252:253], v[238:239], v[44:45], v[252:253] op_sel:[0,1,0]
	v_pk_fma_f32 v[254:255], v[246:247], v[44:45], v[254:255] op_sel:[0,1,0]
	v_pk_fma_f32 v[252:253], v[240:241], v[46:47], v[252:253] op_sel_hi:[1,0,1]
	v_pk_fma_f32 v[254:255], v[248:249], v[46:47], v[254:255] op_sel_hi:[1,0,1]
	v_pk_fma_f32 v[252:253], v[242:243], v[46:47], v[252:253] op_sel:[0,1,0]
	v_pk_fma_f32 v[254:255], v[250:251], v[46:47], v[254:255] op_sel:[0,1,0]
	v_permlane16_swap_b32_e32 v92, v76
	v_add_f32_e32 v92, v92, v76
	v_add_f32_dpp v60, v62, v61 row_ror:4 row_mask:0xf bank_mask:0xf
	v_add_f32_dpp v48, v140, v140 quad_perm:[1,0,3,2] row_mask:0xf bank_mask:0xf
	v_add_f32_dpp v49, v141, v141 quad_perm:[1,0,3,2] row_mask:0xf bank_mask:0xf
	v_add_f32_dpp v50, v142, v142 quad_perm:[1,0,3,2] row_mask:0xf bank_mask:0xf
	v_add_f32_dpp v51, v143, v143 quad_perm:[1,0,3,2] row_mask:0xf bank_mask:0xf
	v_cndmask_b32_e32 v48, v50, v48, vcc
	v_cndmask_b32_e32 v49, v51, v49, vcc
	v_add_f32_dpp v54, v52, v52 quad_perm:[2,3,0,1] row_mask:0xf bank_mask:0xf
	v_add_f32_dpp v55, v53, v53 quad_perm:[2,3,0,1] row_mask:0xf bank_mask:0xf
	v_cndmask_b32_e64 v52, v55, v54, s[4:5]
	s_waitcnt vmcnt(10)
	v_pk_mul_f32 v[140:141], v[236:237], v[40:41] op_sel_hi:[1,0]
	v_pk_mul_f32 v[142:143], v[244:245], v[40:41] op_sel_hi:[1,0]
	v_pk_fma_f32 v[140:141], v[238:239], v[40:41], v[140:141] op_sel:[0,1,0]
	v_pk_fma_f32 v[142:143], v[246:247], v[40:41], v[142:143] op_sel:[0,1,0]
	v_pk_fma_f32 v[140:141], v[240:241], v[42:43], v[140:141] op_sel_hi:[1,0,1]
	v_pk_fma_f32 v[142:143], v[248:249], v[42:43], v[142:143] op_sel_hi:[1,0,1]
	v_pk_fma_f32 v[140:141], v[242:243], v[42:43], v[140:141] op_sel:[0,1,0]
	v_pk_fma_f32 v[142:143], v[250:251], v[42:43], v[142:143] op_sel:[0,1,0]
	v_permlane32_swap_b32_e32 v124, v92
	v_add_f32_e32 v124, v124, v92
	ds_write_b32 v235, v124
	v_add_u32_e32 v100, v158, v144
	global_load_dwordx4 v[100:103], v100, s[66:67] nt
	v_add_u32_e32 v92, v162, v144
	global_load_dwordx4 v[92:95], v92, s[66:67] nt
	v_add_u32_e32 v112, v164, v144
	global_load_dwordx4 v[112:115], v112, s[66:67] nt
	v_add_u32_e32 v108, v168, v144
	global_load_dwordx4 v[108:111], v108, s[66:67] nt
	v_add_u32_e32 v120, v172, v144
	global_load_dwordx4 v[120:123], v120, s[66:67] nt
	v_add_u32_e32 v116, v176, v144
	global_load_dwordx4 v[116:119], v116, s[66:67] nt
	v_add_u32_e32 v124, v180, v144
	global_load_dwordx4 v[124:127], v124, s[66:67] nt
	v_add_u32_e32 v104, v184, v144
	global_load_dwordx4 v[104:107], v104, s[66:67] nt
	v_add_u32_e32 v68, v188, v144
	global_load_dwordx4 v[68:71], v68, s[66:67] nt
	v_add_u32_e32 v64, v192, v144
	global_load_dwordx4 v[64:67], v64, s[66:67] nt
	v_add_u32_e32 v80, v196, v144
	global_load_dwordx4 v[80:83], v80, s[66:67] nt
	v_add_u32_e32 v76, v200, v144
	global_load_dwordx4 v[76:79], v76, s[66:67] nt
	v_add_u32_e32 v88, v202, v144
	global_load_dwordx4 v[88:91], v88, s[66:67] nt
	v_add_u32_e32 v84, v204, v144
	global_load_dwordx4 v[84:87], v84, s[66:67] nt
	v_add_u32_e32 v96, v206, v144
	global_load_dwordx4 v[96:99], v96, s[66:67] nt
	v_add_u32_e32 v72, v208, v144
	global_load_dwordx4 v[72:75], v72, s[66:67] nt
	v_add_f32_dpp v44, v252, v252 quad_perm:[1,0,3,2] row_mask:0xf bank_mask:0xf
	v_add_f32_dpp v45, v253, v253 quad_perm:[1,0,3,2] row_mask:0xf bank_mask:0xf
	v_add_f32_dpp v46, v254, v254 quad_perm:[1,0,3,2] row_mask:0xf bank_mask:0xf
	v_add_f32_dpp v47, v255, v255 quad_perm:[1,0,3,2] row_mask:0xf bank_mask:0xf
	v_cndmask_b32_e32 v44, v46, v44, vcc
	v_cndmask_b32_e32 v45, v47, v45, vcc
	v_add_f32_dpp v50, v48, v48 quad_perm:[2,3,0,1] row_mask:0xf bank_mask:0xf
	v_add_f32_dpp v51, v49, v49 quad_perm:[2,3,0,1] row_mask:0xf bank_mask:0xf
	v_cndmask_b32_e64 v48, v51, v50, s[4:5]
	v_cndmask_b32_e64 v53, v48, v52, s[6:7]
	v_cndmask_b32_e64 v54, v52, v48, s[6:7]
	s_waitcnt vmcnt(25)
	v_pk_mul_f32 v[252:253], v[236:237], v[36:37] op_sel_hi:[1,0]
	v_pk_mul_f32 v[254:255], v[244:245], v[36:37] op_sel_hi:[1,0]
	v_pk_fma_f32 v[252:253], v[238:239], v[36:37], v[252:253] op_sel:[0,1,0]
	v_pk_fma_f32 v[254:255], v[246:247], v[36:37], v[254:255] op_sel:[0,1,0]
	v_pk_fma_f32 v[252:253], v[240:241], v[38:39], v[252:253] op_sel_hi:[1,0,1]
	v_pk_fma_f32 v[254:255], v[248:249], v[38:39], v[254:255] op_sel_hi:[1,0,1]
	v_pk_fma_f32 v[252:253], v[242:243], v[38:39], v[252:253] op_sel:[0,1,0]
	v_pk_fma_f32 v[254:255], v[250:251], v[38:39], v[254:255] op_sel:[0,1,0]
	v_add_f32_dpp v52, v54, v53 row_ror:4 row_mask:0xf bank_mask:0xf
	v_cndmask_b32_e64 v61, v52, v60, s[64:65]
	v_cndmask_b32_e64 v62, v60, v52, s[64:65]
	v_add_f32_dpp v40, v140, v140 quad_perm:[1,0,3,2] row_mask:0xf bank_mask:0xf
	v_add_f32_dpp v41, v141, v141 quad_perm:[1,0,3,2] row_mask:0xf bank_mask:0xf
	v_add_f32_dpp v42, v142, v142 quad_perm:[1,0,3,2] row_mask:0xf bank_mask:0xf
	v_add_f32_dpp v43, v143, v143 quad_perm:[1,0,3,2] row_mask:0xf bank_mask:0xf
	v_cndmask_b32_e32 v40, v42, v40, vcc
	v_cndmask_b32_e32 v41, v43, v41, vcc
	v_add_f32_dpp v46, v44, v44 quad_perm:[2,3,0,1] row_mask:0xf bank_mask:0xf
	v_add_f32_dpp v47, v45, v45 quad_perm:[2,3,0,1] row_mask:0xf bank_mask:0xf
	v_cndmask_b32_e64 v44, v47, v46, s[4:5]
	s_waitcnt vmcnt(24)
	v_pk_mul_f32 v[140:141], v[236:237], v[32:33] op_sel_hi:[1,0]
	v_pk_mul_f32 v[142:143], v[244:245], v[32:33] op_sel_hi:[1,0]
	v_pk_fma_f32 v[140:141], v[238:239], v[32:33], v[140:141] op_sel:[0,1,0]
	v_pk_fma_f32 v[142:143], v[246:247], v[32:33], v[142:143] op_sel:[0,1,0]
	v_pk_fma_f32 v[140:141], v[240:241], v[34:35], v[140:141] op_sel_hi:[1,0,1]
	v_pk_fma_f32 v[142:143], v[248:249], v[34:35], v[142:143] op_sel_hi:[1,0,1]
	v_pk_fma_f32 v[140:141], v[242:243], v[34:35], v[140:141] op_sel:[0,1,0]
	v_pk_fma_f32 v[142:143], v[250:251], v[34:35], v[142:143] op_sel:[0,1,0]
	v_add_f32_dpp v60, v62, v61 row_ror:8 row_mask:0xf bank_mask:0xf
	v_add_f32_dpp v36, v252, v252 quad_perm:[1,0,3,2] row_mask:0xf bank_mask:0xf
	v_add_f32_dpp v37, v253, v253 quad_perm:[1,0,3,2] row_mask:0xf bank_mask:0xf
	v_add_f32_dpp v38, v254, v254 quad_perm:[1,0,3,2] row_mask:0xf bank_mask:0xf
	v_add_f32_dpp v39, v255, v255 quad_perm:[1,0,3,2] row_mask:0xf bank_mask:0xf
	v_cndmask_b32_e32 v36, v38, v36, vcc
	v_cndmask_b32_e32 v37, v39, v37, vcc
	v_add_f32_dpp v42, v40, v40 quad_perm:[2,3,0,1] row_mask:0xf bank_mask:0xf
	v_add_f32_dpp v43, v41, v41 quad_perm:[2,3,0,1] row_mask:0xf bank_mask:0xf
	v_cndmask_b32_e64 v40, v43, v42, s[4:5]
	v_cndmask_b32_e64 v45, v40, v44, s[6:7]
	v_cndmask_b32_e64 v46, v44, v40, s[6:7]
	s_waitcnt vmcnt(23)
	v_pk_mul_f32 v[252:253], v[236:237], v[28:29] op_sel_hi:[1,0]
	v_pk_mul_f32 v[254:255], v[244:245], v[28:29] op_sel_hi:[1,0]
	v_pk_fma_f32 v[252:253], v[238:239], v[28:29], v[252:253] op_sel:[0,1,0]
	v_pk_fma_f32 v[254:255], v[246:247], v[28:29], v[254:255] op_sel:[0,1,0]
	v_pk_fma_f32 v[252:253], v[240:241], v[30:31], v[252:253] op_sel_hi:[1,0,1]
	v_pk_fma_f32 v[254:255], v[248:249], v[30:31], v[254:255] op_sel_hi:[1,0,1]
	v_pk_fma_f32 v[252:253], v[242:243], v[30:31], v[252:253] op_sel:[0,1,0]
	v_pk_fma_f32 v[254:255], v[250:251], v[30:31], v[254:255] op_sel:[0,1,0]
	v_add_f32_dpp v44, v46, v45 row_ror:4 row_mask:0xf bank_mask:0xf
	v_add_f32_dpp v32, v140, v140 quad_perm:[1,0,3,2] row_mask:0xf bank_mask:0xf
	v_add_f32_dpp v33, v141, v141 quad_perm:[1,0,3,2] row_mask:0xf bank_mask:0xf
	v_add_f32_dpp v34, v142, v142 quad_perm:[1,0,3,2] row_mask:0xf bank_mask:0xf
	v_add_f32_dpp v35, v143, v143 quad_perm:[1,0,3,2] row_mask:0xf bank_mask:0xf
	v_cndmask_b32_e32 v32, v34, v32, vcc
	v_cndmask_b32_e32 v33, v35, v33, vcc
	v_add_f32_dpp v38, v36, v36 quad_perm:[2,3,0,1] row_mask:0xf bank_mask:0xf
	v_add_f32_dpp v39, v37, v37 quad_perm:[2,3,0,1] row_mask:0xf bank_mask:0xf
	v_cndmask_b32_e64 v36, v39, v38, s[4:5]
	s_waitcnt vmcnt(22)
	v_pk_mul_f32 v[140:141], v[236:237], v[24:25] op_sel_hi:[1,0]
	v_pk_mul_f32 v[142:143], v[244:245], v[24:25] op_sel_hi:[1,0]
	v_pk_fma_f32 v[140:141], v[238:239], v[24:25], v[140:141] op_sel:[0,1,0]
	v_pk_fma_f32 v[142:143], v[246:247], v[24:25], v[142:143] op_sel:[0,1,0]
	v_pk_fma_f32 v[140:141], v[240:241], v[26:27], v[140:141] op_sel_hi:[1,0,1]
	v_pk_fma_f32 v[142:143], v[248:249], v[26:27], v[142:143] op_sel_hi:[1,0,1]
	v_pk_fma_f32 v[140:141], v[242:243], v[26:27], v[140:141] op_sel:[0,1,0]
	v_pk_fma_f32 v[142:143], v[250:251], v[26:27], v[142:143] op_sel:[0,1,0]
	v_add_f32_dpp v28, v252, v252 quad_perm:[1,0,3,2] row_mask:0xf bank_mask:0xf
	v_add_f32_dpp v29, v253, v253 quad_perm:[1,0,3,2] row_mask:0xf bank_mask:0xf
	v_add_f32_dpp v30, v254, v254 quad_perm:[1,0,3,2] row_mask:0xf bank_mask:0xf
	v_add_f32_dpp v31, v255, v255 quad_perm:[1,0,3,2] row_mask:0xf bank_mask:0xf
	v_cndmask_b32_e32 v28, v30, v28, vcc
	v_cndmask_b32_e32 v29, v31, v29, vcc
	v_add_f32_dpp v34, v32, v32 quad_perm:[2,3,0,1] row_mask:0xf bank_mask:0xf
	v_add_f32_dpp v35, v33, v33 quad_perm:[2,3,0,1] row_mask:0xf bank_mask:0xf
	v_cndmask_b32_e64 v32, v35, v34, s[4:5]
	v_cndmask_b32_e64 v37, v32, v36, s[6:7]
	v_cndmask_b32_e64 v38, v36, v32, s[6:7]
	s_waitcnt vmcnt(21)
	v_pk_mul_f32 v[252:253], v[236:237], v[20:21] op_sel_hi:[1,0]
	v_pk_mul_f32 v[254:255], v[244:245], v[20:21] op_sel_hi:[1,0]
	v_pk_fma_f32 v[252:253], v[238:239], v[20:21], v[252:253] op_sel:[0,1,0]
	v_pk_fma_f32 v[254:255], v[246:247], v[20:21], v[254:255] op_sel:[0,1,0]
	v_pk_fma_f32 v[252:253], v[240:241], v[22:23], v[252:253] op_sel_hi:[1,0,1]
	v_pk_fma_f32 v[254:255], v[248:249], v[22:23], v[254:255] op_sel_hi:[1,0,1]
	v_pk_fma_f32 v[252:253], v[242:243], v[22:23], v[252:253] op_sel:[0,1,0]
	v_pk_fma_f32 v[254:255], v[250:251], v[22:23], v[254:255] op_sel:[0,1,0]
	v_add_f32_dpp v36, v38, v37 row_ror:4 row_mask:0xf bank_mask:0xf
	v_cndmask_b32_e64 v45, v36, v44, s[64:65]
	v_cndmask_b32_e64 v46, v44, v36, s[64:65]
	v_add_f32_dpp v24, v140, v140 quad_perm:[1,0,3,2] row_mask:0xf bank_mask:0xf
	v_add_f32_dpp v25, v141, v141 quad_perm:[1,0,3,2] row_mask:0xf bank_mask:0xf
	v_add_f32_dpp v26, v142, v142 quad_perm:[1,0,3,2] row_mask:0xf bank_mask:0xf
	v_add_f32_dpp v27, v143, v143 quad_perm:[1,0,3,2] row_mask:0xf bank_mask:0xf
	v_cndmask_b32_e32 v24, v26, v24, vcc
	v_cndmask_b32_e32 v25, v27, v25, vcc
	v_add_f32_dpp v30, v28, v28 quad_perm:[2,3,0,1] row_mask:0xf bank_mask:0xf
	v_add_f32_dpp v31, v29, v29 quad_perm:[2,3,0,1] row_mask:0xf bank_mask:0xf
	v_cndmask_b32_e64 v28, v31, v30, s[4:5]
	s_waitcnt vmcnt(20)
	v_pk_mul_f32 v[140:141], v[236:237], v[16:17] op_sel_hi:[1,0]
	v_pk_mul_f32 v[142:143], v[244:245], v[16:17] op_sel_hi:[1,0]
	v_pk_fma_f32 v[140:141], v[238:239], v[16:17], v[140:141] op_sel:[0,1,0]
	v_pk_fma_f32 v[142:143], v[246:247], v[16:17], v[142:143] op_sel:[0,1,0]
	v_pk_fma_f32 v[140:141], v[240:241], v[18:19], v[140:141] op_sel_hi:[1,0,1]
	v_pk_fma_f32 v[142:143], v[248:249], v[18:19], v[142:143] op_sel_hi:[1,0,1]
	v_pk_fma_f32 v[140:141], v[242:243], v[18:19], v[140:141] op_sel:[0,1,0]
	v_pk_fma_f32 v[142:143], v[250:251], v[18:19], v[142:143] op_sel:[0,1,0]
	v_add_f32_dpp v44, v46, v45 row_ror:8 row_mask:0xf bank_mask:0xf
	v_add_f32_dpp v20, v252, v252 quad_perm:[1,0,3,2] row_mask:0xf bank_mask:0xf
	v_add_f32_dpp v21, v253, v253 quad_perm:[1,0,3,2] row_mask:0xf bank_mask:0xf
	v_add_f32_dpp v22, v254, v254 quad_perm:[1,0,3,2] row_mask:0xf bank_mask:0xf
	v_add_f32_dpp v23, v255, v255 quad_perm:[1,0,3,2] row_mask:0xf bank_mask:0xf
	v_cndmask_b32_e32 v20, v22, v20, vcc
	v_cndmask_b32_e32 v21, v23, v21, vcc
	v_add_f32_dpp v26, v24, v24 quad_perm:[2,3,0,1] row_mask:0xf bank_mask:0xf
	v_add_f32_dpp v27, v25, v25 quad_perm:[2,3,0,1] row_mask:0xf bank_mask:0xf
	v_cndmask_b32_e64 v24, v27, v26, s[4:5]
	v_cndmask_b32_e64 v29, v24, v28, s[6:7]
	v_cndmask_b32_e64 v30, v28, v24, s[6:7]
	s_waitcnt vmcnt(19)
	v_pk_mul_f32 v[252:253], v[236:237], v[12:13] op_sel_hi:[1,0]
	v_pk_mul_f32 v[254:255], v[244:245], v[12:13] op_sel_hi:[1,0]
	v_pk_fma_f32 v[252:253], v[238:239], v[12:13], v[252:253] op_sel:[0,1,0]
	v_pk_fma_f32 v[254:255], v[246:247], v[12:13], v[254:255] op_sel:[0,1,0]
	v_pk_fma_f32 v[252:253], v[240:241], v[14:15], v[252:253] op_sel_hi:[1,0,1]
	v_pk_fma_f32 v[254:255], v[248:249], v[14:15], v[254:255] op_sel_hi:[1,0,1]
	v_pk_fma_f32 v[252:253], v[242:243], v[14:15], v[252:253] op_sel:[0,1,0]
	v_pk_fma_f32 v[254:255], v[250:251], v[14:15], v[254:255] op_sel:[0,1,0]
	v_permlane16_swap_b32_e32 v60, v44
	v_add_f32_e32 v60, v60, v44
	v_add_f32_dpp v28, v30, v29 row_ror:4 row_mask:0xf bank_mask:0xf
	v_add_f32_dpp v16, v140, v140 quad_perm:[1,0,3,2] row_mask:0xf bank_mask:0xf
	v_add_f32_dpp v17, v141, v141 quad_perm:[1,0,3,2] row_mask:0xf bank_mask:0xf
	v_add_f32_dpp v18, v142, v142 quad_perm:[1,0,3,2] row_mask:0xf bank_mask:0xf
	v_add_f32_dpp v19, v143, v143 quad_perm:[1,0,3,2] row_mask:0xf bank_mask:0xf
	v_cndmask_b32_e32 v16, v18, v16, vcc
	v_cndmask_b32_e32 v17, v19, v17, vcc
	v_add_f32_dpp v22, v20, v20 quad_perm:[2,3,0,1] row_mask:0xf bank_mask:0xf
	v_add_f32_dpp v23, v21, v21 quad_perm:[2,3,0,1] row_mask:0xf bank_mask:0xf
	v_cndmask_b32_e64 v20, v23, v22, s[4:5]
	s_waitcnt vmcnt(18)
	v_pk_mul_f32 v[140:141], v[236:237], v[8:9] op_sel_hi:[1,0]
	v_pk_mul_f32 v[142:143], v[244:245], v[8:9] op_sel_hi:[1,0]
	v_pk_fma_f32 v[140:141], v[238:239], v[8:9], v[140:141] op_sel:[0,1,0]
	v_pk_fma_f32 v[142:143], v[246:247], v[8:9], v[142:143] op_sel:[0,1,0]
	v_pk_fma_f32 v[140:141], v[240:241], v[10:11], v[140:141] op_sel_hi:[1,0,1]
	v_pk_fma_f32 v[142:143], v[248:249], v[10:11], v[142:143] op_sel_hi:[1,0,1]
	v_pk_fma_f32 v[140:141], v[242:243], v[10:11], v[140:141] op_sel:[0,1,0]
	v_pk_fma_f32 v[142:143], v[250:251], v[10:11], v[142:143] op_sel:[0,1,0]
	v_add_f32_dpp v12, v252, v252 quad_perm:[1,0,3,2] row_mask:0xf bank_mask:0xf
	v_add_f32_dpp v13, v253, v253 quad_perm:[1,0,3,2] row_mask:0xf bank_mask:0xf
	v_add_f32_dpp v14, v254, v254 quad_perm:[1,0,3,2] row_mask:0xf bank_mask:0xf
	v_add_f32_dpp v15, v255, v255 quad_perm:[1,0,3,2] row_mask:0xf bank_mask:0xf
	v_cndmask_b32_e32 v12, v14, v12, vcc
	v_cndmask_b32_e32 v13, v15, v13, vcc
	v_add_f32_dpp v18, v16, v16 quad_perm:[2,3,0,1] row_mask:0xf bank_mask:0xf
	v_add_f32_dpp v19, v17, v17 quad_perm:[2,3,0,1] row_mask:0xf bank_mask:0xf
	v_cndmask_b32_e64 v16, v19, v18, s[4:5]
	v_cndmask_b32_e64 v21, v16, v20, s[6:7]
	v_cndmask_b32_e64 v22, v20, v16, s[6:7]
	s_waitcnt vmcnt(17)
	v_pk_mul_f32 v[252:253], v[236:237], v[4:5] op_sel_hi:[1,0]
	v_pk_mul_f32 v[254:255], v[244:245], v[4:5] op_sel_hi:[1,0]
	v_pk_fma_f32 v[252:253], v[238:239], v[4:5], v[252:253] op_sel:[0,1,0]
	v_pk_fma_f32 v[254:255], v[246:247], v[4:5], v[254:255] op_sel:[0,1,0]
	v_pk_fma_f32 v[252:253], v[240:241], v[6:7], v[252:253] op_sel_hi:[1,0,1]
	v_pk_fma_f32 v[254:255], v[248:249], v[6:7], v[254:255] op_sel_hi:[1,0,1]
	v_pk_fma_f32 v[252:253], v[242:243], v[6:7], v[252:253] op_sel:[0,1,0]
	v_pk_fma_f32 v[254:255], v[250:251], v[6:7], v[254:255] op_sel:[0,1,0]
	v_add_f32_dpp v20, v22, v21 row_ror:4 row_mask:0xf bank_mask:0xf
	v_cndmask_b32_e64 v29, v20, v28, s[64:65]
	v_cndmask_b32_e64 v30, v28, v20, s[64:65]
	v_add_f32_dpp v8, v140, v140 quad_perm:[1,0,3,2] row_mask:0xf bank_mask:0xf
	v_add_f32_dpp v9, v141, v141 quad_perm:[1,0,3,2] row_mask:0xf bank_mask:0xf
	v_add_f32_dpp v10, v142, v142 quad_perm:[1,0,3,2] row_mask:0xf bank_mask:0xf
	v_add_f32_dpp v11, v143, v143 quad_perm:[1,0,3,2] row_mask:0xf bank_mask:0xf
	v_cndmask_b32_e32 v8, v10, v8, vcc
	v_cndmask_b32_e32 v9, v11, v9, vcc
	v_add_f32_dpp v14, v12, v12 quad_perm:[2,3,0,1] row_mask:0xf bank_mask:0xf
	v_add_f32_dpp v15, v13, v13 quad_perm:[2,3,0,1] row_mask:0xf bank_mask:0xf
	v_cndmask_b32_e64 v12, v15, v14, s[4:5]
	s_waitcnt vmcnt(16)
; DI void attn_sample_item(const Params& p, int item, ldsp lds, int tid_) {
;     ...
;   SC_SCORE(kvA, 0)
;   SC_SCORE(kvB, 1)
;     ...
;   f32x4 vvA[16], vvB[16];
; #pragma unroll
;   for (int j = 0; j < 16; ++j) vvA[j] = __builtin_nontemporal_load((const f32x4*)(cv + (size_t)(wid * 32 + j) * 1024 + lane * 4));
;     ...
;   for (int j = 0; j < 16; ++j) vvB[j] = __builtin_nontemporal_load((const f32x4*)(cv + (size_t)(wid * 32 + 16 + j) * 1024 + lane * 4));
	v_pk_mul_f32 v[140:141], v[236:237], v[0:1] op_sel_hi:[1,0]
	v_pk_mul_f32 v[142:143], v[244:245], v[0:1] op_sel_hi:[1,0]
	v_pk_fma_f32 v[140:141], v[238:239], v[0:1], v[140:141] op_sel:[0,1,0]
	v_pk_fma_f32 v[142:143], v[246:247], v[0:1], v[142:143] op_sel:[0,1,0]
	v_pk_fma_f32 v[140:141], v[240:241], v[2:3], v[140:141] op_sel_hi:[1,0,1]
	v_pk_fma_f32 v[142:143], v[248:249], v[2:3], v[142:143] op_sel_hi:[1,0,1]
	v_pk_fma_f32 v[140:141], v[242:243], v[2:3], v[140:141] op_sel:[0,1,0]
	v_pk_fma_f32 v[142:143], v[250:251], v[2:3], v[142:143] op_sel:[0,1,0]
	v_add_f32_dpp v28, v30, v29 row_ror:8 row_mask:0xf bank_mask:0xf
	v_add_f32_dpp v4, v252, v252 quad_perm:[1,0,3,2] row_mask:0xf bank_mask:0xf
	v_add_f32_dpp v5, v253, v253 quad_perm:[1,0,3,2] row_mask:0xf bank_mask:0xf
	v_add_f32_dpp v6, v254, v254 quad_perm:[1,0,3,2] row_mask:0xf bank_mask:0xf
	v_add_f32_dpp v7, v255, v255 quad_perm:[1,0,3,2] row_mask:0xf bank_mask:0xf
	v_cndmask_b32_e32 v4, v6, v4, vcc
	v_cndmask_b32_e32 v5, v7, v5, vcc
	v_add_f32_dpp v10, v8, v8 quad_perm:[2,3,0,1] row_mask:0xf bank_mask:0xf
	v_add_f32_dpp v11, v9, v9 quad_perm:[2,3,0,1] row_mask:0xf bank_mask:0xf
	v_cndmask_b32_e64 v8, v11, v10, s[4:5]
	v_cndmask_b32_e64 v13, v8, v12, s[6:7]
	v_cndmask_b32_e64 v14, v12, v8, s[6:7]
	s_nop 1
	v_add_f32_dpp v12, v14, v13 row_ror:4 row_mask:0xf bank_mask:0xf
	v_add_f32_dpp v0, v140, v140 quad_perm:[1,0,3,2] row_mask:0xf bank_mask:0xf
	v_add_f32_dpp v1, v141, v141 quad_perm:[1,0,3,2] row_mask:0xf bank_mask:0xf
	v_add_f32_dpp v2, v142, v142 quad_perm:[1,0,3,2] row_mask:0xf bank_mask:0xf
	v_add_f32_dpp v3, v143, v143 quad_perm:[1,0,3,2] row_mask:0xf bank_mask:0xf
	v_cndmask_b32_e32 v0, v2, v0, vcc
	v_cndmask_b32_e32 v1, v3, v1, vcc
	v_add_f32_dpp v6, v4, v4 quad_perm:[2,3,0,1] row_mask:0xf bank_mask:0xf
	v_add_f32_dpp v7, v5, v5 quad_perm:[2,3,0,1] row_mask:0xf bank_mask:0xf
	v_cndmask_b32_e64 v4, v7, v6, s[4:5]
	v_add_f32_dpp v2, v0, v0 quad_perm:[2,3,0,1] row_mask:0xf bank_mask:0xf
	v_add_f32_dpp v3, v1, v1 quad_perm:[2,3,0,1] row_mask:0xf bank_mask:0xf
	v_cndmask_b32_e64 v0, v3, v2, s[4:5]
	v_cndmask_b32_e64 v5, v0, v4, s[6:7]
	v_cndmask_b32_e64 v6, v4, v0, s[6:7]
	s_nop 1
	v_add_f32_dpp v4, v6, v5 row_ror:4 row_mask:0xf bank_mask:0xf
	v_cndmask_b32_e64 v13, v4, v12, s[64:65]
	v_cndmask_b32_e64 v14, v12, v4, s[64:65]
	s_nop 1
	v_add_f32_dpp v12, v14, v13 row_ror:8 row_mask:0xf bank_mask:0xf
	s_nop 1
	v_permlane16_swap_b32_e32 v28, v12
	v_add_f32_e32 v28, v28, v12
	s_nop 1
	v_permlane32_swap_b32_e32 v60, v28
	v_add_f32_e32 v60, v60, v28
	ds_write_b32 v235, v60 offset:64
	v_add_u32_e32 v40, v146, v144
	global_load_dwordx4 v[40:43], v40, s[66:67] nt
	v_add_u32_e32 v36, v148, v144
	global_load_dwordx4 v[36:39], v36, s[66:67] nt
	v_add_u32_e32 v48, v150, v144
	global_load_dwordx4 v[48:51], v48, s[66:67] nt
	v_add_u32_e32 v44, v152, v144
	global_load_dwordx4 v[44:47], v44, s[66:67] nt
	v_add_u32_e32 v56, v154, v144
	global_load_dwordx4 v[56:59], v56, s[66:67] nt
	v_add_u32_e32 v52, v156, v144
	global_load_dwordx4 v[52:55], v52, s[66:67] nt
	v_add_u32_e32 v60, v160, v144
	global_load_dwordx4 v[60:63], v60, s[66:67] nt
	v_add_u32_e32 v32, v166, v144
	global_load_dwordx4 v[32:35], v32, s[66:67] nt
	v_add_u32_e32 v12, v170, v144
	global_load_dwordx4 v[12:15], v12, s[66:67] nt
	v_add_u32_e32 v4, v174, v144
	global_load_dwordx4 v[4:7], v4, s[66:67] nt
	v_add_u32_e32 v20, v178, v144
	global_load_dwordx4 v[20:23], v20, s[66:67] nt
	v_add_u32_e32 v8, v182, v144
	global_load_dwordx4 v[8:11], v8, s[66:67] nt
	v_add_u32_e32 v24, v186, v144
	global_load_dwordx4 v[24:27], v24, s[66:67] nt
	v_add_u32_e32 v16, v190, v144
	global_load_dwordx4 v[16:19], v16, s[66:67] nt
	v_add_u32_e32 v28, v194, v144
	global_load_dwordx4 v[28:31], v28, s[66:67] nt
	v_add_u32_e32 v0, v198, v144
	global_load_dwordx4 v[0:3], v0, s[66:67] nt
	v_lshlrev_b32_e32 v240, 2, v223
	s_waitcnt lgkmcnt(0)
	s_barrier
	v_cmp_gt_i32_e32 vcc, 4, v210
	s_and_saveexec_b64 s[4:5], vcc
	s_cbranch_execz .LBB0_1675

; DI float wave_sum(float v) { for (int o = 32; o >= 1; o >>= 1) v += __shfl_xor(v, o); return v; }
; DI void attn_sample_item(const Params& p, int item, ldsp lds, int tid_) {
;     ...
;   if (wid < 4) {
;     float v[4]; float mx = -1e30f;
; #pragma unroll
;     for (int j = 0; j < 4; ++j) { v[j] = SC[wid * 256 + j * 64 + lane]; mx = fmaxf(mx, v[j]); }
;     for (int o = 32; o >= 1; o >>= 1) mx = fmaxf(mx, __shfl_xor(mx, o));
;     float s = 0.f;
; #pragma unroll
;     for (int j = 0; j < 4; ++j) { v[j] = __expf(v[j] - mx); s += v[j]; }
;     s = wave_sum(s); const float inv = 1.f / s;
; #pragma unroll
;     for (int j = 0; j < 4; ++j) SC[wid * 256 + j * 64 + lane] = v[j] * inv;
;   }
	v_lshlrev_b32_e32 v241, 10, v210
	v_add3_u32 v244, 16, v241, v240
	ds_read2st64_b32 v[240:241], v244 offset1:1
	ds_read2st64_b32 v[242:243], v244 offset0:2 offset1:3
	s_waitcnt lgkmcnt(1)
	v_max3_f32 v245, v240, s35, v241
	s_waitcnt lgkmcnt(0)
	v_max3_f32 v245, v245, v242, v243
	ds_bpermute_b32 v246, v133, v245
	s_waitcnt lgkmcnt(0)
	v_max_f32_e32 v246, v246, v246
	v_max_f32_e32 v245, v245, v246
	ds_bpermute_b32 v246, v132, v245
	s_waitcnt lgkmcnt(0)
	v_max_f32_e32 v246, v246, v246
	v_max_f32_e32 v245, v245, v246
	ds_bpermute_b32 v246, v131, v245
	s_waitcnt lgkmcnt(0)
	v_max_f32_e32 v246, v246, v246
	v_max_f32_e32 v245, v245, v246
	ds_bpermute_b32 v246, v130, v245
	s_waitcnt lgkmcnt(0)
	v_max_f32_e32 v246, v246, v246
	v_max_f32_e32 v245, v245, v246
	ds_bpermute_b32 v246, v129, v245
	s_waitcnt lgkmcnt(0)
	v_max_f32_e32 v246, v246, v246
	v_max_f32_e32 v245, v245, v246
	ds_bpermute_b32 v246, v128, v245
	s_waitcnt lgkmcnt(0)
	v_max_f32_e32 v246, v246, v246
	v_max_f32_e32 v245, v245, v246
	v_sub_f32_e32 v240, v240, v245
	v_sub_f32_e32 v241, v241, v245
	v_mul_f32_e32 v240, 0x3fb8aa3b, v240
	v_sub_f32_e32 v242, v242, v245
	v_mul_f32_e32 v241, 0x3fb8aa3b, v241
	v_exp_f32_e32 v240, v240
	v_sub_f32_e32 v243, v243, v245
	v_mul_f32_e32 v242, 0x3fb8aa3b, v242
	v_exp_f32_e32 v241, v241
	v_mul_f32_e32 v243, 0x3fb8aa3b, v243
	v_exp_f32_e32 v242, v242
	v_exp_f32_e32 v243, v243
	v_add_f32_e32 v245, 0, v240
	v_add_f32_e32 v245, v241, v245
	v_add_f32_e32 v245, v242, v245
	v_add_f32_e32 v245, v243, v245
	ds_bpermute_b32 v246, v133, v245
	s_waitcnt lgkmcnt(0)
	v_add_f32_e32 v245, v245, v246
	ds_bpermute_b32 v246, v132, v245
	s_waitcnt lgkmcnt(0)
	v_add_f32_e32 v245, v245, v246
	ds_bpermute_b32 v246, v131, v245
	s_waitcnt lgkmcnt(0)
	v_add_f32_e32 v245, v245, v246
	ds_bpermute_b32 v246, v130, v245
	s_waitcnt lgkmcnt(0)
	v_add_f32_e32 v245, v245, v246
	ds_bpermute_b32 v246, v129, v245
	s_waitcnt lgkmcnt(0)
	v_add_f32_e32 v245, v245, v246
	ds_bpermute_b32 v246, v128, v245
	s_waitcnt lgkmcnt(0)
	v_add_f32_e32 v245, v245, v246
	v_div_scale_f32 v246, s[6:7], v245, v245, 1.0
	v_rcp_f32_e32 v247, v246
	v_div_scale_f32 v248, vcc, 1.0, v245, 1.0
	v_fma_f32 v249, -v246, v247, 1.0
	v_fmac_f32_e32 v247, v249, v247
	v_mul_f32_e32 v249, v248, v247
	v_fma_f32 v250, -v246, v249, v248
	v_fmac_f32_e32 v249, v250, v247
	v_fma_f32 v246, -v246, v249, v248
	v_div_fmas_f32 v246, v246, v247, v249
	v_div_fixup_f32 v245, v246, v245, 1.0
	v_mul_f32_e32 v240, v240, v245
	v_mul_f32_e32 v241, v241, v245
	v_mul_f32_e32 v242, v242, v245
	v_mul_f32_e32 v243, v243, v245
	ds_write2st64_b32 v244, v240, v241 offset1:1
	ds_write2st64_b32 v244, v242, v243 offset0:2 offset1:3
	s_branch .LBB0_1675
